# MLA attention loop: softmax VALU interleaved under QK/PV MFMAs, no s_nop row-sum chain; GEMM LDS-DMA loads use saddr form (no per-load 64-bit VALU add)
# speedup vs baseline: 1.0088x; 1.0088x over previous
; #define PG8_STAGE(bufoff, gbase, voff) do { _Pragma("unroll") for (int _i = 0; _i < 2; ++_i) \
;     __builtin_amdgcn_global_load_lds((const unsigned*)((const char*)(gbase) + (voff)[_i]), (LAS unsigned*)(lds + (bufoff) + ldsw + _i * 8192), 16, 0, 0); } while (0)
; #define PG8_LDA(dst, b, h) do { _Pragma("unroll") for (int m = 0; m < 4; ++m) _Pragma("unroll") for (int k = 0; k < 2; ++k) dst[m][k] = *(const LAS bf16x8*)(lds + PG8_SA(b, h) + aoff + m * 2048 + k * 1024); } while (0)
; #define PG8_LDB(dst, b, h) do { _Pragma("unroll") for (int n = 0; n < 2; ++n) _Pragma("unroll") for (int k = 0; k < 2; ++k) dst[n][k] = *(const LAS bf16x8*)(lds + PG8_SB(b, h) + boff + n * 2048 + k * 1024); } while (0)
; #define PG8_MMA(ai, bj, At, Bt) do { __builtin_amdgcn_s_setprio(1); _Pragma("unroll") for (int m = 0; m < 4; ++m) _Pragma("unroll") for (int n = 0; n < 2; ++n) _Pragma("unroll") for (int k = 0; k < 2; ++k) \
;     acc[ai][bj][m][n] = __builtin_amdgcn_mfma_f32_16x16x32_bf16(Bt[n][k], At[m][k], acc[ai][bj][m][n], 0, 0, 0); __builtin_amdgcn_s_setprio(0); } while (0)
; #define PG8_WAIT_V(n) asm volatile("s_waitcnt vmcnt(" #n ")" ::: "memory")
; #define PG8_WAIT_L(n) asm volatile("s_waitcnt lgkmcnt(" #n ")" ::: "memory")
; #define PG8_BAR __builtin_amdgcn_s_barrier()
; #define PG8_SCHED __builtin_amdgcn_sched_barrier(0)
; template <class Epi, class Sched>
; DI void gemm_phase(LAS unsigned char* lds, const int tid, const Gemm g, const Sched& S, const Epi& E) {
;     ...
;       const bool last = (t == nt - 2);
;       const char* a1 = cA + (size_t)(t + 1) * kstep;
;       const char* a2 = last ? nA : cA + (size_t)(t + 2) * kstep; const char* b2 = last ? nB : cB + (size_t)(t + 2) * kstep;
;       const char* a3 = a2 + kstep; const char* b3 = b2 + kstep;
;       PG8_LDB(B0, 0, 0); PG8_SCHED; PG8_LDA(At, 0, 0); PG8_STAGE(PG8_SA(1, 1), a1 + hstepA, voffA);
;       PG8_WAIT_L(8); PG8_BAR; PG8_WAIT_L(0); PG8_MMA(0, 0, At, B0); PG8_BAR; PG8_SCHED;
;       PG8_LDB(B1, 0, 1); PG8_STAGE(PG8_SB(0, 0), b2, voffB);
;       PG8_BAR; PG8_WAIT_L(0); PG8_MMA(0, 1, At, B1); PG8_BAR;
;       PG8_LDA(At, 0, 1); PG8_STAGE(PG8_SA(0, 0), a2, voffA);
;       PG8_BAR; PG8_WAIT_L(0); PG8_MMA(1, 0, At, B0); PG8_BAR; PG8_SCHED;
;       PG8_STAGE(PG8_SB(0, 1), b2 + hstepB, voffB);
;       PG8_WAIT_V(6); PG8_BAR; PG8_MMA(1, 1, At, B1); PG8_BAR;
.LBB0_387:
	s_add_u32 s14, s16, 0xfffc0080
	s_addc_u32 s15, s17, -1
	s_add_i32 s46, 0, 0x10000
	v_add_u32_e32 v0, s46, v140
	ds_read_b128 v[142:145], v0
	ds_read_b128 v[146:149], v0 offset:1024
	ds_read_b128 v[150:153], v0 offset:2048
	ds_read_b128 v[154:157], v0 offset:3072
	s_cmp_eq_u32 s44, 12
	s_cselect_b32 s19, s7, s15
	s_cselect_b32 s18, s40, s14
	s_cselect_b32 s15, s1, s43
	s_cselect_b32 s14, s41, s42
	s_add_i32 m0, s27, 0xc000
	ds_read_b128 v[158:161], v141
	ds_read_b128 v[162:165], v141 offset:1024
	ds_read_b128 v[166:169], v141 offset:2048
	ds_read_b128 v[170:173], v141 offset:3072
	ds_read_b128 v[174:177], v141 offset:4096
	ds_read_b128 v[178:181], v141 offset:5120
	ds_read_b128 v[182:185], v141 offset:6144
	ds_read_b128 v[202:205], v141 offset:7168
	global_load_lds_dwordx4 v136, s[16:17]
	s_add_i32 m0, s27, 0xe000
	s_nop 0
	global_load_lds_dwordx4 v134, s[16:17]
	s_waitcnt lgkmcnt(8)
	s_barrier
	s_waitcnt lgkmcnt(0)
	s_setprio 1
	s_waitcnt lgkmcnt(0)
	v_mfma_f32_16x16x32_bf16 v[126:129], v[142:145], v[158:161], v[126:129]
	v_mfma_f32_16x16x32_bf16 v[122:125], v[150:153], v[158:161], v[122:125]
	v_mfma_f32_16x16x32_bf16 v[110:113], v[142:145], v[166:169], v[110:113]
	v_mfma_f32_16x16x32_bf16 v[106:109], v[150:153], v[166:169], v[106:109]
	v_mfma_f32_16x16x32_bf16 v[94:97], v[142:145], v[174:177], v[94:97]
	v_mfma_f32_16x16x32_bf16 v[90:93], v[150:153], v[174:177], v[90:93]
	v_mfma_f32_16x16x32_bf16 v[78:81], v[142:145], v[182:185], v[78:81]
	v_mfma_f32_16x16x32_bf16 v[74:77], v[150:153], v[182:185], v[74:77]
	v_mfma_f32_16x16x32_bf16 v[126:129], v[146:149], v[162:165], v[126:129]
	v_mfma_f32_16x16x32_bf16 v[122:125], v[154:157], v[162:165], v[122:125]
	v_mfma_f32_16x16x32_bf16 v[110:113], v[146:149], v[170:173], v[110:113]
	v_mfma_f32_16x16x32_bf16 v[106:109], v[154:157], v[170:173], v[106:109]
	v_mfma_f32_16x16x32_bf16 v[94:97], v[146:149], v[178:181], v[94:97]
	v_mfma_f32_16x16x32_bf16 v[90:93], v[154:157], v[178:181], v[90:93]
	v_mfma_f32_16x16x32_bf16 v[78:81], v[146:149], v[202:205], v[78:81]
	v_mfma_f32_16x16x32_bf16 v[74:77], v[154:157], v[202:205], v[74:77]
	s_setprio 0
	s_barrier
	s_add_i32 s48, 0, 0x14000
	s_add_i32 s46, s46, s24
	v_add_u32_e32 v0, s48, v140
	s_add_u32 s98, s14, s50
	s_addc_u32 s99, s15, s51
	s_mov_b32 m0, s46
	ds_read_b128 v[206:209], v0
	ds_read_b128 v[210:213], v0 offset:1024
	ds_read_b128 v[226:229], v0 offset:2048
	ds_read_b128 v[238:241], v0 offset:3072
	global_load_lds_dwordx4 v132, s[14:15]
	s_add_i32 m0, s46, 0x2000
	s_nop 0
	global_load_lds_dwordx4 v130, s[14:15]
	s_barrier
	s_waitcnt lgkmcnt(0)
	s_setprio 1
	s_waitcnt lgkmcnt(0)
	v_mfma_f32_16x16x32_bf16 v[118:121], v[206:209], v[158:161], v[118:121]
	v_mfma_f32_16x16x32_bf16 v[114:117], v[226:229], v[158:161], v[114:117]
	v_mfma_f32_16x16x32_bf16 v[102:105], v[206:209], v[166:169], v[102:105]
	v_mfma_f32_16x16x32_bf16 v[98:101], v[226:229], v[166:169], v[98:101]
	v_mfma_f32_16x16x32_bf16 v[86:89], v[206:209], v[174:177], v[86:89]
	v_mfma_f32_16x16x32_bf16 v[82:85], v[226:229], v[174:177], v[82:85]
	v_mfma_f32_16x16x32_bf16 v[70:73], v[206:209], v[182:185], v[70:73]
	v_mfma_f32_16x16x32_bf16 v[66:69], v[226:229], v[182:185], v[66:69]
	v_mfma_f32_16x16x32_bf16 v[118:121], v[210:213], v[162:165], v[118:121]
	v_mfma_f32_16x16x32_bf16 v[114:117], v[238:241], v[162:165], v[114:117]
	v_mfma_f32_16x16x32_bf16 v[102:105], v[210:213], v[170:173], v[102:105]
	v_mfma_f32_16x16x32_bf16 v[98:101], v[238:241], v[170:173], v[98:101]
	v_mfma_f32_16x16x32_bf16 v[86:89], v[210:213], v[178:181], v[86:89]
	v_mfma_f32_16x16x32_bf16 v[82:85], v[238:241], v[178:181], v[82:85]
	v_mfma_f32_16x16x32_bf16 v[70:73], v[210:213], v[202:205], v[70:73]
	v_mfma_f32_16x16x32_bf16 v[66:69], v[238:241], v[202:205], v[66:69]
	s_setprio 0
	s_mov_b32 m0, s27
	s_add_u32 s100, s18, s50
	s_addc_u32 s101, s19, s51
	s_barrier
	ds_read_b128 v[158:161], v141 offset:16384
	ds_read_b128 v[162:165], v141 offset:17408
	ds_read_b128 v[166:169], v141 offset:18432
	ds_read_b128 v[170:173], v141 offset:19456
	ds_read_b128 v[174:177], v141 offset:20480
	ds_read_b128 v[178:181], v141 offset:21504
	ds_read_b128 v[182:185], v141 offset:22528
	ds_read_b128 v[202:205], v141 offset:23552
	global_load_lds_dwordx4 v132, s[18:19]
	s_mov_b32 m0, s28
	s_nop 0
	global_load_lds_dwordx4 v130, s[18:19]
	s_barrier
	s_waitcnt lgkmcnt(0)
	s_setprio 1
	s_waitcnt lgkmcnt(0)
	v_mfma_f32_16x16x32_bf16 v[62:65], v[142:145], v[158:161], v[62:65]
	v_mfma_f32_16x16x32_bf16 v[58:61], v[150:153], v[158:161], v[58:61]
	v_mfma_f32_16x16x32_bf16 v[46:49], v[142:145], v[166:169], v[46:49]
	v_mfma_f32_16x16x32_bf16 v[42:45], v[150:153], v[166:169], v[42:45]
	v_mfma_f32_16x16x32_bf16 v[30:33], v[142:145], v[174:177], v[30:33]
	v_mfma_f32_16x16x32_bf16 v[26:29], v[150:153], v[174:177], v[26:29]
	v_mfma_f32_16x16x32_bf16 v[14:17], v[142:145], v[182:185], v[14:17]
	v_mfma_f32_16x16x32_bf16 v[10:13], v[150:153], v[182:185], v[10:13]
	v_mfma_f32_16x16x32_bf16 v[62:65], v[146:149], v[162:165], v[62:65]
	v_mfma_f32_16x16x32_bf16 v[58:61], v[154:157], v[162:165], v[58:61]
	v_mfma_f32_16x16x32_bf16 v[46:49], v[146:149], v[170:173], v[46:49]
	v_mfma_f32_16x16x32_bf16 v[42:45], v[154:157], v[170:173], v[42:45]
	v_mfma_f32_16x16x32_bf16 v[30:33], v[146:149], v[178:181], v[30:33]
	v_mfma_f32_16x16x32_bf16 v[26:29], v[154:157], v[178:181], v[26:29]
	v_mfma_f32_16x16x32_bf16 v[14:17], v[146:149], v[202:205], v[14:17]
	v_mfma_f32_16x16x32_bf16 v[10:13], v[154:157], v[202:205], v[10:13]
	s_setprio 0
	s_barrier
	s_add_u32 s46, s14, 0x40000
	s_addc_u32 s47, s15, 0
	s_add_i32 s48, s48, s24
	s_mov_b32 m0, s48
	s_nop 0
	global_load_lds_dwordx4 v132, s[46:47]
	s_add_i32 m0, s48, 0x2000
	s_nop 0
	global_load_lds_dwordx4 v130, s[46:47]
	s_waitcnt vmcnt(6)
	s_barrier
; #define PG8_STAGE(bufoff, gbase, voff) do { _Pragma("unroll") for (int _i = 0; _i < 2; ++_i) \
;     __builtin_amdgcn_global_load_lds((const unsigned*)((const char*)(gbase) + (voff)[_i]), (LAS unsigned*)(lds + (bufoff) + ldsw + _i * 8192), 16, 0, 0); } while (0)
; #define PG8_LDA(dst, b, h) do { _Pragma("unroll") for (int m = 0; m < 4; ++m) _Pragma("unroll") for (int k = 0; k < 2; ++k) dst[m][k] = *(const LAS bf16x8*)(lds + PG8_SA(b, h) + aoff + m * 2048 + k * 1024); } while (0)
; #define PG8_LDB(dst, b, h) do { _Pragma("unroll") for (int n = 0; n < 2; ++n) _Pragma("unroll") for (int k = 0; k < 2; ++k) dst[n][k] = *(const LAS bf16x8*)(lds + PG8_SB(b, h) + boff + n * 2048 + k * 1024); } while (0)
; #define PG8_MMA(ai, bj, At, Bt) do { __builtin_amdgcn_s_setprio(1); _Pragma("unroll") for (int m = 0; m < 4; ++m) _Pragma("unroll") for (int n = 0; n < 2; ++n) _Pragma("unroll") for (int k = 0; k < 2; ++k) \
;     acc[ai][bj][m][n] = __builtin_amdgcn_mfma_f32_16x16x32_bf16(Bt[n][k], At[m][k], acc[ai][bj][m][n], 0, 0, 0); __builtin_amdgcn_s_setprio(0); } while (0)
; #define PG8_WAIT_V(n) asm volatile("s_waitcnt vmcnt(" #n ")" ::: "memory")
; #define PG8_WAIT_L(n) asm volatile("s_waitcnt lgkmcnt(" #n ")" ::: "memory")
; #define PG8_BAR __builtin_amdgcn_s_barrier()
; #define PG8_SCHED __builtin_amdgcn_sched_barrier(0)
; template <class Epi, class Sched>
; DI void gemm_phase(LAS unsigned char* lds, const int tid, const Gemm g, const Sched& S, const Epi& E) {
;     ...
;       PG8_WAIT_V(6); PG8_BAR; PG8_MMA(1, 1, At, B1); PG8_BAR;
;       PG8_LDB(B0, 1, 0); PG8_SCHED; PG8_LDA(At, 1, 0); PG8_STAGE(PG8_SA(0, 1), a2 + hstepA, voffA);
;       PG8_WAIT_L(8); PG8_BAR; PG8_WAIT_L(0); PG8_MMA(0, 0, At, B0); PG8_BAR; PG8_SCHED;
;       PG8_LDB(B1, 1, 1); PG8_STAGE(PG8_SB(1, 0), b3, voffB);
;       PG8_BAR; PG8_WAIT_L(0); PG8_MMA(0, 1, At, B1); PG8_BAR;
;       PG8_LDA(At, 1, 1); PG8_STAGE(PG8_SA(1, 0), a3, voffA);
;       PG8_BAR; PG8_WAIT_L(0); PG8_MMA(1, 0, At, B0); PG8_BAR; PG8_SCHED;
	s_setprio 1
	v_mfma_f32_16x16x32_bf16 v[54:57], v[206:209], v[158:161], v[54:57]
	v_mfma_f32_16x16x32_bf16 v[50:53], v[226:229], v[158:161], v[50:53]
	v_mfma_f32_16x16x32_bf16 v[38:41], v[206:209], v[166:169], v[38:41]
	v_mfma_f32_16x16x32_bf16 v[34:37], v[226:229], v[166:169], v[34:37]
	v_mfma_f32_16x16x32_bf16 v[22:25], v[206:209], v[174:177], v[22:25]
	v_mfma_f32_16x16x32_bf16 v[18:21], v[226:229], v[174:177], v[18:21]
	v_mfma_f32_16x16x32_bf16 v[6:9], v[206:209], v[182:185], v[6:9]
	v_mfma_f32_16x16x32_bf16 v[2:5], v[226:229], v[182:185], v[2:5]
	v_mfma_f32_16x16x32_bf16 v[54:57], v[210:213], v[162:165], v[54:57]
	v_mfma_f32_16x16x32_bf16 v[50:53], v[238:241], v[162:165], v[50:53]
	v_mfma_f32_16x16x32_bf16 v[38:41], v[210:213], v[170:173], v[38:41]
	v_mfma_f32_16x16x32_bf16 v[34:37], v[238:241], v[170:173], v[34:37]
	v_mfma_f32_16x16x32_bf16 v[22:25], v[210:213], v[178:181], v[22:25]
	v_mfma_f32_16x16x32_bf16 v[18:21], v[238:241], v[178:181], v[18:21]
	v_mfma_f32_16x16x32_bf16 v[6:9], v[210:213], v[202:205], v[6:9]
	v_mfma_f32_16x16x32_bf16 v[2:5], v[238:241], v[202:205], v[2:5]
	s_setprio 0
	s_add_i32 s46, 0, 0x18000
	v_add_u32_e32 v0, s46, v140
	s_barrier
	ds_read_b128 v[142:145], v0
	ds_read_b128 v[146:149], v0 offset:1024
	ds_read_b128 v[150:153], v0 offset:2048
	ds_read_b128 v[154:157], v0 offset:3072
	s_add_u32 s18, s18, 0x40000
	s_addc_u32 s19, s19, 0
	s_mov_b32 m0, s29
	ds_read_b128 v[158:161], v141 offset:32768
	ds_read_b128 v[162:165], v141 offset:33792
	ds_read_b128 v[166:169], v141 offset:34816
	ds_read_b128 v[170:173], v141 offset:35840
	ds_read_b128 v[174:177], v141 offset:36864
	ds_read_b128 v[178:181], v141 offset:37888
	ds_read_b128 v[182:185], v141 offset:38912
	ds_read_b128 v[202:205], v141 offset:39936
	global_load_lds_dwordx4 v132, s[18:19]
	s_mov_b32 m0, s30
	s_nop 0
	global_load_lds_dwordx4 v130, s[18:19]
	s_waitcnt lgkmcnt(8)
	s_barrier
	s_waitcnt lgkmcnt(0)
	s_setprio 1
	s_waitcnt lgkmcnt(0)
	v_mfma_f32_16x16x32_bf16 v[126:129], v[142:145], v[158:161], v[126:129]
	v_mfma_f32_16x16x32_bf16 v[122:125], v[150:153], v[158:161], v[122:125]
	v_mfma_f32_16x16x32_bf16 v[110:113], v[142:145], v[166:169], v[110:113]
	v_mfma_f32_16x16x32_bf16 v[106:109], v[150:153], v[166:169], v[106:109]
	v_mfma_f32_16x16x32_bf16 v[94:97], v[142:145], v[174:177], v[94:97]
	v_mfma_f32_16x16x32_bf16 v[90:93], v[150:153], v[174:177], v[90:93]
	v_mfma_f32_16x16x32_bf16 v[78:81], v[142:145], v[182:185], v[78:81]
	v_mfma_f32_16x16x32_bf16 v[74:77], v[150:153], v[182:185], v[74:77]
	v_mfma_f32_16x16x32_bf16 v[126:129], v[146:149], v[162:165], v[126:129]
	v_mfma_f32_16x16x32_bf16 v[122:125], v[154:157], v[162:165], v[122:125]
	v_mfma_f32_16x16x32_bf16 v[110:113], v[146:149], v[170:173], v[110:113]
	v_mfma_f32_16x16x32_bf16 v[106:109], v[154:157], v[170:173], v[106:109]
	v_mfma_f32_16x16x32_bf16 v[94:97], v[146:149], v[178:181], v[94:97]
	v_mfma_f32_16x16x32_bf16 v[90:93], v[154:157], v[178:181], v[90:93]
	v_mfma_f32_16x16x32_bf16 v[78:81], v[146:149], v[202:205], v[78:81]
	v_mfma_f32_16x16x32_bf16 v[74:77], v[154:157], v[202:205], v[74:77]
	s_setprio 0
	s_barrier
	s_add_i32 s18, 0, 0x1c000
	s_add_i32 s19, s46, s24
	v_add_u32_e32 v0, s18, v140
	s_mov_b32 m0, s19
	ds_read_b128 v[206:209], v0
	ds_read_b128 v[210:213], v0 offset:1024
	ds_read_b128 v[226:229], v0 offset:2048
	ds_read_b128 v[238:241], v0 offset:3072
	global_load_lds_dwordx4 v132, s[98:99]
	s_add_i32 m0, s19, 0x2000
	s_nop 0
	global_load_lds_dwordx4 v130, s[98:99]
	s_barrier
	s_waitcnt lgkmcnt(0)
	s_setprio 1
	s_waitcnt lgkmcnt(0)
	v_mfma_f32_16x16x32_bf16 v[118:121], v[206:209], v[158:161], v[118:121]
	v_mfma_f32_16x16x32_bf16 v[114:117], v[226:229], v[158:161], v[114:117]
	v_mfma_f32_16x16x32_bf16 v[102:105], v[206:209], v[166:169], v[102:105]
	v_mfma_f32_16x16x32_bf16 v[98:101], v[226:229], v[166:169], v[98:101]
	v_mfma_f32_16x16x32_bf16 v[86:89], v[206:209], v[174:177], v[86:89]
	v_mfma_f32_16x16x32_bf16 v[82:85], v[226:229], v[174:177], v[82:85]
	v_mfma_f32_16x16x32_bf16 v[70:73], v[206:209], v[182:185], v[70:73]
	v_mfma_f32_16x16x32_bf16 v[66:69], v[226:229], v[182:185], v[66:69]
	v_mfma_f32_16x16x32_bf16 v[118:121], v[210:213], v[162:165], v[118:121]
	v_mfma_f32_16x16x32_bf16 v[114:117], v[238:241], v[162:165], v[114:117]
	v_mfma_f32_16x16x32_bf16 v[102:105], v[210:213], v[170:173], v[102:105]
	v_mfma_f32_16x16x32_bf16 v[98:101], v[238:241], v[170:173], v[98:101]
	v_mfma_f32_16x16x32_bf16 v[86:89], v[210:213], v[178:181], v[86:89]
	v_mfma_f32_16x16x32_bf16 v[82:85], v[238:241], v[178:181], v[82:85]
	v_mfma_f32_16x16x32_bf16 v[70:73], v[210:213], v[202:205], v[70:73]
	v_mfma_f32_16x16x32_bf16 v[66:69], v[238:241], v[202:205], v[66:69]
	s_setprio 0
	s_mov_b32 m0, s36
	s_barrier
	ds_read_b128 v[158:161], v141 offset:49152
	ds_read_b128 v[162:165], v141 offset:50176
	ds_read_b128 v[166:169], v141 offset:51200
	ds_read_b128 v[170:173], v141 offset:52224
	ds_read_b128 v[174:177], v141 offset:53248
	ds_read_b128 v[178:181], v141 offset:54272
	ds_read_b128 v[182:185], v141 offset:55296
	ds_read_b128 v[202:205], v141 offset:56320
	global_load_lds_dwordx4 v132, s[100:101]
	s_mov_b32 m0, s37
	s_nop 0
	global_load_lds_dwordx4 v130, s[100:101]
	s_barrier
; #define GAS __attribute__((address_space(1)))
; DI unsigned pk(float a, float b) { f32x2 v = {a, b}; return __builtin_bit_cast(unsigned, __builtin_convertvector(v, bf16x2_t)); }
; #define PG8_STAGE(bufoff, gbase, voff) do { _Pragma("unroll") for (int _i = 0; _i < 2; ++_i) \
;     __builtin_amdgcn_global_load_lds((const unsigned*)((const char*)(gbase) + (voff)[_i]), (LAS unsigned*)(lds + (bufoff) + ldsw + _i * 8192), 16, 0, 0); } while (0)
; #define PG8_MMA(ai, bj, At, Bt) do { __builtin_amdgcn_s_setprio(1); _Pragma("unroll") for (int m = 0; m < 4; ++m) _Pragma("unroll") for (int n = 0; n < 2; ++n) _Pragma("unroll") for (int k = 0; k < 2; ++k) \
;     acc[ai][bj][m][n] = __builtin_amdgcn_mfma_f32_16x16x32_bf16(Bt[n][k], At[m][k], acc[ai][bj][m][n], 0, 0, 0); __builtin_amdgcn_s_setprio(0); } while (0)
; #define PG8_WAIT_V(n) asm volatile("s_waitcnt vmcnt(" #n ")" ::: "memory")
; #define PG8_WAIT_L(n) asm volatile("s_waitcnt lgkmcnt(" #n ")" ::: "memory")
; #define PG8_BAR __builtin_amdgcn_s_barrier()
; #define PG8_SCHED __builtin_amdgcn_sched_barrier(0)
; #define ROWS_LOOP _Pragma("unroll") for (int ai = 0; ai < 2; ++ai) _Pragma("unroll") for (int m = 0; m < 4; ++m)
; template <class Epi, class Sched>
; DI void gemm_phase(LAS unsigned char* lds, const int tid, const Gemm g, const Sched& S, const Epi& E) {
;     ...
;       PG8_BAR; PG8_WAIT_L(0); PG8_MMA(1, 0, At, B0); PG8_BAR; PG8_SCHED;
;       PG8_STAGE(PG8_SB(1, 1), b3 + hstepB, voffB);
;       PG8_WAIT_V(6); PG8_BAR; PG8_MMA(1, 1, At, B1); PG8_BAR;
;   DI void operator()(const AccT& acc, const Unit& u, int wr, int wc, int fr, int fq) const {
;     const char* base = (const char*)(HID + (size_t)u.pm * 256 * DFF + u.pn * 128);
;     const unsigned o0 = (unsigned)((wr * 64 + fr) * DFF + wc * 32 + fq * 8) * 2u;
;     ROWS_LOOP {
;       char* rb = (char*)base + (size_t)(ai * 128 + m * 16) * DFF * 2;
;       f32x4 h[2];
; #pragma unroll
;       for (int n = 0; n < 2; ++n) {
;         const f32x4 gt = acc[ai][0][m][n], up = acc[ai][1][m][n];
; #pragma unroll
;         for (int e = 0; e < 4; ++e) h[n][e] = gt[e] * __builtin_amdgcn_rcpf(1.f + __expf(-gt[e])) * up[e];
;       }
;       u32x4 o = {pk(h[0][0], h[0][1]), pk(h[0][2], h[0][3]), pk(h[1][0], h[1][1]), pk(h[1][2], h[1][3])};
;       *(GAS u32x4*)(rb + o0) = o;
;     }
	s_waitcnt lgkmcnt(0)
	s_setprio 1
	s_waitcnt lgkmcnt(0)
	v_mfma_f32_16x16x32_bf16 v[62:65], v[142:145], v[158:161], v[62:65]
	v_mfma_f32_16x16x32_bf16 v[58:61], v[150:153], v[158:161], v[58:61]
	v_mfma_f32_16x16x32_bf16 v[46:49], v[142:145], v[166:169], v[46:49]
	v_mfma_f32_16x16x32_bf16 v[42:45], v[150:153], v[166:169], v[42:45]
	v_mfma_f32_16x16x32_bf16 v[30:33], v[142:145], v[174:177], v[30:33]
	v_mfma_f32_16x16x32_bf16 v[26:29], v[150:153], v[174:177], v[26:29]
	v_mfma_f32_16x16x32_bf16 v[14:17], v[142:145], v[182:185], v[14:17]
	v_mfma_f32_16x16x32_bf16 v[10:13], v[150:153], v[182:185], v[10:13]
	v_mfma_f32_16x16x32_bf16 v[62:65], v[146:149], v[162:165], v[62:65]
	v_mfma_f32_16x16x32_bf16 v[58:61], v[154:157], v[162:165], v[58:61]
	v_mfma_f32_16x16x32_bf16 v[46:49], v[146:149], v[170:173], v[46:49]
	v_mfma_f32_16x16x32_bf16 v[42:45], v[154:157], v[170:173], v[42:45]
	v_mfma_f32_16x16x32_bf16 v[30:33], v[146:149], v[178:181], v[30:33]
	v_mfma_f32_16x16x32_bf16 v[26:29], v[154:157], v[178:181], v[26:29]
	v_mfma_f32_16x16x32_bf16 v[14:17], v[146:149], v[202:205], v[14:17]
	v_mfma_f32_16x16x32_bf16 v[10:13], v[154:157], v[202:205], v[10:13]
	s_setprio 0
	s_barrier
	s_add_u32 s14, s14, 0x40080
	s_addc_u32 s15, s15, 0
	s_add_i32 s18, s18, s24
	s_mov_b32 m0, s18
	s_nop 0
	global_load_lds_dwordx4 v132, s[14:15]
	s_add_i32 m0, s18, 0x2000
	s_nop 0
	global_load_lds_dwordx4 v130, s[14:15]
	s_waitcnt vmcnt(6)
	s_barrier
	s_setprio 1
	v_mfma_f32_16x16x32_bf16 v[54:57], v[206:209], v[158:161], v[54:57]
	v_mfma_f32_16x16x32_bf16 v[50:53], v[226:229], v[158:161], v[50:53]
	v_mfma_f32_16x16x32_bf16 v[38:41], v[206:209], v[166:169], v[38:41]
	v_mfma_f32_16x16x32_bf16 v[34:37], v[226:229], v[166:169], v[34:37]
	v_mfma_f32_16x16x32_bf16 v[22:25], v[206:209], v[174:177], v[22:25]
	v_mfma_f32_16x16x32_bf16 v[18:21], v[226:229], v[174:177], v[18:21]
	v_mfma_f32_16x16x32_bf16 v[6:9], v[206:209], v[182:185], v[6:9]
	v_mfma_f32_16x16x32_bf16 v[2:5], v[226:229], v[182:185], v[2:5]
	v_mfma_f32_16x16x32_bf16 v[54:57], v[210:213], v[162:165], v[54:57]
	v_mfma_f32_16x16x32_bf16 v[50:53], v[238:241], v[162:165], v[50:53]
	v_mfma_f32_16x16x32_bf16 v[38:41], v[210:213], v[170:173], v[38:41]
	v_mfma_f32_16x16x32_bf16 v[34:37], v[238:241], v[170:173], v[34:37]
	v_mfma_f32_16x16x32_bf16 v[22:25], v[210:213], v[178:181], v[22:25]
	v_mfma_f32_16x16x32_bf16 v[18:21], v[238:241], v[178:181], v[18:21]
	v_mfma_f32_16x16x32_bf16 v[6:9], v[210:213], v[202:205], v[6:9]
	v_mfma_f32_16x16x32_bf16 v[2:5], v[238:241], v[202:205], v[2:5]
	s_setprio 0
	s_add_i32 s44, s44, 2
	s_add_u32 s42, s42, 0x100
	s_addc_u32 s43, s43, 0
	s_add_u32 s16, s16, 0x100
	s_addc_u32 s17, s17, 0
	s_cmp_gt_u32 s44, 13
	s_barrier
	s_cbranch_scc0 .LBB0_387
	v_mul_f32_e32 v139, 0xbfb8aa3b, v126
	v_exp_f32_e32 v139, v139
	v_mul_f32_e32 v142, 0xbfb8aa3b, v127
	v_exp_f32_e32 v143, v142
	s_mul_i32 s7, s12, 0x160000
	v_add_f32_e32 v139, 1.0, v139
	v_rcp_f32_e32 v142, v139
	v_add_f32_e32 v139, 1.0, v143
	v_rcp_f32_e32 v143, v139
	s_mul_hi_i32 s1, s12, 0x160000
	s_add_u32 s7, s31, s7
	v_mov_b32_e32 v0, v1
	v_pk_mul_f32 v[126:127], v[126:127], v[142:143]
	v_mul_f32_e32 v142, 0xbfb8aa3b, v128
	v_mul_f32_e32 v143, 0xbfb8aa3b, v129
	v_exp_f32_e32 v142, v142
	v_exp_f32_e32 v143, v143
	v_pk_mul_f32 v[118:119], v[126:127], v[118:119]
	s_addc_u32 s1, s34, s1
	v_add_f32_e32 v126, 1.0, v142
	v_add_f32_e32 v127, 1.0, v143
	v_mul_f32_e32 v142, 0xbfb8aa3b, v122
	v_mul_f32_e32 v143, 0xbfb8aa3b, v123
	v_rcp_f32_e32 v126, v126
	v_rcp_f32_e32 v127, v127
	v_exp_f32_e32 v142, v142
	v_exp_f32_e32 v143, v143
	s_lshl_b32 s12, s13, 7
	v_pk_mul_f32 v[126:127], v[128:129], v[126:127]
	v_add_f32_e32 v128, 1.0, v142
	v_add_f32_e32 v129, 1.0, v143
	v_mul_f32_e32 v142, 0xbfb8aa3b, v124
	v_mul_f32_e32 v143, 0xbfb8aa3b, v125
	v_exp_f32_e32 v142, v142
	v_exp_f32_e32 v143, v143
	v_rcp_f32_e32 v128, v128
	v_rcp_f32_e32 v129, v129
	v_add_f32_e32 v142, 1.0, v142
	v_add_f32_e32 v143, 1.0, v143
	v_rcp_f32_e32 v142, v142
	v_rcp_f32_e32 v143, v143
	v_pk_mul_f32 v[122:123], v[122:123], v[128:129]
	s_ashr_i32 s13, s12, 31
	v_pk_mul_f32 v[122:123], v[122:123], v[114:115]
	v_pk_mul_f32 v[114:115], v[124:125], v[142:143]
	v_mbcnt_lo_u32_b32 v0, -1, v0
	v_pk_mul_f32 v[124:125], v[114:115], v[116:117]
	v_mul_f32_e32 v115, 0xbfb8aa3b, v110
	v_exp_f32_e32 v116, v115
	v_mul_f32_e32 v115, 0xbfb8aa3b, v111
	v_exp_f32_e32 v117, v115
	s_lshl_b64 s[12:13], s[12:13], 1
	v_mbcnt_hi_u32_b32 v0, -1, v0
	s_add_u32 s12, s7, s12
	s_addc_u32 s13, s1, s13
	v_and_or_b32 v138, v0, 15, s35
	s_movk_i32 s1, 0x1600
	v_add_f32_e32 v116, 1.0, v116
	v_and_b32_e32 v0, -16, v0
	v_mul_lo_u32 v138, v138, s1
	v_pk_mul_f32 v[120:121], v[126:127], v[120:121]
	v_cvt_pk_bf16_f32 v114, v118, v119
	v_rcp_f32_e32 v118, v116
	v_add_f32_e32 v116, 1.0, v117
	v_add3_u32 v0, v0, s38, v138
	v_cvt_pk_bf16_f32 v115, v120, v121
	v_rcp_f32_e32 v119, v116
	v_cvt_pk_bf16_f32 v116, v122, v123
	v_cvt_pk_bf16_f32 v117, v124, v125
	v_lshl_add_u64 v[138:139], s[12:13], 0, v[0:1]
	global_store_dwordx4 v0, v[114:117], s[12:13]
	v_mul_f32_e32 v0, 0xbfb8aa3b, v112
	v_exp_f32_e32 v0, v0
	v_mul_f32_e32 v114, 0xbfb8aa3b, v113
	v_exp_f32_e32 v114, v114
	v_pk_mul_f32 v[110:111], v[110:111], v[118:119]
	v_add_f32_e32 v0, 1.0, v0
	v_pk_mul_f32 v[102:103], v[110:111], v[102:103]
	v_rcp_f32_e32 v110, v0
	v_add_f32_e32 v0, 1.0, v114
	v_rcp_f32_e32 v111, v0
	v_mul_f32_e32 v0, 0xbfb8aa3b, v106
	v_exp_f32_e32 v0, v0
	v_mul_f32_e32 v114, 0xbfb8aa3b, v107
	v_exp_f32_e32 v114, v114
	v_pk_mul_f32 v[110:111], v[112:113], v[110:111]
	v_add_f32_e32 v0, 1.0, v0
	v_mul_f32_e32 v113, 0xbfb8aa3b, v108
	v_rcp_f32_e32 v112, v0
; #define GAS __attribute__((address_space(1)))
; DI unsigned pk(float a, float b) { f32x2 v = {a, b}; return __builtin_bit_cast(unsigned, __builtin_convertvector(v, bf16x2_t)); }
; #define ROWS_LOOP _Pragma("unroll") for (int ai = 0; ai < 2; ++ai) _Pragma("unroll") for (int m = 0; m < 4; ++m)
;   DI void operator()(const AccT& acc, const Unit& u, int wr, int wc, int fr, int fq) const {
;     ...
;     ROWS_LOOP {
;       char* rb = (char*)base + (size_t)(ai * 128 + m * 16) * DFF * 2;
;       f32x4 h[2];
; #pragma unroll
;       for (int n = 0; n < 2; ++n) {
;         const f32x4 gt = acc[ai][0][m][n], up = acc[ai][1][m][n];
; #pragma unroll
;         for (int e = 0; e < 4; ++e) h[n][e] = gt[e] * __builtin_amdgcn_rcpf(1.f + __expf(-gt[e])) * up[e];
;       }
;       u32x4 o = {pk(h[0][0], h[0][1]), pk(h[0][2], h[0][3]), pk(h[1][0], h[1][1]), pk(h[1][2], h[1][3])};
;       *(GAS u32x4*)(rb + o0) = o;
;     }
	v_add_f32_e32 v0, 1.0, v114
	v_exp_f32_e32 v114, v113
	v_mul_f32_e32 v113, 0xbfb8aa3b, v109
	v_exp_f32_e32 v115, v113
	v_rcp_f32_e32 v113, v0
	v_add_f32_e32 v0, 1.0, v114
	v_rcp_f32_e32 v114, v0
	v_add_f32_e32 v0, 1.0, v115
	v_rcp_f32_e32 v115, v0
	v_pk_mul_f32 v[106:107], v[106:107], v[112:113]
	v_mul_f32_e32 v0, 0xbfb8aa3b, v94
	v_pk_mul_f32 v[106:107], v[106:107], v[98:99]
	v_pk_mul_f32 v[98:99], v[108:109], v[114:115]
	v_exp_f32_e32 v0, v0
	v_pk_mul_f32 v[108:109], v[98:99], v[100:101]
	v_mul_f32_e32 v101, 0xbfb8aa3b, v95
	v_cvt_pk_bf16_f32 v98, v102, v103
	v_exp_f32_e32 v103, v101
	v_pk_mul_f32 v[104:105], v[110:111], v[104:105]
	v_add_f32_e32 v0, 1.0, v0
	s_mov_b32 s1, 0x16000
	v_cvt_pk_bf16_f32 v99, v104, v105
	v_rcp_f32_e32 v102, v0
	v_add_f32_e32 v0, 1.0, v103
	v_add_co_u32_e32 v104, vcc, s1, v138
	v_cvt_pk_bf16_f32 v100, v106, v107
	v_cvt_pk_bf16_f32 v101, v108, v109
	v_rcp_f32_e32 v103, v0
	v_addc_co_u32_e32 v105, vcc, 0, v139, vcc
	v_mul_f32_e32 v0, 0xbfb8aa3b, v96
	global_store_dwordx4 v[104:105], v[98:101], off
	v_exp_f32_e32 v0, v0
	v_pk_mul_f32 v[94:95], v[94:95], v[102:103]
	v_mul_f32_e32 v98, 0xbfb8aa3b, v97
	v_exp_f32_e32 v98, v98
	v_add_f32_e32 v0, 1.0, v0
	v_pk_mul_f32 v[86:87], v[94:95], v[86:87]
	v_rcp_f32_e32 v94, v0
	v_add_f32_e32 v0, 1.0, v98
	v_rcp_f32_e32 v95, v0
	v_mul_f32_e32 v0, 0xbfb8aa3b, v90
	v_exp_f32_e32 v0, v0
	v_mul_f32_e32 v98, 0xbfb8aa3b, v91
	v_exp_f32_e32 v98, v98
	v_pk_mul_f32 v[94:95], v[96:97], v[94:95]
	v_add_f32_e32 v0, 1.0, v0
	v_mul_f32_e32 v97, 0xbfb8aa3b, v92
	v_rcp_f32_e32 v96, v0
	v_add_f32_e32 v0, 1.0, v98
	v_exp_f32_e32 v98, v97
	v_mul_f32_e32 v97, 0xbfb8aa3b, v93
	v_exp_f32_e32 v99, v97
	v_rcp_f32_e32 v97, v0
	v_add_f32_e32 v0, 1.0, v98
	v_rcp_f32_e32 v98, v0
	v_add_f32_e32 v0, 1.0, v99
	v_rcp_f32_e32 v99, v0
	v_pk_mul_f32 v[90:91], v[90:91], v[96:97]
	v_mul_f32_e32 v0, 0xbfb8aa3b, v78
	v_pk_mul_f32 v[90:91], v[90:91], v[82:83]
	v_pk_mul_f32 v[82:83], v[92:93], v[98:99]
	v_exp_f32_e32 v0, v0
	v_pk_mul_f32 v[92:93], v[82:83], v[84:85]
	v_mul_f32_e32 v85, 0xbfb8aa3b, v79
	v_cvt_pk_bf16_f32 v82, v86, v87
	v_exp_f32_e32 v87, v85
	v_pk_mul_f32 v[88:89], v[94:95], v[88:89]
	v_add_f32_e32 v0, 1.0, v0
	s_mov_b32 s1, 0x2c000
	v_cvt_pk_bf16_f32 v83, v88, v89
	v_rcp_f32_e32 v86, v0
	v_add_f32_e32 v0, 1.0, v87
	v_add_co_u32_e32 v88, vcc, s1, v138
	v_cvt_pk_bf16_f32 v84, v90, v91
	v_cvt_pk_bf16_f32 v85, v92, v93
	v_rcp_f32_e32 v87, v0
	v_addc_co_u32_e32 v89, vcc, 0, v139, vcc
	v_mul_f32_e32 v0, 0xbfb8aa3b, v80
	global_store_dwordx4 v[88:89], v[82:85], off
	v_exp_f32_e32 v0, v0
	v_pk_mul_f32 v[78:79], v[78:79], v[86:87]
	v_mul_f32_e32 v82, 0xbfb8aa3b, v81
	v_exp_f32_e32 v82, v82
	v_add_f32_e32 v0, 1.0, v0
	v_pk_mul_f32 v[70:71], v[78:79], v[70:71]
	v_rcp_f32_e32 v78, v0
	v_add_f32_e32 v0, 1.0, v82
	v_rcp_f32_e32 v79, v0
	v_mul_f32_e32 v0, 0xbfb8aa3b, v74
	v_exp_f32_e32 v0, v0
	v_mul_f32_e32 v82, 0xbfb8aa3b, v75
	v_exp_f32_e32 v82, v82
	v_pk_mul_f32 v[78:79], v[80:81], v[78:79]
	v_add_f32_e32 v0, 1.0, v0
	v_mul_f32_e32 v81, 0xbfb8aa3b, v76
	v_rcp_f32_e32 v80, v0
	v_add_f32_e32 v0, 1.0, v82
	v_exp_f32_e32 v82, v81
	v_mul_f32_e32 v81, 0xbfb8aa3b, v77
	v_exp_f32_e32 v83, v81
	v_rcp_f32_e32 v81, v0
	v_add_f32_e32 v0, 1.0, v82
	v_rcp_f32_e32 v82, v0
	v_add_f32_e32 v0, 1.0, v83
	v_rcp_f32_e32 v83, v0
	v_pk_mul_f32 v[74:75], v[74:75], v[80:81]
	v_mul_f32_e32 v0, 0xbfb8aa3b, v62
	v_pk_mul_f32 v[74:75], v[74:75], v[66:67]
	v_pk_mul_f32 v[66:67], v[76:77], v[82:83]
	v_exp_f32_e32 v0, v0
	v_pk_mul_f32 v[76:77], v[66:67], v[68:69]
	v_mul_f32_e32 v69, 0xbfb8aa3b, v63
	v_cvt_pk_bf16_f32 v66, v70, v71
	v_exp_f32_e32 v71, v69
	v_pk_mul_f32 v[72:73], v[78:79], v[72:73]
	v_add_f32_e32 v0, 1.0, v0
	s_mov_b32 s1, 0x42000
	v_cvt_pk_bf16_f32 v67, v72, v73
	v_rcp_f32_e32 v70, v0
	v_add_f32_e32 v0, 1.0, v71
	v_add_co_u32_e32 v72, vcc, s1, v138
	v_cvt_pk_bf16_f32 v68, v74, v75
	v_cvt_pk_bf16_f32 v69, v76, v77
	v_rcp_f32_e32 v71, v0
	v_addc_co_u32_e32 v73, vcc, 0, v139, vcc
	v_mul_f32_e32 v0, 0xbfb8aa3b, v64
	global_store_dwordx4 v[72:73], v[66:69], off
	v_exp_f32_e32 v0, v0
	v_pk_mul_f32 v[62:63], v[62:63], v[70:71]
	v_mul_f32_e32 v66, 0xbfb8aa3b, v65
	v_exp_f32_e32 v66, v66
	v_add_f32_e32 v0, 1.0, v0
	v_pk_mul_f32 v[54:55], v[62:63], v[54:55]
	v_rcp_f32_e32 v62, v0
	v_add_f32_e32 v0, 1.0, v66
	v_rcp_f32_e32 v63, v0
	v_mul_f32_e32 v0, 0xbfb8aa3b, v58
	v_exp_f32_e32 v0, v0
	v_mul_f32_e32 v66, 0xbfb8aa3b, v59
	v_exp_f32_e32 v66, v66
	v_pk_mul_f32 v[62:63], v[64:65], v[62:63]
	v_add_f32_e32 v0, 1.0, v0
	v_mul_f32_e32 v65, 0xbfb8aa3b, v60
	v_rcp_f32_e32 v64, v0
	v_add_f32_e32 v0, 1.0, v66
	v_exp_f32_e32 v66, v65
	v_mul_f32_e32 v65, 0xbfb8aa3b, v61
	v_exp_f32_e32 v67, v65
	v_rcp_f32_e32 v65, v0
	v_add_f32_e32 v0, 1.0, v66
	v_rcp_f32_e32 v66, v0
	v_add_f32_e32 v0, 1.0, v67
	v_rcp_f32_e32 v67, v0
	v_pk_mul_f32 v[58:59], v[58:59], v[64:65]
	v_mul_f32_e32 v0, 0xbfb8aa3b, v46
	v_pk_mul_f32 v[58:59], v[58:59], v[50:51]
	v_pk_mul_f32 v[50:51], v[60:61], v[66:67]
	v_exp_f32_e32 v0, v0
; #define GAS __attribute__((address_space(1)))
; DI unsigned pk(float a, float b) { f32x2 v = {a, b}; return __builtin_bit_cast(unsigned, __builtin_convertvector(v, bf16x2_t)); }
; #define PG8_WAIT_V(n) asm volatile("s_waitcnt vmcnt(" #n ")" ::: "memory")
; #define PG8_BAR __builtin_amdgcn_s_barrier()
; #define ROWS_LOOP _Pragma("unroll") for (int ai = 0; ai < 2; ++ai) _Pragma("unroll") for (int m = 0; m < 4; ++m)
; template <class Epi, class Sched>
; DI void gemm_phase(LAS unsigned char* lds, const int tid, const Gemm g, const Sched& S, const Epi& E) {
;     ...
;     cur = nxt; cA = nA; cB = nB; ++ui;
;   }
;   PG8_WAIT_V(0);
;   if (wr == 0) PG8_BAR;
;   PG8_BAR;
;   DI void operator()(const AccT& acc, const Unit& u, int wr, int wc, int fr, int fq) const {
;     ...
;     ROWS_LOOP {
;       char* rb = (char*)base + (size_t)(ai * 128 + m * 16) * DFF * 2;
;       f32x4 h[2];
; #pragma unroll
;       for (int n = 0; n < 2; ++n) {
;         const f32x4 gt = acc[ai][0][m][n], up = acc[ai][1][m][n];
; #pragma unroll
;         for (int e = 0; e < 4; ++e) h[n][e] = gt[e] * __builtin_amdgcn_rcpf(1.f + __expf(-gt[e])) * up[e];
;       }
;       u32x4 o = {pk(h[0][0], h[0][1]), pk(h[0][2], h[0][3]), pk(h[1][0], h[1][1]), pk(h[1][2], h[1][3])};
;       *(GAS u32x4*)(rb + o0) = o;
;     }
	v_pk_mul_f32 v[60:61], v[50:51], v[52:53]
	v_mul_f32_e32 v53, 0xbfb8aa3b, v47
	v_cvt_pk_bf16_f32 v50, v54, v55
	v_exp_f32_e32 v55, v53
	v_pk_mul_f32 v[56:57], v[62:63], v[56:57]
	v_add_f32_e32 v0, 1.0, v0
	s_mov_b32 s1, 0xb0000
	v_cvt_pk_bf16_f32 v51, v56, v57
	v_rcp_f32_e32 v54, v0
	v_add_f32_e32 v0, 1.0, v55
	v_add_co_u32_e32 v56, vcc, s1, v138
	v_cvt_pk_bf16_f32 v52, v58, v59
	v_cvt_pk_bf16_f32 v53, v60, v61
	v_rcp_f32_e32 v55, v0
	v_addc_co_u32_e32 v57, vcc, 0, v139, vcc
	v_mul_f32_e32 v0, 0xbfb8aa3b, v48
	global_store_dwordx4 v[56:57], v[50:53], off
	v_exp_f32_e32 v0, v0
	v_pk_mul_f32 v[46:47], v[46:47], v[54:55]
	v_mul_f32_e32 v50, 0xbfb8aa3b, v49
	v_exp_f32_e32 v50, v50
	v_add_f32_e32 v0, 1.0, v0
	v_pk_mul_f32 v[38:39], v[46:47], v[38:39]
	v_rcp_f32_e32 v46, v0
	v_add_f32_e32 v0, 1.0, v50
	v_rcp_f32_e32 v47, v0
	v_mul_f32_e32 v0, 0xbfb8aa3b, v42
	v_exp_f32_e32 v0, v0
	v_mul_f32_e32 v50, 0xbfb8aa3b, v43
	v_exp_f32_e32 v50, v50
	v_pk_mul_f32 v[46:47], v[48:49], v[46:47]
	v_add_f32_e32 v0, 1.0, v0
	v_mul_f32_e32 v49, 0xbfb8aa3b, v44
	v_rcp_f32_e32 v48, v0
	v_add_f32_e32 v0, 1.0, v50
	v_exp_f32_e32 v50, v49
	v_mul_f32_e32 v49, 0xbfb8aa3b, v45
	v_exp_f32_e32 v51, v49
	v_rcp_f32_e32 v49, v0
	v_add_f32_e32 v0, 1.0, v50
	v_rcp_f32_e32 v50, v0
	v_add_f32_e32 v0, 1.0, v51
	v_rcp_f32_e32 v51, v0
	v_pk_mul_f32 v[42:43], v[42:43], v[48:49]
	v_mul_f32_e32 v0, 0xbfb8aa3b, v30
	v_pk_mul_f32 v[42:43], v[42:43], v[34:35]
	v_pk_mul_f32 v[34:35], v[44:45], v[50:51]
	v_exp_f32_e32 v0, v0
	v_pk_mul_f32 v[44:45], v[34:35], v[36:37]
	v_mul_f32_e32 v37, 0xbfb8aa3b, v31
	v_cvt_pk_bf16_f32 v34, v38, v39
	v_exp_f32_e32 v39, v37
	v_pk_mul_f32 v[40:41], v[46:47], v[40:41]
	v_add_f32_e32 v0, 1.0, v0
	s_mov_b32 s1, 0xc6000
	v_cvt_pk_bf16_f32 v35, v40, v41
	v_rcp_f32_e32 v38, v0
	v_add_f32_e32 v0, 1.0, v39
	v_add_co_u32_e32 v40, vcc, s1, v138
	v_cvt_pk_bf16_f32 v36, v42, v43
	v_cvt_pk_bf16_f32 v37, v44, v45
	v_rcp_f32_e32 v39, v0
	v_addc_co_u32_e32 v41, vcc, 0, v139, vcc
	v_mul_f32_e32 v0, 0xbfb8aa3b, v32
	global_store_dwordx4 v[40:41], v[34:37], off
	v_exp_f32_e32 v0, v0
	v_pk_mul_f32 v[30:31], v[30:31], v[38:39]
	v_mul_f32_e32 v34, 0xbfb8aa3b, v33
	v_exp_f32_e32 v34, v34
	v_add_f32_e32 v0, 1.0, v0
	v_pk_mul_f32 v[22:23], v[30:31], v[22:23]
	v_rcp_f32_e32 v30, v0
	v_add_f32_e32 v0, 1.0, v34
	v_rcp_f32_e32 v31, v0
	v_mul_f32_e32 v0, 0xbfb8aa3b, v26
	v_exp_f32_e32 v0, v0
	v_mul_f32_e32 v34, 0xbfb8aa3b, v27
	v_exp_f32_e32 v34, v34
	v_pk_mul_f32 v[30:31], v[32:33], v[30:31]
	v_add_f32_e32 v0, 1.0, v0
	v_mul_f32_e32 v33, 0xbfb8aa3b, v28
	v_rcp_f32_e32 v32, v0
	v_add_f32_e32 v0, 1.0, v34
	v_exp_f32_e32 v34, v33
	v_mul_f32_e32 v33, 0xbfb8aa3b, v29
	v_exp_f32_e32 v35, v33
	v_rcp_f32_e32 v33, v0
	v_add_f32_e32 v0, 1.0, v34
	v_rcp_f32_e32 v34, v0
	v_add_f32_e32 v0, 1.0, v35
	v_rcp_f32_e32 v35, v0
	v_pk_mul_f32 v[26:27], v[26:27], v[32:33]
	v_mul_f32_e32 v0, 0xbfb8aa3b, v14
	v_pk_mul_f32 v[26:27], v[26:27], v[18:19]
	v_pk_mul_f32 v[18:19], v[28:29], v[34:35]
	v_exp_f32_e32 v0, v0
	v_pk_mul_f32 v[28:29], v[18:19], v[20:21]
	v_mul_f32_e32 v21, 0xbfb8aa3b, v15
	v_cvt_pk_bf16_f32 v18, v22, v23
	v_exp_f32_e32 v23, v21
	v_pk_mul_f32 v[24:25], v[30:31], v[24:25]
	v_add_f32_e32 v0, 1.0, v0
	s_mov_b32 s1, 0xdc000
	v_cvt_pk_bf16_f32 v19, v24, v25
	v_rcp_f32_e32 v22, v0
	v_add_f32_e32 v0, 1.0, v23
	v_add_co_u32_e32 v24, vcc, s1, v138
	v_cvt_pk_bf16_f32 v20, v26, v27
	v_cvt_pk_bf16_f32 v21, v28, v29
	v_rcp_f32_e32 v23, v0
	v_addc_co_u32_e32 v25, vcc, 0, v139, vcc
	v_mul_f32_e32 v0, 0xbfb8aa3b, v16
	global_store_dwordx4 v[24:25], v[18:21], off
	v_exp_f32_e32 v0, v0
	v_pk_mul_f32 v[14:15], v[14:15], v[22:23]
	v_mul_f32_e32 v18, 0xbfb8aa3b, v17
	v_exp_f32_e32 v18, v18
	v_add_f32_e32 v0, 1.0, v0
	v_pk_mul_f32 v[6:7], v[14:15], v[6:7]
	v_rcp_f32_e32 v14, v0
	v_add_f32_e32 v0, 1.0, v18
	v_rcp_f32_e32 v15, v0
	v_mul_f32_e32 v0, 0xbfb8aa3b, v10
	v_exp_f32_e32 v0, v0
	v_mul_f32_e32 v18, 0xbfb8aa3b, v11
	v_exp_f32_e32 v18, v18
	v_pk_mul_f32 v[14:15], v[16:17], v[14:15]
	v_add_f32_e32 v0, 1.0, v0
	v_mul_f32_e32 v17, 0xbfb8aa3b, v12
	v_rcp_f32_e32 v16, v0
	v_add_f32_e32 v0, 1.0, v18
	v_exp_f32_e32 v18, v17
	v_mul_f32_e32 v17, 0xbfb8aa3b, v13
	v_exp_f32_e32 v19, v17
	v_rcp_f32_e32 v17, v0
	v_add_f32_e32 v0, 1.0, v18
	v_rcp_f32_e32 v18, v0
	v_add_f32_e32 v0, 1.0, v19
	v_rcp_f32_e32 v19, v0
	v_pk_mul_f32 v[10:11], v[10:11], v[16:17]
	v_pk_mul_f32 v[8:9], v[14:15], v[8:9]
	v_pk_mul_f32 v[10:11], v[10:11], v[2:3]
	v_pk_mul_f32 v[2:3], v[12:13], v[18:19]
	s_mov_b32 s13, s0
	v_pk_mul_f32 v[12:13], v[2:3], v[4:5]
	v_cvt_pk_bf16_f32 v2, v6, v7
	v_add_co_u32_e32 v6, vcc, 0xf2000, v138
	v_cvt_pk_bf16_f32 v3, v8, v9
	s_nop 0
	v_addc_co_u32_e32 v7, vcc, 0, v139, vcc
	v_cvt_pk_bf16_f32 v4, v10, v11
	v_cvt_pk_bf16_f32 v5, v12, v13
	s_and_b64 vcc, exec, s[4:5]
	s_mov_b32 s12, s6
	s_mov_b64 s[16:17], s[10:11]
	s_mov_b64 s[18:19], s[8:9]
	global_store_dwordx4 v[6:7], v[2:5], off
	s_cbranch_vccz .LBB0_384
	s_waitcnt vmcnt(0)
	s_cmpk_gt_u32 s3, 0xff
	s_cbranch_scc1 .LBB0_391
	s_barrier

; DI void st8p(void* ub, unsigned voff, f32x4 a, f32x4 b) { u32x4 o = {pk(a[0], a[1]), pk(a[2], a[3]), pk(b[0], b[1]), pk(b[2], b[3])}; *(GAS u32x4*)((char*)ub + voff) = o; }
; #define ROWS_LOOP _Pragma("unroll") for (int ai = 0; ai < 2; ++ai) _Pragma("unroll") for (int m = 0; m < 4; ++m)
;   DI void operator()(const AccT& acc, const Unit& u, int wr, int wc, int fr, int fq) const {
;     const bool lat = u.pn < 128;
;     const int ld = lat ? 4096 : 512, snoff = lat ? 2048 : 256;
;     const char* base = (const char*)((lat ? ZTL + ((size_t)(u.pn >> 3) * 256 * 4096 + (u.pn & 7) * 256) : ZTC + (size_t)(u.pn - 128) * 256 * 512) + (size_t)(u.pm * 128) * ld + wr * snoff);
;     const unsigned o0 = (unsigned)(fr * ld + wc * 32 + fq * 8) * 2u;
;     ROWS_LOOP {
;       char* rb = (char*)base + (size_t)((ai * 64 + m * 16) * ld) * 2;
; #pragma unroll
;       for (int bj = 0; bj < 2; ++bj) st8p(rb + bj * 256, o0, acc[ai][bj][m][0], acc[ai][bj][m][1]);
;     }
;   }
.LBB0_443:
	s_lshl_b32 s16, s37, 7
	s_ashr_i32 s17, s16, 31
	s_lshl_b64 s[14:15], s[16:17], s14
	s_lshl_b64 s[14:15], s[14:15], 1
	v_mbcnt_lo_u32_b32 v0, -1, v0
	s_add_u32 s14, s12, s14
	v_mbcnt_hi_u32_b32 v0, -1, v0
	s_addc_u32 s15, s13, s15
	s_lshl_b32 s12, s21, s7
	v_and_b32_e32 v144, 15, v0
	s_ashr_i32 s13, s12, 31
	s_lshl_b64 s[12:13], s[12:13], 1
	v_lshlrev_b32_e32 v144, s1, v144
	s_add_u32 s12, s14, s12
	v_and_b32_e32 v0, -16, v0
	v_lshlrev_b32_e32 v144, 1, v144
	s_addc_u32 s13, s15, s13
	v_add3_u32 v0, v0, s35, v144
	v_lshl_add_u64 v[144:145], s[12:13], 0, v[0:1]
	v_cvt_pk_bf16_f32 v110, v110, v111
	v_cvt_pk_bf16_f32 v111, v112, v113
	v_cvt_pk_bf16_f32 v112, v106, v107
	v_cvt_pk_bf16_f32 v113, v108, v109
	s_lshl_b32 s96, 32, s1
	global_store_dwordx4 v0, v[110:113], s[12:13] offset:256
	v_cvt_pk_bf16_f32 v94, v94, v95
	v_cvt_pk_bf16_f32 v95, v96, v97
	v_lshl_add_u64 v[110:111], v[144:145], 0, s[96:97]
	v_cvt_pk_bf16_f32 v96, v90, v91
	v_cvt_pk_bf16_f32 v97, v92, v93
	s_lshl_b32 s96, 64, s1
	v_cvt_pk_bf16_f32 v106, v118, v119
	v_cvt_pk_bf16_f32 v107, v120, v121
	v_cvt_pk_bf16_f32 v108, v114, v115
	v_cvt_pk_bf16_f32 v109, v116, v117
	global_store_dwordx4 v[110:111], v[94:97], off offset:256
	v_cvt_pk_bf16_f32 v78, v78, v79
	v_cvt_pk_bf16_f32 v79, v80, v81
	v_lshl_add_u64 v[94:95], v[144:145], 0, s[96:97]
	v_cvt_pk_bf16_f32 v80, v74, v75
	v_cvt_pk_bf16_f32 v81, v76, v77
	s_lshl_b32 s96, 0x60, s1
	global_store_dwordx4 v[110:111], v[106:109], off
	global_store_dwordx4 v[94:95], v[78:81], off offset:256
	v_cvt_pk_bf16_f32 v90, v102, v103
	v_cvt_pk_bf16_f32 v91, v104, v105
	v_lshl_add_u64 v[78:79], v[144:145], 0, s[96:97]
	s_lshl_b32 s96, 0x80, s1
	v_cvt_pk_bf16_f32 v92, v98, v99
	v_cvt_pk_bf16_f32 v93, v100, v101
	v_cvt_pk_bf16_f32 v74, v86, v87
	v_cvt_pk_bf16_f32 v75, v88, v89
	v_cvt_pk_bf16_f32 v76, v82, v83
	v_cvt_pk_bf16_f32 v77, v84, v85
	v_cvt_pk_bf16_f32 v70, v70, v71
	v_cvt_pk_bf16_f32 v71, v72, v73
	v_cvt_pk_bf16_f32 v72, v66, v67
	v_cvt_pk_bf16_f32 v73, v68, v69
	v_lshl_add_u64 v[66:67], v[144:145], 0, s[96:97]
	v_cvt_pk_bf16_f32 v46, v46, v47
	v_cvt_pk_bf16_f32 v47, v48, v49
	v_cvt_pk_bf16_f32 v48, v42, v43
	v_cvt_pk_bf16_f32 v49, v44, v45
	s_lshl_b32 s96, 0xa0, s1
	global_store_dwordx4 v[94:95], v[90:93], off
	global_store_dwordx4 v[78:79], v[74:77], off
	global_store_dwordx4 v[78:79], v[70:73], off offset:256
	v_cvt_pk_bf16_f32 v62, v62, v63
	v_cvt_pk_bf16_f32 v63, v64, v65
	v_cvt_pk_bf16_f32 v64, v58, v59
	v_cvt_pk_bf16_f32 v65, v60, v61
	global_store_dwordx4 v[66:67], v[46:49], off offset:256
	v_cvt_pk_bf16_f32 v30, v30, v31
	v_cvt_pk_bf16_f32 v31, v32, v33
	v_lshl_add_u64 v[46:47], v[144:145], 0, s[96:97]
	v_cvt_pk_bf16_f32 v32, v26, v27
	v_cvt_pk_bf16_f32 v33, v28, v29
	s_lshl_b32 s96, 0xc0, s1
	v_cvt_pk_bf16_f32 v126, v126, v127
	v_cvt_pk_bf16_f32 v127, v128, v129
	v_cvt_pk_bf16_f32 v128, v122, v123
	v_cvt_pk_bf16_f32 v129, v124, v125
	global_store_dwordx4 v[66:67], v[62:65], off
	v_cvt_pk_bf16_f32 v42, v54, v55
	v_cvt_pk_bf16_f32 v43, v56, v57
	v_cvt_pk_bf16_f32 v44, v50, v51
	v_cvt_pk_bf16_f32 v45, v52, v53
	global_store_dwordx4 v[46:47], v[30:33], off offset:256
	v_cvt_pk_bf16_f32 v14, v14, v15
	v_cvt_pk_bf16_f32 v15, v16, v17
	v_lshl_add_u64 v[30:31], v[144:145], 0, s[96:97]
	v_cvt_pk_bf16_f32 v16, v10, v11
	v_cvt_pk_bf16_f32 v17, v12, v13
	s_lshl_b32 s96, 0xe0, s1
	global_store_dwordx4 v0, v[126:129], s[12:13]
	global_store_dwordx4 v[46:47], v[42:45], off
	v_cvt_pk_bf16_f32 v26, v38, v39
	v_cvt_pk_bf16_f32 v27, v40, v41
	v_cvt_pk_bf16_f32 v28, v34, v35
	v_cvt_pk_bf16_f32 v29, v36, v37
	global_store_dwordx4 v[30:31], v[14:17], off offset:256
	v_cvt_pk_bf16_f32 v10, v22, v23
	v_cvt_pk_bf16_f32 v11, v24, v25
	v_lshl_add_u64 v[14:15], v[144:145], 0, s[96:97]
	v_cvt_pk_bf16_f32 v12, v18, v19
	v_cvt_pk_bf16_f32 v13, v20, v21
	v_cvt_pk_bf16_f32 v6, v6, v7
	v_cvt_pk_bf16_f32 v7, v8, v9
	v_cvt_pk_bf16_f32 v8, v2, v3
	v_cvt_pk_bf16_f32 v9, v4, v5
	s_and_b64 vcc, exec, s[4:5]
	s_mov_b32 s38, s0
	s_mov_b32 s37, s6
	s_mov_b64 s[12:13], s[10:11]
	s_mov_b64 s[16:17], s[8:9]
	global_store_dwordx4 v[30:31], v[26:29], off
	global_store_dwordx4 v[14:15], v[10:13], off
	global_store_dwordx4 v[14:15], v[6:9], off offset:256
	s_cbranch_vccnz .LBB0_453

; #define PG8_STAGE(bufoff, gbase, voff) do { _Pragma("unroll") for (int _i = 0; _i < 2; ++_i) \
;     __builtin_amdgcn_global_load_lds((const unsigned*)((const char*)(gbase) + (voff)[_i]), (LAS unsigned*)(lds + (bufoff) + ldsw + _i * 8192), 16, 0, 0); } while (0)
; #define PG8_LDA(dst, b, h) do { _Pragma("unroll") for (int m = 0; m < 4; ++m) _Pragma("unroll") for (int k = 0; k < 2; ++k) dst[m][k] = *(const LAS bf16x8*)(lds + PG8_SA(b, h) + aoff + m * 2048 + k * 1024); } while (0)
; #define PG8_LDB(dst, b, h) do { _Pragma("unroll") for (int n = 0; n < 2; ++n) _Pragma("unroll") for (int k = 0; k < 2; ++k) dst[n][k] = *(const LAS bf16x8*)(lds + PG8_SB(b, h) + boff + n * 2048 + k * 1024); } while (0)
; #define PG8_MMA(ai, bj, At, Bt) do { __builtin_amdgcn_s_setprio(1); _Pragma("unroll") for (int m = 0; m < 4; ++m) _Pragma("unroll") for (int n = 0; n < 2; ++n) _Pragma("unroll") for (int k = 0; k < 2; ++k) \
;     acc[ai][bj][m][n] = __builtin_amdgcn_mfma_f32_16x16x32_bf16(Bt[n][k], At[m][k], acc[ai][bj][m][n], 0, 0, 0); __builtin_amdgcn_s_setprio(0); } while (0)
; #define PG8_WAIT_V(n) asm volatile("s_waitcnt vmcnt(" #n ")" ::: "memory")
; #define PG8_WAIT_L(n) asm volatile("s_waitcnt lgkmcnt(" #n ")" ::: "memory")
; #define PG8_BAR __builtin_amdgcn_s_barrier()
; #define PG8_SCHED __builtin_amdgcn_sched_barrier(0)
; template <class Epi, class Sched>
; DI void gemm_phase(LAS unsigned char* lds, const int tid, const Gemm g, const Sched& S, const Epi& E) {
;     ...
;       const bool last = (t == nt - 2);
;       const char* a1 = cA + (size_t)(t + 1) * kstep;
;       const char* a2 = last ? nA : cA + (size_t)(t + 2) * kstep; const char* b2 = last ? nB : cB + (size_t)(t + 2) * kstep;
;       const char* a3 = a2 + kstep; const char* b3 = b2 + kstep;
;       PG8_LDB(B0, 0, 0); PG8_SCHED; PG8_LDA(At, 0, 0); PG8_STAGE(PG8_SA(1, 1), a1 + hstepA, voffA);
;       PG8_WAIT_L(8); PG8_BAR; PG8_WAIT_L(0); PG8_MMA(0, 0, At, B0); PG8_BAR; PG8_SCHED;
;       PG8_LDB(B1, 0, 1); PG8_STAGE(PG8_SB(0, 0), b2, voffB);
;       PG8_BAR; PG8_WAIT_L(0); PG8_MMA(0, 1, At, B1); PG8_BAR;
;       PG8_LDA(At, 0, 1); PG8_STAGE(PG8_SA(0, 0), a2, voffA);
;       PG8_BAR; PG8_WAIT_L(0); PG8_MMA(1, 0, At, B0); PG8_BAR; PG8_SCHED;
;       PG8_STAGE(PG8_SB(0, 1), b2 + hstepB, voffB);
;       PG8_WAIT_V(6); PG8_BAR; PG8_MMA(1, 1, At, B1); PG8_BAR;
.LBB0_447:
	s_add_u32 s14, s12, 0xfffc0080
	s_addc_u32 s15, s13, -1
	s_add_i32 s44, 0, 0x10000
	v_add_u32_e32 v0, s44, v142
	ds_read_b128 v[144:147], v0
	ds_read_b128 v[148:151], v0 offset:1024
	ds_read_b128 v[152:155], v0 offset:2048
	ds_read_b128 v[156:159], v0 offset:3072
	s_cmp_eq_u32 s43, 12
	s_cselect_b32 s17, s7, s15
	s_cselect_b32 s16, s39, s14
	s_cselect_b32 s15, s1, s42
	s_cselect_b32 s14, s40, s41
	s_add_i32 m0, s23, 0xc000
	ds_read_b128 v[160:163], v143
	ds_read_b128 v[164:167], v143 offset:1024
	ds_read_b128 v[168:171], v143 offset:2048
	ds_read_b128 v[172:175], v143 offset:3072
	ds_read_b128 v[176:179], v143 offset:4096
	ds_read_b128 v[180:183], v143 offset:5120
	ds_read_b128 v[202:205], v143 offset:6144
	ds_read_b128 v[206:209], v143 offset:7168
	global_load_lds_dwordx4 v140, s[12:13]
	s_add_i32 m0, s23, 0xe000
	s_nop 0
	global_load_lds_dwordx4 v138, s[12:13]
	s_waitcnt lgkmcnt(8)
	s_barrier
	s_waitcnt lgkmcnt(0)
	s_setprio 1
	s_waitcnt lgkmcnt(0)
	v_mfma_f32_16x16x32_bf16 v[126:129], v[144:147], v[160:163], v[126:129]
	v_mfma_f32_16x16x32_bf16 v[122:125], v[152:155], v[160:163], v[122:125]
	v_mfma_f32_16x16x32_bf16 v[118:121], v[144:147], v[168:171], v[118:121]
	v_mfma_f32_16x16x32_bf16 v[114:117], v[152:155], v[168:171], v[114:117]
	v_mfma_f32_16x16x32_bf16 v[102:105], v[144:147], v[176:179], v[102:105]
	v_mfma_f32_16x16x32_bf16 v[98:101], v[152:155], v[176:179], v[98:101]
	v_mfma_f32_16x16x32_bf16 v[86:89], v[144:147], v[202:205], v[86:89]
	v_mfma_f32_16x16x32_bf16 v[82:85], v[152:155], v[202:205], v[82:85]
	v_mfma_f32_16x16x32_bf16 v[126:129], v[148:151], v[164:167], v[126:129]
	v_mfma_f32_16x16x32_bf16 v[122:125], v[156:159], v[164:167], v[122:125]
	v_mfma_f32_16x16x32_bf16 v[118:121], v[148:151], v[172:175], v[118:121]
	v_mfma_f32_16x16x32_bf16 v[114:117], v[156:159], v[172:175], v[114:117]
	v_mfma_f32_16x16x32_bf16 v[102:105], v[148:151], v[180:183], v[102:105]
	v_mfma_f32_16x16x32_bf16 v[98:101], v[156:159], v[180:183], v[98:101]
	v_mfma_f32_16x16x32_bf16 v[86:89], v[148:151], v[206:209], v[86:89]
	v_mfma_f32_16x16x32_bf16 v[82:85], v[156:159], v[206:209], v[82:85]
	s_setprio 0
	s_barrier
	s_add_i32 s48, 0, 0x14000
	s_add_i32 s44, s44, s22
	v_add_u32_e32 v0, s48, v142
	s_add_u32 s98, s14, s50
	s_addc_u32 s99, s15, s51
	s_mov_b32 m0, s44
	ds_read_b128 v[210:213], v0
	ds_read_b128 v[226:229], v0 offset:1024
	ds_read_b128 v[238:241], v0 offset:2048
	ds_read_b128 v[242:245], v0 offset:3072
	global_load_lds_dwordx4 v134, s[14:15]
	s_add_i32 m0, s44, 0x2000
	s_nop 0
	global_load_lds_dwordx4 v130, s[14:15]
	s_barrier
	s_waitcnt lgkmcnt(0)
	s_setprio 1
	s_waitcnt lgkmcnt(0)
	v_mfma_f32_16x16x32_bf16 v[110:113], v[210:213], v[160:163], v[110:113]
	v_mfma_f32_16x16x32_bf16 v[106:109], v[238:241], v[160:163], v[106:109]
	v_mfma_f32_16x16x32_bf16 v[94:97], v[210:213], v[168:171], v[94:97]
	v_mfma_f32_16x16x32_bf16 v[90:93], v[238:241], v[168:171], v[90:93]
	v_mfma_f32_16x16x32_bf16 v[78:81], v[210:213], v[176:179], v[78:81]
	v_mfma_f32_16x16x32_bf16 v[74:77], v[238:241], v[176:179], v[74:77]
	v_mfma_f32_16x16x32_bf16 v[70:73], v[210:213], v[202:205], v[70:73]
	v_mfma_f32_16x16x32_bf16 v[66:69], v[238:241], v[202:205], v[66:69]
	v_mfma_f32_16x16x32_bf16 v[110:113], v[226:229], v[164:167], v[110:113]
	v_mfma_f32_16x16x32_bf16 v[106:109], v[242:245], v[164:167], v[106:109]
	v_mfma_f32_16x16x32_bf16 v[94:97], v[226:229], v[172:175], v[94:97]
	v_mfma_f32_16x16x32_bf16 v[90:93], v[242:245], v[172:175], v[90:93]
	v_mfma_f32_16x16x32_bf16 v[78:81], v[226:229], v[180:183], v[78:81]
	v_mfma_f32_16x16x32_bf16 v[74:77], v[242:245], v[180:183], v[74:77]
	v_mfma_f32_16x16x32_bf16 v[70:73], v[226:229], v[206:209], v[70:73]
	v_mfma_f32_16x16x32_bf16 v[66:69], v[242:245], v[206:209], v[66:69]
	s_setprio 0
	s_mov_b32 m0, s23
	s_add_u32 s100, s16, s50
	s_addc_u32 s101, s17, s51
	s_barrier
	ds_read_b128 v[160:163], v143 offset:16384
	ds_read_b128 v[164:167], v143 offset:17408
	ds_read_b128 v[168:171], v143 offset:18432
	ds_read_b128 v[172:175], v143 offset:19456
	ds_read_b128 v[176:179], v143 offset:20480
	ds_read_b128 v[180:183], v143 offset:21504
	ds_read_b128 v[202:205], v143 offset:22528
	ds_read_b128 v[206:209], v143 offset:23552
	global_load_lds_dwordx4 v136, s[16:17]
	s_mov_b32 m0, s24
	s_nop 0
	global_load_lds_dwordx4 v132, s[16:17]
	s_barrier
	s_waitcnt lgkmcnt(0)
	s_setprio 1
	s_waitcnt lgkmcnt(0)
	v_mfma_f32_16x16x32_bf16 v[62:65], v[144:147], v[160:163], v[62:65]
	v_mfma_f32_16x16x32_bf16 v[58:61], v[152:155], v[160:163], v[58:61]
	v_mfma_f32_16x16x32_bf16 v[54:57], v[144:147], v[168:171], v[54:57]
	v_mfma_f32_16x16x32_bf16 v[50:53], v[152:155], v[168:171], v[50:53]
	v_mfma_f32_16x16x32_bf16 v[38:41], v[144:147], v[176:179], v[38:41]
	v_mfma_f32_16x16x32_bf16 v[34:37], v[152:155], v[176:179], v[34:37]
	v_mfma_f32_16x16x32_bf16 v[22:25], v[144:147], v[202:205], v[22:25]
	v_mfma_f32_16x16x32_bf16 v[18:21], v[152:155], v[202:205], v[18:21]
	v_mfma_f32_16x16x32_bf16 v[62:65], v[148:151], v[164:167], v[62:65]
	v_mfma_f32_16x16x32_bf16 v[58:61], v[156:159], v[164:167], v[58:61]
	v_mfma_f32_16x16x32_bf16 v[54:57], v[148:151], v[172:175], v[54:57]
	v_mfma_f32_16x16x32_bf16 v[50:53], v[156:159], v[172:175], v[50:53]
	v_mfma_f32_16x16x32_bf16 v[38:41], v[148:151], v[180:183], v[38:41]
	v_mfma_f32_16x16x32_bf16 v[34:37], v[156:159], v[180:183], v[34:37]
	v_mfma_f32_16x16x32_bf16 v[22:25], v[148:151], v[206:209], v[22:25]
	v_mfma_f32_16x16x32_bf16 v[18:21], v[156:159], v[206:209], v[18:21]
	s_setprio 0
	s_barrier
	s_add_u32 s46, s14, 0x40000
	s_addc_u32 s47, s15, 0
	s_add_i32 s44, s48, s22
	s_mov_b32 m0, s44
	s_nop 0
	global_load_lds_dwordx4 v134, s[46:47]
	s_add_i32 m0, s44, 0x2000
	s_nop 0
	global_load_lds_dwordx4 v130, s[46:47]
	s_waitcnt vmcnt(6)
	s_barrier
; #define PG8_STAGE(bufoff, gbase, voff) do { _Pragma("unroll") for (int _i = 0; _i < 2; ++_i) \
;     __builtin_amdgcn_global_load_lds((const unsigned*)((const char*)(gbase) + (voff)[_i]), (LAS unsigned*)(lds + (bufoff) + ldsw + _i * 8192), 16, 0, 0); } while (0)
; #define PG8_LDA(dst, b, h) do { _Pragma("unroll") for (int m = 0; m < 4; ++m) _Pragma("unroll") for (int k = 0; k < 2; ++k) dst[m][k] = *(const LAS bf16x8*)(lds + PG8_SA(b, h) + aoff + m * 2048 + k * 1024); } while (0)
; #define PG8_LDB(dst, b, h) do { _Pragma("unroll") for (int n = 0; n < 2; ++n) _Pragma("unroll") for (int k = 0; k < 2; ++k) dst[n][k] = *(const LAS bf16x8*)(lds + PG8_SB(b, h) + boff + n * 2048 + k * 1024); } while (0)
; #define PG8_MMA(ai, bj, At, Bt) do { __builtin_amdgcn_s_setprio(1); _Pragma("unroll") for (int m = 0; m < 4; ++m) _Pragma("unroll") for (int n = 0; n < 2; ++n) _Pragma("unroll") for (int k = 0; k < 2; ++k) \
;     acc[ai][bj][m][n] = __builtin_amdgcn_mfma_f32_16x16x32_bf16(Bt[n][k], At[m][k], acc[ai][bj][m][n], 0, 0, 0); __builtin_amdgcn_s_setprio(0); } while (0)
; #define PG8_WAIT_V(n) asm volatile("s_waitcnt vmcnt(" #n ")" ::: "memory")
; #define PG8_WAIT_L(n) asm volatile("s_waitcnt lgkmcnt(" #n ")" ::: "memory")
; #define PG8_BAR __builtin_amdgcn_s_barrier()
; #define PG8_SCHED __builtin_amdgcn_sched_barrier(0)
; template <class Epi, class Sched>
; DI void gemm_phase(LAS unsigned char* lds, const int tid, const Gemm g, const Sched& S, const Epi& E) {
;     ...
;       PG8_WAIT_V(6); PG8_BAR; PG8_MMA(1, 1, At, B1); PG8_BAR;
;       PG8_LDB(B0, 1, 0); PG8_SCHED; PG8_LDA(At, 1, 0); PG8_STAGE(PG8_SA(0, 1), a2 + hstepA, voffA);
;       PG8_WAIT_L(8); PG8_BAR; PG8_WAIT_L(0); PG8_MMA(0, 0, At, B0); PG8_BAR; PG8_SCHED;
;       PG8_LDB(B1, 1, 1); PG8_STAGE(PG8_SB(1, 0), b3, voffB);
;       PG8_BAR; PG8_WAIT_L(0); PG8_MMA(0, 1, At, B1); PG8_BAR;
;       PG8_LDA(At, 1, 1); PG8_STAGE(PG8_SA(1, 0), a3, voffA);
;       PG8_BAR; PG8_WAIT_L(0); PG8_MMA(1, 0, At, B0); PG8_BAR; PG8_SCHED;
	s_setprio 1
	v_mfma_f32_16x16x32_bf16 v[46:49], v[210:213], v[160:163], v[46:49]
	v_mfma_f32_16x16x32_bf16 v[42:45], v[238:241], v[160:163], v[42:45]
	v_mfma_f32_16x16x32_bf16 v[30:33], v[210:213], v[168:171], v[30:33]
	v_mfma_f32_16x16x32_bf16 v[26:29], v[238:241], v[168:171], v[26:29]
	v_mfma_f32_16x16x32_bf16 v[14:17], v[210:213], v[176:179], v[14:17]
	v_mfma_f32_16x16x32_bf16 v[10:13], v[238:241], v[176:179], v[10:13]
	v_mfma_f32_16x16x32_bf16 v[6:9], v[210:213], v[202:205], v[6:9]
	v_mfma_f32_16x16x32_bf16 v[2:5], v[238:241], v[202:205], v[2:5]
	v_mfma_f32_16x16x32_bf16 v[46:49], v[226:229], v[164:167], v[46:49]
	v_mfma_f32_16x16x32_bf16 v[42:45], v[242:245], v[164:167], v[42:45]
	v_mfma_f32_16x16x32_bf16 v[30:33], v[226:229], v[172:175], v[30:33]
	v_mfma_f32_16x16x32_bf16 v[26:29], v[242:245], v[172:175], v[26:29]
	v_mfma_f32_16x16x32_bf16 v[14:17], v[226:229], v[180:183], v[14:17]
	v_mfma_f32_16x16x32_bf16 v[10:13], v[242:245], v[180:183], v[10:13]
	v_mfma_f32_16x16x32_bf16 v[6:9], v[226:229], v[206:209], v[6:9]
	v_mfma_f32_16x16x32_bf16 v[2:5], v[242:245], v[206:209], v[2:5]
	s_setprio 0
	s_add_i32 s44, 0, 0x18000
	v_add_u32_e32 v0, s44, v142
	s_barrier
	ds_read_b128 v[144:147], v0
	ds_read_b128 v[148:151], v0 offset:1024
	ds_read_b128 v[152:155], v0 offset:2048
	ds_read_b128 v[156:159], v0 offset:3072
	s_add_u32 s16, s16, 0x40000
	s_addc_u32 s17, s17, 0
	s_mov_b32 m0, s25
	ds_read_b128 v[160:163], v143 offset:32768
	ds_read_b128 v[164:167], v143 offset:33792
	ds_read_b128 v[168:171], v143 offset:34816
	ds_read_b128 v[172:175], v143 offset:35840
	ds_read_b128 v[176:179], v143 offset:36864
	ds_read_b128 v[180:183], v143 offset:37888
	ds_read_b128 v[202:205], v143 offset:38912
	ds_read_b128 v[206:209], v143 offset:39936
	global_load_lds_dwordx4 v136, s[16:17]
	s_mov_b32 m0, s26
	s_nop 0
	global_load_lds_dwordx4 v132, s[16:17]
	s_waitcnt lgkmcnt(8)
	s_barrier
	s_waitcnt lgkmcnt(0)
	s_setprio 1
	s_waitcnt lgkmcnt(0)
	v_mfma_f32_16x16x32_bf16 v[126:129], v[144:147], v[160:163], v[126:129]
	v_mfma_f32_16x16x32_bf16 v[122:125], v[152:155], v[160:163], v[122:125]
	v_mfma_f32_16x16x32_bf16 v[118:121], v[144:147], v[168:171], v[118:121]
	v_mfma_f32_16x16x32_bf16 v[114:117], v[152:155], v[168:171], v[114:117]
	v_mfma_f32_16x16x32_bf16 v[102:105], v[144:147], v[176:179], v[102:105]
	v_mfma_f32_16x16x32_bf16 v[98:101], v[152:155], v[176:179], v[98:101]
	v_mfma_f32_16x16x32_bf16 v[86:89], v[144:147], v[202:205], v[86:89]
	v_mfma_f32_16x16x32_bf16 v[82:85], v[152:155], v[202:205], v[82:85]
	v_mfma_f32_16x16x32_bf16 v[126:129], v[148:151], v[164:167], v[126:129]
	v_mfma_f32_16x16x32_bf16 v[122:125], v[156:159], v[164:167], v[122:125]
	v_mfma_f32_16x16x32_bf16 v[118:121], v[148:151], v[172:175], v[118:121]
	v_mfma_f32_16x16x32_bf16 v[114:117], v[156:159], v[172:175], v[114:117]
	v_mfma_f32_16x16x32_bf16 v[102:105], v[148:151], v[180:183], v[102:105]
	v_mfma_f32_16x16x32_bf16 v[98:101], v[156:159], v[180:183], v[98:101]
	v_mfma_f32_16x16x32_bf16 v[86:89], v[148:151], v[206:209], v[86:89]
	v_mfma_f32_16x16x32_bf16 v[82:85], v[156:159], v[206:209], v[82:85]
	s_setprio 0
	s_barrier
	s_add_i32 s16, 0, 0x1c000
	s_add_i32 s17, s44, s22
	v_add_u32_e32 v0, s16, v142
	s_mov_b32 m0, s17
	ds_read_b128 v[210:213], v0
	ds_read_b128 v[226:229], v0 offset:1024
	ds_read_b128 v[238:241], v0 offset:2048
	ds_read_b128 v[242:245], v0 offset:3072
	global_load_lds_dwordx4 v134, s[98:99]
	s_add_i32 m0, s17, 0x2000
	s_nop 0
	global_load_lds_dwordx4 v130, s[98:99]
	s_barrier
; #define PG8_STAGE(bufoff, gbase, voff) do { _Pragma("unroll") for (int _i = 0; _i < 2; ++_i) \
;     __builtin_amdgcn_global_load_lds((const unsigned*)((const char*)(gbase) + (voff)[_i]), (LAS unsigned*)(lds + (bufoff) + ldsw + _i * 8192), 16, 0, 0); } while (0)
; #define PG8_LDA(dst, b, h) do { _Pragma("unroll") for (int m = 0; m < 4; ++m) _Pragma("unroll") for (int k = 0; k < 2; ++k) dst[m][k] = *(const LAS bf16x8*)(lds + PG8_SA(b, h) + aoff + m * 2048 + k * 1024); } while (0)
; #define PG8_MMA(ai, bj, At, Bt) do { __builtin_amdgcn_s_setprio(1); _Pragma("unroll") for (int m = 0; m < 4; ++m) _Pragma("unroll") for (int n = 0; n < 2; ++n) _Pragma("unroll") for (int k = 0; k < 2; ++k) \
;     acc[ai][bj][m][n] = __builtin_amdgcn_mfma_f32_16x16x32_bf16(Bt[n][k], At[m][k], acc[ai][bj][m][n], 0, 0, 0); __builtin_amdgcn_s_setprio(0); } while (0)
; #define PG8_WAIT_V(n) asm volatile("s_waitcnt vmcnt(" #n ")" ::: "memory")
; #define PG8_WAIT_L(n) asm volatile("s_waitcnt lgkmcnt(" #n ")" ::: "memory")
; #define PG8_BAR __builtin_amdgcn_s_barrier()
; #define PG8_SCHED __builtin_amdgcn_sched_barrier(0)
; template <class Epi, class Sched>
; DI void gemm_phase(LAS unsigned char* lds, const int tid, const Gemm g, const Sched& S, const Epi& E) {
;     ...
;       PG8_BAR; PG8_WAIT_L(0); PG8_MMA(0, 1, At, B1); PG8_BAR;
;       PG8_LDA(At, 1, 1); PG8_STAGE(PG8_SA(1, 0), a3, voffA);
;       PG8_BAR; PG8_WAIT_L(0); PG8_MMA(1, 0, At, B0); PG8_BAR; PG8_SCHED;
;       PG8_STAGE(PG8_SB(1, 1), b3 + hstepB, voffB);
;       PG8_WAIT_V(6); PG8_BAR; PG8_MMA(1, 1, At, B1); PG8_BAR;
;     }
;     { int z_e = 0; asm volatile("" : "+v"(z_e)); const int lane_e = __builtin_amdgcn_mbcnt_hi(~0u, __builtin_amdgcn_mbcnt_lo(~0u, (unsigned)z_e));
;       E(acc, cur, wr, wc, lane_e & 15, lane_e >> 4); }
;   DI void operator()(const AccT& acc, const Unit& u, int wr, int wc, int fr, int fq) const {
;     const bool lat = u.pn < 128;
;     const int ld = lat ? 4096 : 512, snoff = lat ? 2048 : 256;
;     const char* base = (const char*)((lat ? ZTL + ((size_t)(u.pn >> 3) * 256 * 4096 + (u.pn & 7) * 256) : ZTC + (size_t)(u.pn - 128) * 256 * 512) + (size_t)(u.pm * 128) * ld + wr * snoff);
	s_waitcnt lgkmcnt(0)
	s_setprio 1
	s_waitcnt lgkmcnt(0)
	v_mfma_f32_16x16x32_bf16 v[110:113], v[210:213], v[160:163], v[110:113]
	v_mfma_f32_16x16x32_bf16 v[106:109], v[238:241], v[160:163], v[106:109]
	v_mfma_f32_16x16x32_bf16 v[94:97], v[210:213], v[168:171], v[94:97]
	v_mfma_f32_16x16x32_bf16 v[90:93], v[238:241], v[168:171], v[90:93]
	v_mfma_f32_16x16x32_bf16 v[78:81], v[210:213], v[176:179], v[78:81]
	v_mfma_f32_16x16x32_bf16 v[74:77], v[238:241], v[176:179], v[74:77]
	v_mfma_f32_16x16x32_bf16 v[70:73], v[210:213], v[202:205], v[70:73]
	v_mfma_f32_16x16x32_bf16 v[66:69], v[238:241], v[202:205], v[66:69]
	v_mfma_f32_16x16x32_bf16 v[110:113], v[226:229], v[164:167], v[110:113]
	v_mfma_f32_16x16x32_bf16 v[106:109], v[242:245], v[164:167], v[106:109]
	v_mfma_f32_16x16x32_bf16 v[94:97], v[226:229], v[172:175], v[94:97]
	v_mfma_f32_16x16x32_bf16 v[90:93], v[242:245], v[172:175], v[90:93]
	v_mfma_f32_16x16x32_bf16 v[78:81], v[226:229], v[180:183], v[78:81]
	v_mfma_f32_16x16x32_bf16 v[74:77], v[242:245], v[180:183], v[74:77]
	v_mfma_f32_16x16x32_bf16 v[70:73], v[226:229], v[206:209], v[70:73]
	v_mfma_f32_16x16x32_bf16 v[66:69], v[242:245], v[206:209], v[66:69]
	s_setprio 0
	s_mov_b32 m0, s31
	s_barrier
	ds_read_b128 v[160:163], v143 offset:49152
	ds_read_b128 v[164:167], v143 offset:50176
	ds_read_b128 v[168:171], v143 offset:51200
	ds_read_b128 v[172:175], v143 offset:52224
	ds_read_b128 v[176:179], v143 offset:53248
	ds_read_b128 v[180:183], v143 offset:54272
	ds_read_b128 v[202:205], v143 offset:55296
	ds_read_b128 v[206:209], v143 offset:56320
	global_load_lds_dwordx4 v136, s[100:101]
	s_mov_b32 m0, s34
	s_nop 0
	global_load_lds_dwordx4 v132, s[100:101]
	s_barrier
	s_waitcnt lgkmcnt(0)
	s_setprio 1
	s_waitcnt lgkmcnt(0)
	v_mfma_f32_16x16x32_bf16 v[62:65], v[144:147], v[160:163], v[62:65]
	v_mfma_f32_16x16x32_bf16 v[58:61], v[152:155], v[160:163], v[58:61]
	v_mfma_f32_16x16x32_bf16 v[54:57], v[144:147], v[168:171], v[54:57]
	v_mfma_f32_16x16x32_bf16 v[50:53], v[152:155], v[168:171], v[50:53]
	v_mfma_f32_16x16x32_bf16 v[38:41], v[144:147], v[176:179], v[38:41]
	v_mfma_f32_16x16x32_bf16 v[34:37], v[152:155], v[176:179], v[34:37]
	v_mfma_f32_16x16x32_bf16 v[22:25], v[144:147], v[202:205], v[22:25]
	v_mfma_f32_16x16x32_bf16 v[18:21], v[152:155], v[202:205], v[18:21]
	v_mfma_f32_16x16x32_bf16 v[62:65], v[148:151], v[164:167], v[62:65]
	v_mfma_f32_16x16x32_bf16 v[58:61], v[156:159], v[164:167], v[58:61]
	v_mfma_f32_16x16x32_bf16 v[54:57], v[148:151], v[172:175], v[54:57]
	v_mfma_f32_16x16x32_bf16 v[50:53], v[156:159], v[172:175], v[50:53]
	v_mfma_f32_16x16x32_bf16 v[38:41], v[148:151], v[180:183], v[38:41]
	v_mfma_f32_16x16x32_bf16 v[34:37], v[156:159], v[180:183], v[34:37]
	v_mfma_f32_16x16x32_bf16 v[22:25], v[148:151], v[206:209], v[22:25]
	v_mfma_f32_16x16x32_bf16 v[18:21], v[156:159], v[206:209], v[18:21]
	s_setprio 0
	s_barrier
	s_add_u32 s14, s14, 0x40080
	s_addc_u32 s15, s15, 0
	s_add_i32 s16, s16, s22
	s_mov_b32 m0, s16
	s_nop 0
	global_load_lds_dwordx4 v134, s[14:15]
	s_add_i32 m0, s16, 0x2000
	s_nop 0
	global_load_lds_dwordx4 v130, s[14:15]
	s_waitcnt vmcnt(6)
	s_barrier
	s_setprio 1
	v_mfma_f32_16x16x32_bf16 v[46:49], v[210:213], v[160:163], v[46:49]
	v_mfma_f32_16x16x32_bf16 v[42:45], v[238:241], v[160:163], v[42:45]
	v_mfma_f32_16x16x32_bf16 v[30:33], v[210:213], v[168:171], v[30:33]
	v_mfma_f32_16x16x32_bf16 v[26:29], v[238:241], v[168:171], v[26:29]
	v_mfma_f32_16x16x32_bf16 v[14:17], v[210:213], v[176:179], v[14:17]
	v_mfma_f32_16x16x32_bf16 v[10:13], v[238:241], v[176:179], v[10:13]
	v_mfma_f32_16x16x32_bf16 v[6:9], v[210:213], v[202:205], v[6:9]
	v_mfma_f32_16x16x32_bf16 v[2:5], v[238:241], v[202:205], v[2:5]
	v_mfma_f32_16x16x32_bf16 v[46:49], v[226:229], v[164:167], v[46:49]
	v_mfma_f32_16x16x32_bf16 v[42:45], v[242:245], v[164:167], v[42:45]
	v_mfma_f32_16x16x32_bf16 v[30:33], v[226:229], v[172:175], v[30:33]
	v_mfma_f32_16x16x32_bf16 v[26:29], v[242:245], v[172:175], v[26:29]
	v_mfma_f32_16x16x32_bf16 v[14:17], v[226:229], v[180:183], v[14:17]
	v_mfma_f32_16x16x32_bf16 v[10:13], v[242:245], v[180:183], v[10:13]
	v_mfma_f32_16x16x32_bf16 v[6:9], v[226:229], v[206:209], v[6:9]
	v_mfma_f32_16x16x32_bf16 v[2:5], v[242:245], v[206:209], v[2:5]
	s_setprio 0
	s_add_i32 s43, s43, 2
	s_add_u32 s41, s41, 0x100
	s_addc_u32 s42, s42, 0
	s_add_u32 s12, s12, 0x100
	s_addc_u32 s13, s13, 0
	s_cmp_gt_u32 s43, 13
	s_barrier
	s_cbranch_scc0 .LBB0_447
	v_mov_b32_e32 v0, v1
	s_cmpk_gt_i32 s38, 0x7f
	s_mov_b64 s[14:15], -1
	s_cbranch_scc0 .LBB0_450
	s_add_i32 s96, s38, 0xffffff80
	s_lshl_b64 s[12:13], s[96:97], 18
	s_add_u32 s12, s29, s12
	s_addc_u32 s13, s30, s13
	s_mov_b64 s[14:15], 0

; #define PG8_STAGE(bufoff, gbase, voff) do { _Pragma("unroll") for (int _i = 0; _i < 2; ++_i) \
;     __builtin_amdgcn_global_load_lds((const unsigned*)((const char*)(gbase) + (voff)[_i]), (LAS unsigned*)(lds + (bufoff) + ldsw + _i * 8192), 16, 0, 0); } while (0)
; #define PG8_LDA(dst, b, h) do { _Pragma("unroll") for (int m = 0; m < 4; ++m) _Pragma("unroll") for (int k = 0; k < 2; ++k) dst[m][k] = *(const LAS bf16x8*)(lds + PG8_SA(b, h) + aoff + m * 2048 + k * 1024); } while (0)
; #define PG8_LDB(dst, b, h) do { _Pragma("unroll") for (int n = 0; n < 2; ++n) _Pragma("unroll") for (int k = 0; k < 2; ++k) dst[n][k] = *(const LAS bf16x8*)(lds + PG8_SB(b, h) + boff + n * 2048 + k * 1024); } while (0)
; #define PG8_MMA(ai, bj, At, Bt) do { __builtin_amdgcn_s_setprio(1); _Pragma("unroll") for (int m = 0; m < 4; ++m) _Pragma("unroll") for (int n = 0; n < 2; ++n) _Pragma("unroll") for (int k = 0; k < 2; ++k) \
;     acc[ai][bj][m][n] = __builtin_amdgcn_mfma_f32_16x16x32_bf16(Bt[n][k], At[m][k], acc[ai][bj][m][n], 0, 0, 0); __builtin_amdgcn_s_setprio(0); } while (0)
; #define PG8_WAIT_V(n) asm volatile("s_waitcnt vmcnt(" #n ")" ::: "memory")
; #define PG8_WAIT_L(n) asm volatile("s_waitcnt lgkmcnt(" #n ")" ::: "memory")
; #define PG8_BAR __builtin_amdgcn_s_barrier()
; #define PG8_SCHED __builtin_amdgcn_sched_barrier(0)
; template <class Epi, class Sched>
; DI void gemm_phase(LAS unsigned char* lds, const int tid, const Gemm g, const Sched& S, const Epi& E) {
;     ...
;       const bool last = (t == nt - 2);
;       const char* a1 = cA + (size_t)(t + 1) * kstep;
;       const char* a2 = last ? nA : cA + (size_t)(t + 2) * kstep; const char* b2 = last ? nB : cB + (size_t)(t + 2) * kstep;
;       const char* a3 = a2 + kstep; const char* b3 = b2 + kstep;
;       PG8_LDB(B0, 0, 0); PG8_SCHED; PG8_LDA(At, 0, 0); PG8_STAGE(PG8_SA(1, 1), a1 + hstepA, voffA);
;       PG8_WAIT_L(8); PG8_BAR; PG8_WAIT_L(0); PG8_MMA(0, 0, At, B0); PG8_BAR; PG8_SCHED;
;       PG8_LDB(B1, 0, 1); PG8_STAGE(PG8_SB(0, 0), b2, voffB);
;       PG8_BAR; PG8_WAIT_L(0); PG8_MMA(0, 1, At, B1); PG8_BAR;
;       PG8_LDA(At, 0, 1); PG8_STAGE(PG8_SA(0, 0), a2, voffA);
;       PG8_BAR; PG8_WAIT_L(0); PG8_MMA(1, 0, At, B0); PG8_BAR; PG8_SCHED;
;       PG8_STAGE(PG8_SB(0, 1), b2 + hstepB, voffB);
;       PG8_WAIT_V(6); PG8_BAR; PG8_MMA(1, 1, At, B1); PG8_BAR;
.LBB0_467:
	s_add_u32 s14, s0, 0xfffc0080
	s_addc_u32 s15, s1, -1
	s_add_i32 s39, 0, 0x10000
	v_add_u32_e32 v0, s39, v239
	ds_read_b128 v[130:133], v0
	ds_read_b128 v[134:137], v0 offset:1024
	ds_read_b128 v[138:141], v0 offset:2048
	ds_read_b128 v[142:145], v0 offset:3072
	s_cmp_eq_u32 s38, 12
	s_cselect_b32 s31, s7, s15
	s_cselect_b32 s30, s9, s14
	s_cselect_b32 s15, s23, s35
	s_cselect_b32 s14, s25, s34
	s_add_i32 m0, s41, 0xc000
	ds_read_b128 v[146:149], v241
	ds_read_b128 v[150:153], v241 offset:1024
	ds_read_b128 v[154:157], v241 offset:2048
	ds_read_b128 v[158:161], v241 offset:3072
	ds_read_b128 v[162:165], v241 offset:4096
	ds_read_b128 v[166:169], v241 offset:5120
	ds_read_b128 v[170:173], v241 offset:6144
	ds_read_b128 v[174:177], v241 offset:7168
	global_load_lds_dwordx4 v208, s[0:1]
	s_add_i32 m0, s41, 0xe000
	s_nop 0
	global_load_lds_dwordx4 v206, s[0:1]
	s_waitcnt lgkmcnt(8)
	s_barrier
	s_waitcnt lgkmcnt(0)
	s_setprio 1
	s_waitcnt lgkmcnt(0)
	v_mfma_f32_16x16x32_bf16 v[126:129], v[130:133], v[146:149], v[126:129]
	v_mfma_f32_16x16x32_bf16 v[122:125], v[138:141], v[146:149], v[122:125]
	v_mfma_f32_16x16x32_bf16 v[110:113], v[130:133], v[154:157], v[110:113]
	v_mfma_f32_16x16x32_bf16 v[106:109], v[138:141], v[154:157], v[106:109]
	v_mfma_f32_16x16x32_bf16 v[94:97], v[130:133], v[162:165], v[94:97]
	v_mfma_f32_16x16x32_bf16 v[90:93], v[138:141], v[162:165], v[90:93]
	v_mfma_f32_16x16x32_bf16 v[78:81], v[130:133], v[170:173], v[78:81]
	v_mfma_f32_16x16x32_bf16 v[74:77], v[138:141], v[170:173], v[74:77]
	v_mfma_f32_16x16x32_bf16 v[126:129], v[134:137], v[150:153], v[126:129]
	v_mfma_f32_16x16x32_bf16 v[122:125], v[142:145], v[150:153], v[122:125]
	v_mfma_f32_16x16x32_bf16 v[110:113], v[134:137], v[158:161], v[110:113]
	v_mfma_f32_16x16x32_bf16 v[106:109], v[142:145], v[158:161], v[106:109]
	v_mfma_f32_16x16x32_bf16 v[94:97], v[134:137], v[166:169], v[94:97]
	v_mfma_f32_16x16x32_bf16 v[90:93], v[142:145], v[166:169], v[90:93]
	v_mfma_f32_16x16x32_bf16 v[78:81], v[134:137], v[174:177], v[78:81]
	v_mfma_f32_16x16x32_bf16 v[74:77], v[142:145], v[174:177], v[74:77]
	s_setprio 0
	s_barrier
	s_add_i32 s79, 0, 0x14000
	s_add_i32 s39, s39, s40
	v_add_u32_e32 v0, s79, v239
	s_add_u32 s98, s14, s50
	s_addc_u32 s99, s15, s51
	s_mov_b32 m0, s39
	ds_read_b128 v[178:181], v0
	ds_read_b128 v[182:185], v0 offset:1024
	ds_read_b128 v[210:213], v0 offset:2048
	ds_read_b128 v[226:229], v0 offset:3072
	global_load_lds_dwordx4 v202, s[14:15]
	s_add_i32 m0, s39, 0x2000
	s_nop 0
	global_load_lds_dwordx4 v204, s[14:15]
	s_barrier
	s_waitcnt lgkmcnt(0)
	s_setprio 1
	s_waitcnt lgkmcnt(0)
	v_mfma_f32_16x16x32_bf16 v[118:121], v[178:181], v[146:149], v[118:121]
	v_mfma_f32_16x16x32_bf16 v[114:117], v[210:213], v[146:149], v[114:117]
	v_mfma_f32_16x16x32_bf16 v[102:105], v[178:181], v[154:157], v[102:105]
	v_mfma_f32_16x16x32_bf16 v[98:101], v[210:213], v[154:157], v[98:101]
	v_mfma_f32_16x16x32_bf16 v[86:89], v[178:181], v[162:165], v[86:89]
	v_mfma_f32_16x16x32_bf16 v[82:85], v[210:213], v[162:165], v[82:85]
	v_mfma_f32_16x16x32_bf16 v[70:73], v[178:181], v[170:173], v[70:73]
	v_mfma_f32_16x16x32_bf16 v[66:69], v[210:213], v[170:173], v[66:69]
	v_mfma_f32_16x16x32_bf16 v[118:121], v[182:185], v[150:153], v[118:121]
	v_mfma_f32_16x16x32_bf16 v[114:117], v[226:229], v[150:153], v[114:117]
	v_mfma_f32_16x16x32_bf16 v[102:105], v[182:185], v[158:161], v[102:105]
	v_mfma_f32_16x16x32_bf16 v[98:101], v[226:229], v[158:161], v[98:101]
	v_mfma_f32_16x16x32_bf16 v[86:89], v[182:185], v[166:169], v[86:89]
	v_mfma_f32_16x16x32_bf16 v[82:85], v[226:229], v[166:169], v[82:85]
	v_mfma_f32_16x16x32_bf16 v[70:73], v[182:185], v[174:177], v[70:73]
	v_mfma_f32_16x16x32_bf16 v[66:69], v[226:229], v[174:177], v[66:69]
	s_setprio 0
	s_mov_b32 m0, s41
	s_add_u32 s100, s30, s50
	s_addc_u32 s101, s31, s51
	s_barrier
	ds_read_b128 v[146:149], v241 offset:16384
	ds_read_b128 v[150:153], v241 offset:17408
	ds_read_b128 v[154:157], v241 offset:18432
	ds_read_b128 v[158:161], v241 offset:19456
	ds_read_b128 v[162:165], v241 offset:20480
	ds_read_b128 v[166:169], v241 offset:21504
	ds_read_b128 v[170:173], v241 offset:22528
	ds_read_b128 v[174:177], v241 offset:23552
	global_load_lds_dwordx4 v202, s[30:31]
	s_mov_b32 m0, s42
	s_nop 0
	global_load_lds_dwordx4 v204, s[30:31]
	s_barrier
	s_waitcnt lgkmcnt(0)
	s_setprio 1
	s_waitcnt lgkmcnt(0)
	v_mfma_f32_16x16x32_bf16 v[62:65], v[130:133], v[146:149], v[62:65]
	v_mfma_f32_16x16x32_bf16 v[58:61], v[138:141], v[146:149], v[58:61]
	v_mfma_f32_16x16x32_bf16 v[46:49], v[130:133], v[154:157], v[46:49]
	v_mfma_f32_16x16x32_bf16 v[42:45], v[138:141], v[154:157], v[42:45]
	v_mfma_f32_16x16x32_bf16 v[30:33], v[130:133], v[162:165], v[30:33]
	v_mfma_f32_16x16x32_bf16 v[26:29], v[138:141], v[162:165], v[26:29]
	v_mfma_f32_16x16x32_bf16 v[14:17], v[130:133], v[170:173], v[14:17]
	v_mfma_f32_16x16x32_bf16 v[10:13], v[138:141], v[170:173], v[10:13]
	v_mfma_f32_16x16x32_bf16 v[62:65], v[134:137], v[150:153], v[62:65]
	v_mfma_f32_16x16x32_bf16 v[58:61], v[142:145], v[150:153], v[58:61]
	v_mfma_f32_16x16x32_bf16 v[46:49], v[134:137], v[158:161], v[46:49]
	v_mfma_f32_16x16x32_bf16 v[42:45], v[142:145], v[158:161], v[42:45]
	v_mfma_f32_16x16x32_bf16 v[30:33], v[134:137], v[166:169], v[30:33]
	v_mfma_f32_16x16x32_bf16 v[26:29], v[142:145], v[166:169], v[26:29]
	v_mfma_f32_16x16x32_bf16 v[14:17], v[134:137], v[174:177], v[14:17]
	v_mfma_f32_16x16x32_bf16 v[10:13], v[142:145], v[174:177], v[10:13]
	s_setprio 0
	s_barrier
	s_add_u32 s82, s14, 0x40000
	s_addc_u32 s83, s15, 0
	s_add_i32 s39, s79, s40
	s_mov_b32 m0, s39
	s_nop 0
	global_load_lds_dwordx4 v202, s[82:83]
	s_add_i32 m0, s39, 0x2000
	s_nop 0
	global_load_lds_dwordx4 v204, s[82:83]
	s_waitcnt vmcnt(6)
	s_barrier
; #define PG8_STAGE(bufoff, gbase, voff) do { _Pragma("unroll") for (int _i = 0; _i < 2; ++_i) \
;     __builtin_amdgcn_global_load_lds((const unsigned*)((const char*)(gbase) + (voff)[_i]), (LAS unsigned*)(lds + (bufoff) + ldsw + _i * 8192), 16, 0, 0); } while (0)
; #define PG8_LDA(dst, b, h) do { _Pragma("unroll") for (int m = 0; m < 4; ++m) _Pragma("unroll") for (int k = 0; k < 2; ++k) dst[m][k] = *(const LAS bf16x8*)(lds + PG8_SA(b, h) + aoff + m * 2048 + k * 1024); } while (0)
; #define PG8_LDB(dst, b, h) do { _Pragma("unroll") for (int n = 0; n < 2; ++n) _Pragma("unroll") for (int k = 0; k < 2; ++k) dst[n][k] = *(const LAS bf16x8*)(lds + PG8_SB(b, h) + boff + n * 2048 + k * 1024); } while (0)
; #define PG8_MMA(ai, bj, At, Bt) do { __builtin_amdgcn_s_setprio(1); _Pragma("unroll") for (int m = 0; m < 4; ++m) _Pragma("unroll") for (int n = 0; n < 2; ++n) _Pragma("unroll") for (int k = 0; k < 2; ++k) \
;     acc[ai][bj][m][n] = __builtin_amdgcn_mfma_f32_16x16x32_bf16(Bt[n][k], At[m][k], acc[ai][bj][m][n], 0, 0, 0); __builtin_amdgcn_s_setprio(0); } while (0)
; #define PG8_WAIT_V(n) asm volatile("s_waitcnt vmcnt(" #n ")" ::: "memory")
; #define PG8_WAIT_L(n) asm volatile("s_waitcnt lgkmcnt(" #n ")" ::: "memory")
; #define PG8_BAR __builtin_amdgcn_s_barrier()
; #define PG8_SCHED __builtin_amdgcn_sched_barrier(0)
; template <class Epi, class Sched>
; DI void gemm_phase(LAS unsigned char* lds, const int tid, const Gemm g, const Sched& S, const Epi& E) {
;     ...
;       PG8_WAIT_V(6); PG8_BAR; PG8_MMA(1, 1, At, B1); PG8_BAR;
;       PG8_LDB(B0, 1, 0); PG8_SCHED; PG8_LDA(At, 1, 0); PG8_STAGE(PG8_SA(0, 1), a2 + hstepA, voffA);
;       PG8_WAIT_L(8); PG8_BAR; PG8_WAIT_L(0); PG8_MMA(0, 0, At, B0); PG8_BAR; PG8_SCHED;
;       PG8_LDB(B1, 1, 1); PG8_STAGE(PG8_SB(1, 0), b3, voffB);
;       PG8_BAR; PG8_WAIT_L(0); PG8_MMA(0, 1, At, B1); PG8_BAR;
;       PG8_LDA(At, 1, 1); PG8_STAGE(PG8_SA(1, 0), a3, voffA);
;       PG8_BAR; PG8_WAIT_L(0); PG8_MMA(1, 0, At, B0); PG8_BAR; PG8_SCHED;
	s_setprio 1
	v_mfma_f32_16x16x32_bf16 v[54:57], v[178:181], v[146:149], v[54:57]
	v_mfma_f32_16x16x32_bf16 v[50:53], v[210:213], v[146:149], v[50:53]
	v_mfma_f32_16x16x32_bf16 v[38:41], v[178:181], v[154:157], v[38:41]
	v_mfma_f32_16x16x32_bf16 v[34:37], v[210:213], v[154:157], v[34:37]
	v_mfma_f32_16x16x32_bf16 v[22:25], v[178:181], v[162:165], v[22:25]
	v_mfma_f32_16x16x32_bf16 v[18:21], v[210:213], v[162:165], v[18:21]
	v_mfma_f32_16x16x32_bf16 v[6:9], v[178:181], v[170:173], v[6:9]
	v_mfma_f32_16x16x32_bf16 v[2:5], v[210:213], v[170:173], v[2:5]
	v_mfma_f32_16x16x32_bf16 v[54:57], v[182:185], v[150:153], v[54:57]
	v_mfma_f32_16x16x32_bf16 v[50:53], v[226:229], v[150:153], v[50:53]
	v_mfma_f32_16x16x32_bf16 v[38:41], v[182:185], v[158:161], v[38:41]
	v_mfma_f32_16x16x32_bf16 v[34:37], v[226:229], v[158:161], v[34:37]
	v_mfma_f32_16x16x32_bf16 v[22:25], v[182:185], v[166:169], v[22:25]
	v_mfma_f32_16x16x32_bf16 v[18:21], v[226:229], v[166:169], v[18:21]
	v_mfma_f32_16x16x32_bf16 v[6:9], v[182:185], v[174:177], v[6:9]
	v_mfma_f32_16x16x32_bf16 v[2:5], v[226:229], v[174:177], v[2:5]
	s_setprio 0
	s_add_i32 s39, 0, 0x18000
	v_add_u32_e32 v0, s39, v239
	s_barrier
	ds_read_b128 v[130:133], v0
	ds_read_b128 v[134:137], v0 offset:1024
	ds_read_b128 v[138:141], v0 offset:2048
	ds_read_b128 v[142:145], v0 offset:3072
	s_add_u32 s30, s30, 0x40000
	s_addc_u32 s31, s31, 0
	s_mov_b32 m0, s43
	ds_read_b128 v[146:149], v241 offset:32768
	ds_read_b128 v[150:153], v241 offset:33792
	ds_read_b128 v[154:157], v241 offset:34816
	ds_read_b128 v[158:161], v241 offset:35840
	ds_read_b128 v[162:165], v241 offset:36864
	ds_read_b128 v[166:169], v241 offset:37888
	ds_read_b128 v[170:173], v241 offset:38912
	ds_read_b128 v[174:177], v241 offset:39936
	global_load_lds_dwordx4 v202, s[30:31]
	s_mov_b32 m0, s44
	s_nop 0
	global_load_lds_dwordx4 v204, s[30:31]
	s_waitcnt lgkmcnt(8)
	s_barrier
	s_waitcnt lgkmcnt(0)
	s_setprio 1
	s_waitcnt lgkmcnt(0)
	v_mfma_f32_16x16x32_bf16 v[126:129], v[130:133], v[146:149], v[126:129]
	v_mfma_f32_16x16x32_bf16 v[122:125], v[138:141], v[146:149], v[122:125]
	v_mfma_f32_16x16x32_bf16 v[110:113], v[130:133], v[154:157], v[110:113]
	v_mfma_f32_16x16x32_bf16 v[106:109], v[138:141], v[154:157], v[106:109]
	v_mfma_f32_16x16x32_bf16 v[94:97], v[130:133], v[162:165], v[94:97]
	v_mfma_f32_16x16x32_bf16 v[90:93], v[138:141], v[162:165], v[90:93]
	v_mfma_f32_16x16x32_bf16 v[78:81], v[130:133], v[170:173], v[78:81]
	v_mfma_f32_16x16x32_bf16 v[74:77], v[138:141], v[170:173], v[74:77]
	v_mfma_f32_16x16x32_bf16 v[126:129], v[134:137], v[150:153], v[126:129]
	v_mfma_f32_16x16x32_bf16 v[122:125], v[142:145], v[150:153], v[122:125]
	v_mfma_f32_16x16x32_bf16 v[110:113], v[134:137], v[158:161], v[110:113]
	v_mfma_f32_16x16x32_bf16 v[106:109], v[142:145], v[158:161], v[106:109]
	v_mfma_f32_16x16x32_bf16 v[94:97], v[134:137], v[166:169], v[94:97]
	v_mfma_f32_16x16x32_bf16 v[90:93], v[142:145], v[166:169], v[90:93]
	v_mfma_f32_16x16x32_bf16 v[78:81], v[134:137], v[174:177], v[78:81]
	v_mfma_f32_16x16x32_bf16 v[74:77], v[142:145], v[174:177], v[74:77]
	s_setprio 0
	s_barrier
	s_add_i32 s30, 0, 0x1c000
	s_add_i32 s31, s39, s40
	v_add_u32_e32 v0, s30, v239
	s_mov_b32 m0, s31
	ds_read_b128 v[178:181], v0
	ds_read_b128 v[182:185], v0 offset:1024
	ds_read_b128 v[210:213], v0 offset:2048
	ds_read_b128 v[226:229], v0 offset:3072
	global_load_lds_dwordx4 v202, s[98:99]
	s_add_i32 m0, s31, 0x2000
	s_nop 0
	global_load_lds_dwordx4 v204, s[98:99]
	s_barrier
	s_waitcnt lgkmcnt(0)
	s_setprio 1
	s_waitcnt lgkmcnt(0)
	v_mfma_f32_16x16x32_bf16 v[118:121], v[178:181], v[146:149], v[118:121]
	v_mfma_f32_16x16x32_bf16 v[114:117], v[210:213], v[146:149], v[114:117]
	v_mfma_f32_16x16x32_bf16 v[102:105], v[178:181], v[154:157], v[102:105]
	v_mfma_f32_16x16x32_bf16 v[98:101], v[210:213], v[154:157], v[98:101]
	v_mfma_f32_16x16x32_bf16 v[86:89], v[178:181], v[162:165], v[86:89]
	v_mfma_f32_16x16x32_bf16 v[82:85], v[210:213], v[162:165], v[82:85]
	v_mfma_f32_16x16x32_bf16 v[70:73], v[178:181], v[170:173], v[70:73]
	v_mfma_f32_16x16x32_bf16 v[66:69], v[210:213], v[170:173], v[66:69]
	v_mfma_f32_16x16x32_bf16 v[118:121], v[182:185], v[150:153], v[118:121]
	v_mfma_f32_16x16x32_bf16 v[114:117], v[226:229], v[150:153], v[114:117]
	v_mfma_f32_16x16x32_bf16 v[102:105], v[182:185], v[158:161], v[102:105]
	v_mfma_f32_16x16x32_bf16 v[98:101], v[226:229], v[158:161], v[98:101]
	v_mfma_f32_16x16x32_bf16 v[86:89], v[182:185], v[166:169], v[86:89]
	v_mfma_f32_16x16x32_bf16 v[82:85], v[226:229], v[166:169], v[82:85]
	v_mfma_f32_16x16x32_bf16 v[70:73], v[182:185], v[174:177], v[70:73]
	v_mfma_f32_16x16x32_bf16 v[66:69], v[226:229], v[174:177], v[66:69]
	s_setprio 0
	s_mov_b32 m0, s66
	s_barrier
	ds_read_b128 v[146:149], v241 offset:49152
	ds_read_b128 v[150:153], v241 offset:50176
	ds_read_b128 v[154:157], v241 offset:51200
	ds_read_b128 v[158:161], v241 offset:52224
	ds_read_b128 v[162:165], v241 offset:53248
	ds_read_b128 v[166:169], v241 offset:54272
	ds_read_b128 v[170:173], v241 offset:55296
	ds_read_b128 v[174:177], v241 offset:56320
	global_load_lds_dwordx4 v202, s[100:101]
	s_mov_b32 m0, s67
	s_nop 0
	global_load_lds_dwordx4 v204, s[100:101]
	s_barrier
; #define GAS __attribute__((address_space(1)))
; #define PG8_MMA(ai, bj, At, Bt) do { __builtin_amdgcn_s_setprio(1); _Pragma("unroll") for (int m = 0; m < 4; ++m) _Pragma("unroll") for (int n = 0; n < 2; ++n) _Pragma("unroll") for (int k = 0; k < 2; ++k) \
;     acc[ai][bj][m][n] = __builtin_amdgcn_mfma_f32_16x16x32_bf16(Bt[n][k], At[m][k], acc[ai][bj][m][n], 0, 0, 0); __builtin_amdgcn_s_setprio(0); } while (0)
; #define PG8_WAIT_V(n) asm volatile("s_waitcnt vmcnt(" #n ")" ::: "memory")
; #define PG8_BAR __builtin_amdgcn_s_barrier()
; template <class Epi, class Sched>
; DI void gemm_phase(LAS unsigned char* lds, const int tid, const Gemm g, const Sched& S, const Epi& E) {
;     ...
;       PG8_WAIT_V(6); PG8_BAR; PG8_MMA(1, 1, At, B1); PG8_BAR;
;     }
;     { int z_e = 0; asm volatile("" : "+v"(z_e)); const int lane_e = __builtin_amdgcn_mbcnt_hi(~0u, __builtin_amdgcn_mbcnt_lo(~0u, (unsigned)z_e));
;   DI void operator()(const AccT& acc, const Unit& u, int wr, int wc, int fr, int fq) const {
;     ...
;     } else if (wc == 2) {
;       const char* base = (const char*)(KR + (size_t)rowb * 32);
;       const char* sb = (const char*)(ssq_kr + rowb);
;       const unsigned o0 = (rl0 * 32u + fq * 8) * 4u, ro0 = (rl0 * 16u + fq * 4) * 4u;
;       const char* cb = (const char*)(cosM + posb * 16), *sbp = (const char*)(sinM + posb * 16);
;       f32x4 gv[2];
; #pragma unroll
;       for (int n = 0; n < 2; ++n) gv[n] = ld4p((const char*)(g_mk + 64) + n * 16, fq * 32u);
; #pragma unroll
;       for (int aim = 0; aim < 4; ++aim) { const int ai = aim >> 1, m0 = (aim & 1) * 2;
;         f32x2 cc[4][2], sn[4][2];
; #pragma unroll
;         for (int m = m0; m < m0 + 2; ++m)
; #pragma unroll
;           for (int n = 0; n < 2; ++n) { cc[m][n] = ld2p(cb + ((ai * 128 + m * 16) * 16 + n * 2) * 4, ro0); sn[m][n] = ld2p(sbp + ((ai * 128 + m * 16) * 16 + n * 2) * 4, ro0); }
; #pragma unroll
;         for (int m = m0; m < m0 + 2; ++m) {
;           const float ss = lane_ssq(acc, ai, m, 1.f);
;           if (fq == 0) *(GAS float*)((char*)sb + (size_t)(ai * 128 + m * 16) * 4 + rl0 * 4u) = ss;
	s_waitcnt lgkmcnt(0)
	s_setprio 1
	s_waitcnt lgkmcnt(0)
	v_mfma_f32_16x16x32_bf16 v[62:65], v[130:133], v[146:149], v[62:65]
	v_mfma_f32_16x16x32_bf16 v[58:61], v[138:141], v[146:149], v[58:61]
	v_mfma_f32_16x16x32_bf16 v[46:49], v[130:133], v[154:157], v[46:49]
	v_mfma_f32_16x16x32_bf16 v[42:45], v[138:141], v[154:157], v[42:45]
	v_mfma_f32_16x16x32_bf16 v[30:33], v[130:133], v[162:165], v[30:33]
	v_mfma_f32_16x16x32_bf16 v[26:29], v[138:141], v[162:165], v[26:29]
	v_mfma_f32_16x16x32_bf16 v[14:17], v[130:133], v[170:173], v[14:17]
	v_mfma_f32_16x16x32_bf16 v[10:13], v[138:141], v[170:173], v[10:13]
	v_mfma_f32_16x16x32_bf16 v[62:65], v[134:137], v[150:153], v[62:65]
	v_mfma_f32_16x16x32_bf16 v[58:61], v[142:145], v[150:153], v[58:61]
	v_mfma_f32_16x16x32_bf16 v[46:49], v[134:137], v[158:161], v[46:49]
	v_mfma_f32_16x16x32_bf16 v[42:45], v[142:145], v[158:161], v[42:45]
	v_mfma_f32_16x16x32_bf16 v[30:33], v[134:137], v[166:169], v[30:33]
	v_mfma_f32_16x16x32_bf16 v[26:29], v[142:145], v[166:169], v[26:29]
	v_mfma_f32_16x16x32_bf16 v[14:17], v[134:137], v[174:177], v[14:17]
	v_mfma_f32_16x16x32_bf16 v[10:13], v[142:145], v[174:177], v[10:13]
	s_setprio 0
	s_barrier
	s_add_u32 s14, s14, 0x40080
	s_addc_u32 s15, s15, 0
	s_add_i32 s30, s30, s40
	s_mov_b32 m0, s30
	s_nop 0
	global_load_lds_dwordx4 v202, s[14:15]
	s_add_i32 m0, s30, 0x2000
	s_nop 0
	global_load_lds_dwordx4 v204, s[14:15]
	s_waitcnt vmcnt(6)
	s_barrier
	s_setprio 1
	v_mfma_f32_16x16x32_bf16 v[54:57], v[178:181], v[146:149], v[54:57]
	v_mfma_f32_16x16x32_bf16 v[50:53], v[210:213], v[146:149], v[50:53]
	v_mfma_f32_16x16x32_bf16 v[38:41], v[178:181], v[154:157], v[38:41]
	v_mfma_f32_16x16x32_bf16 v[34:37], v[210:213], v[154:157], v[34:37]
	v_mfma_f32_16x16x32_bf16 v[22:25], v[178:181], v[162:165], v[22:25]
	v_mfma_f32_16x16x32_bf16 v[18:21], v[210:213], v[162:165], v[18:21]
	v_mfma_f32_16x16x32_bf16 v[6:9], v[178:181], v[170:173], v[6:9]
	v_mfma_f32_16x16x32_bf16 v[2:5], v[210:213], v[170:173], v[2:5]
	v_mfma_f32_16x16x32_bf16 v[54:57], v[182:185], v[150:153], v[54:57]
	v_mfma_f32_16x16x32_bf16 v[50:53], v[226:229], v[150:153], v[50:53]
	v_mfma_f32_16x16x32_bf16 v[38:41], v[182:185], v[158:161], v[38:41]
	v_mfma_f32_16x16x32_bf16 v[34:37], v[226:229], v[158:161], v[34:37]
	v_mfma_f32_16x16x32_bf16 v[22:25], v[182:185], v[166:169], v[22:25]
	v_mfma_f32_16x16x32_bf16 v[18:21], v[226:229], v[166:169], v[18:21]
	v_mfma_f32_16x16x32_bf16 v[6:9], v[182:185], v[174:177], v[6:9]
	v_mfma_f32_16x16x32_bf16 v[2:5], v[226:229], v[174:177], v[2:5]
	s_setprio 0
	s_add_i32 s38, s38, 2
	s_add_u32 s34, s34, 0x100
	s_addc_u32 s35, s35, 0
	s_add_u32 s0, s0, 0x100
	s_addc_u32 s1, s1, 0
	s_cmp_gt_u32 s38, 13
	s_barrier
	s_cbranch_scc0 .LBB0_467
	v_mov_b32_e32 v0, v1
	s_lshl_b32 s30, s8, 8
	v_mbcnt_lo_u32_b32 v0, -1, v0
	s_cmp_eq_u32 s6, 0
	v_mbcnt_hi_u32_b32 v243, -1, v0
	s_cselect_b64 s[0:1], -1, 0
	v_and_or_b32 v244, v243, 15, s63
	s_and_b64 vcc, exec, s[0:1]
	s_cbranch_vccnz .LBB0_496
	s_cmp_eq_u32 s6, 3
	s_cselect_b64 s[0:1], -1, 0
	s_and_b64 s[0:1], s[0:1], s[12:13]
	s_andn2_b64 vcc, exec, s[0:1]
	s_mov_b64 s[0:1], -1
	s_cbranch_vccz .LBB0_509
	s_cmpk_lt_i32 s8, 0x80
	s_cselect_b64 s[8:9], -1, 0
	s_and_b32 s23, s30, 0x700
	s_cmp_eq_u32 s6, 1
	s_cselect_b64 s[38:39], -1, 0
	v_ashrrev_i32_e32 v162, 4, v243
	s_and_b64 vcc, exec, s[38:39]
	s_cbranch_vccnz .LBB0_497
	s_cmp_lg_u32 s6, 2
	s_cselect_b64 s[0:1], -1, 0
	s_cmp_eq_u32 s6, 2
	s_cselect_b64 s[6:7], -1, 0
	s_and_b64 s[6:7], s[6:7], s[12:13]
	s_andn2_b64 vcc, exec, s[6:7]
	s_mov_b64 s[38:39], -1
	s_cbranch_vccz .LBB0_495
	s_mov_b64 s[6:7], -1
	s_and_b64 vcc, exec, s[0:1]
	s_cbranch_vccz .LBB0_492
	s_andn2_b64 vcc, exec, s[16:17]
	s_cbranch_vccnz .LBB0_491
	s_mov_b32 s31, s97
	s_lshl_b64 s[0:1], s[30:31], 2
	s_add_u32 s14, s61, s0
	s_addc_u32 s15, s62, s1
	s_lshl_b32 s6, s23, 6
	v_cmp_lt_i32_e32 vcc, v231, v215
	s_add_u32 s0, s95, s6
	v_readlane_b32 s1, v255, 6
	v_cndmask_b32_e32 v138, v189, v231, vcc
	v_cmp_lt_i32_e32 vcc, v233, v215
	v_and_b32_e32 v0, -16, v243
	s_addc_u32 s1, s1, 0
	v_lshlrev_b32_e32 v164, 2, v138
	v_cndmask_b32_e32 v138, v189, v233, vcc
	v_lshlrev_b32_e32 v156, 5, v162
	v_lshl_add_u32 v0, v244, 6, v0
	s_add_u32 s6, s55, s6
	v_lshlrev_b32_e32 v163, 2, v138
	v_lshlrev_b32_e32 v138, 2, v244
	v_mov_b32_e32 v139, v1
	global_load_dwordx4 v[130:133], v156, s[64:65] offset:272
	global_load_dwordx4 v[134:137], v156, s[64:65] offset:256
	s_addc_u32 s7, s56, 0
	v_lshl_add_u64 v[154:155], s[14:15], 0, v[138:139]
	global_load_dwordx4 v[150:153], v0, s[0:1]
	global_load_dwordx4 v[146:149], v0, s[6:7]
	global_load_dwordx4 v[138:141], v0, s[0:1] offset:1024
	global_load_dwordx4 v[142:145], v0, s[6:7] offset:1024
	v_mul_f32_e32 v157, v127, v127
	v_fmac_f32_e32 v157, v126, v126
	v_fmac_f32_e32 v157, v128, v128
	v_fmac_f32_e32 v157, v129, v129
	v_fmac_f32_e32 v157, v122, v122
	v_fmac_f32_e32 v157, v123, v123
	v_fmac_f32_e32 v157, v124, v124
	v_fmac_f32_e32 v157, v125, v125
	v_fmac_f32_e32 v157, v118, v118
	v_fmac_f32_e32 v157, v119, v119
	v_fmac_f32_e32 v157, v120, v120
	v_fmac_f32_e32 v157, v121, v121
	v_fmac_f32_e32 v157, v114, v114
	v_fmac_f32_e32 v157, v115, v115
	v_fmac_f32_e32 v157, v116, v116
	v_fmac_f32_e32 v157, v117, v117
	ds_bpermute_b32 v158, v164, v157
	v_cmp_gt_u32_e32 vcc, 16, v243
	s_waitcnt lgkmcnt(0)
	v_add_f32_e32 v157, v157, v158
	ds_bpermute_b32 v158, v163, v157
	s_and_saveexec_b64 s[14:15], vcc
	s_cbranch_execz .LBB0_476
	s_waitcnt lgkmcnt(0)
	v_add_f32_e32 v157, v157, v158
	global_store_dword v[154:155], v157, off

; #define PG8_STAGE(bufoff, gbase, voff) do { _Pragma("unroll") for (int _i = 0; _i < 2; ++_i) \
;     __builtin_amdgcn_global_load_lds((const unsigned*)((const char*)(gbase) + (voff)[_i]), (LAS unsigned*)(lds + (bufoff) + ldsw + _i * 8192), 16, 0, 0); } while (0)
; #define PG8_LDA(dst, b, h) do { _Pragma("unroll") for (int m = 0; m < 4; ++m) _Pragma("unroll") for (int k = 0; k < 2; ++k) dst[m][k] = *(const LAS bf16x8*)(lds + PG8_SA(b, h) + aoff + m * 2048 + k * 1024); } while (0)
; #define PG8_LDB(dst, b, h) do { _Pragma("unroll") for (int n = 0; n < 2; ++n) _Pragma("unroll") for (int k = 0; k < 2; ++k) dst[n][k] = *(const LAS bf16x8*)(lds + PG8_SB(b, h) + boff + n * 2048 + k * 1024); } while (0)
; #define PG8_MMA(ai, bj, At, Bt) do { __builtin_amdgcn_s_setprio(1); _Pragma("unroll") for (int m = 0; m < 4; ++m) _Pragma("unroll") for (int n = 0; n < 2; ++n) _Pragma("unroll") for (int k = 0; k < 2; ++k) \
;     acc[ai][bj][m][n] = __builtin_amdgcn_mfma_f32_16x16x32_bf16(Bt[n][k], At[m][k], acc[ai][bj][m][n], 0, 0, 0); __builtin_amdgcn_s_setprio(0); } while (0)
; #define PG8_WAIT_L(n) asm volatile("s_waitcnt lgkmcnt(" #n ")" ::: "memory")
; #define PG8_BAR __builtin_amdgcn_s_barrier()
; #define PG8_SCHED __builtin_amdgcn_sched_barrier(0)
; template <class Epi, class Sched>
; DI void gemm_phase(LAS unsigned char* lds, const int tid, const Gemm g, const Sched& S, const Epi& E) {
;     ...
;       const bool last = (t == nt - 2);
;       const char* a1 = cA + (size_t)(t + 1) * kstep;
;       const char* a2 = last ? nA : cA + (size_t)(t + 2) * kstep; const char* b2 = last ? nB : cB + (size_t)(t + 2) * kstep;
;       const char* a3 = a2 + kstep; const char* b3 = b2 + kstep;
;       PG8_LDB(B0, 0, 0); PG8_SCHED; PG8_LDA(At, 0, 0); PG8_STAGE(PG8_SA(1, 1), a1 + hstepA, voffA);
;       PG8_WAIT_L(8); PG8_BAR; PG8_WAIT_L(0); PG8_MMA(0, 0, At, B0); PG8_BAR; PG8_SCHED;
;       PG8_LDB(B1, 0, 1); PG8_STAGE(PG8_SB(0, 0), b2, voffB);
;       PG8_BAR; PG8_WAIT_L(0); PG8_MMA(0, 1, At, B1); PG8_BAR;
;       PG8_LDA(At, 0, 1); PG8_STAGE(PG8_SA(0, 0), a2, voffA);
;       PG8_BAR; PG8_WAIT_L(0); PG8_MMA(1, 0, At, B0); PG8_BAR; PG8_SCHED;
.LBB0_589:
	s_add_i32 s30, s12, 2
	s_add_u32 s0, s10, 0x100
	s_addc_u32 s1, s11, 0
	s_add_i32 s31, 0, 0x10000
	v_add_u32_e32 v0, s31, v206
	ds_read_b128 v[130:133], v0
	ds_read_b128 v[134:137], v0 offset:1024
	ds_read_b128 v[138:141], v0 offset:2048
	ds_read_b128 v[142:145], v0 offset:3072
	s_cmp_eq_u32 s2, s12
	s_cselect_b32 s12, s24, s0
	s_cselect_b32 s13, s25, s1
	s_cselect_b32 s15, s9, s29
	s_cselect_b32 s14, s23, s28
	s_add_i32 m0, s59, 0xc000
	ds_read_b128 v[146:149], v207
	ds_read_b128 v[150:153], v207 offset:1024
	ds_read_b128 v[154:157], v207 offset:2048
	ds_read_b128 v[158:161], v207 offset:3072
	ds_read_b128 v[162:165], v207 offset:4096
	ds_read_b128 v[178:181], v207 offset:5120
	ds_read_b128 v[182:185], v207 offset:6144
	ds_read_b128 v[202:205], v207 offset:7168
	global_load_lds_dwordx4 v176, s[10:11]
	s_add_i32 m0, s59, 0xe000
	s_nop 0
	global_load_lds_dwordx4 v174, s[10:11]
	s_waitcnt lgkmcnt(8)
	s_barrier
	s_waitcnt lgkmcnt(0)
	s_setprio 1
	s_waitcnt lgkmcnt(0)
	v_mfma_f32_16x16x32_bf16 v[126:129], v[130:133], v[146:149], v[126:129]
	v_mfma_f32_16x16x32_bf16 v[122:125], v[138:141], v[146:149], v[122:125]
	v_mfma_f32_16x16x32_bf16 v[110:113], v[130:133], v[154:157], v[110:113]
	v_mfma_f32_16x16x32_bf16 v[106:109], v[138:141], v[154:157], v[106:109]
	v_mfma_f32_16x16x32_bf16 v[94:97], v[130:133], v[162:165], v[94:97]
	v_mfma_f32_16x16x32_bf16 v[90:93], v[138:141], v[162:165], v[90:93]
	v_mfma_f32_16x16x32_bf16 v[78:81], v[130:133], v[182:185], v[78:81]
	v_mfma_f32_16x16x32_bf16 v[74:77], v[138:141], v[182:185], v[74:77]
	v_mfma_f32_16x16x32_bf16 v[126:129], v[134:137], v[150:153], v[126:129]
	v_mfma_f32_16x16x32_bf16 v[122:125], v[142:145], v[150:153], v[122:125]
	v_mfma_f32_16x16x32_bf16 v[110:113], v[134:137], v[158:161], v[110:113]
	v_mfma_f32_16x16x32_bf16 v[106:109], v[142:145], v[158:161], v[106:109]
	v_mfma_f32_16x16x32_bf16 v[94:97], v[134:137], v[178:181], v[94:97]
	v_mfma_f32_16x16x32_bf16 v[90:93], v[142:145], v[178:181], v[90:93]
	v_mfma_f32_16x16x32_bf16 v[78:81], v[134:137], v[202:205], v[78:81]
	v_mfma_f32_16x16x32_bf16 v[74:77], v[142:145], v[202:205], v[74:77]
	s_setprio 0
	s_barrier
	s_add_i32 s34, 0, 0x14000
	s_add_i32 s10, s31, s53
	v_add_u32_e32 v0, s34, v206
	s_add_u32 s98, s14, s50
	s_addc_u32 s99, s15, s51
	s_mov_b32 m0, s10
	ds_read_b128 v[208:211], v0
	ds_read_b128 v[226:229], v0 offset:1024
	ds_read_b128 v[238:241], v0 offset:2048
	ds_read_b128 v[242:245], v0 offset:3072
	global_load_lds_dwordx4 v168, s[14:15]
	s_add_i32 m0, s10, 0x2000
	s_nop 0
	global_load_lds_dwordx4 v172, s[14:15]
	s_barrier
	s_waitcnt lgkmcnt(0)
	s_setprio 1
	s_waitcnt lgkmcnt(0)
	v_mfma_f32_16x16x32_bf16 v[118:121], v[208:211], v[146:149], v[118:121]
	v_mfma_f32_16x16x32_bf16 v[114:117], v[238:241], v[146:149], v[114:117]
	v_mfma_f32_16x16x32_bf16 v[102:105], v[208:211], v[154:157], v[102:105]
	v_mfma_f32_16x16x32_bf16 v[98:101], v[238:241], v[154:157], v[98:101]
	v_mfma_f32_16x16x32_bf16 v[86:89], v[208:211], v[162:165], v[86:89]
	v_mfma_f32_16x16x32_bf16 v[82:85], v[238:241], v[162:165], v[82:85]
	v_mfma_f32_16x16x32_bf16 v[70:73], v[208:211], v[182:185], v[70:73]
	v_mfma_f32_16x16x32_bf16 v[66:69], v[238:241], v[182:185], v[66:69]
	v_mfma_f32_16x16x32_bf16 v[118:121], v[226:229], v[150:153], v[118:121]
	v_mfma_f32_16x16x32_bf16 v[114:117], v[242:245], v[150:153], v[114:117]
	v_mfma_f32_16x16x32_bf16 v[102:105], v[226:229], v[158:161], v[102:105]
	v_mfma_f32_16x16x32_bf16 v[98:101], v[242:245], v[158:161], v[98:101]
	v_mfma_f32_16x16x32_bf16 v[86:89], v[226:229], v[178:181], v[86:89]
	v_mfma_f32_16x16x32_bf16 v[82:85], v[242:245], v[178:181], v[82:85]
	v_mfma_f32_16x16x32_bf16 v[70:73], v[226:229], v[202:205], v[70:73]
	v_mfma_f32_16x16x32_bf16 v[66:69], v[242:245], v[202:205], v[66:69]
	s_setprio 0
	s_mov_b32 m0, s59
	s_add_u32 s100, s12, s50
	s_addc_u32 s101, s13, s51
	s_barrier
	ds_read_b128 v[146:149], v207 offset:16384
	ds_read_b128 v[150:153], v207 offset:17408
	ds_read_b128 v[154:157], v207 offset:18432
	ds_read_b128 v[158:161], v207 offset:19456
	ds_read_b128 v[162:165], v207 offset:20480
	ds_read_b128 v[178:181], v207 offset:21504
	ds_read_b128 v[182:185], v207 offset:22528
	ds_read_b128 v[202:205], v207 offset:23552
	global_load_lds_dwordx4 v166, s[12:13]
	s_mov_b32 m0, s60
	s_nop 0
	global_load_lds_dwordx4 v170, s[12:13]
	s_barrier
	s_waitcnt lgkmcnt(0)
	s_setprio 1
	s_waitcnt lgkmcnt(0)
	v_mfma_f32_16x16x32_bf16 v[62:65], v[130:133], v[146:149], v[62:65]
	v_mfma_f32_16x16x32_bf16 v[58:61], v[138:141], v[146:149], v[58:61]
	v_mfma_f32_16x16x32_bf16 v[46:49], v[130:133], v[154:157], v[46:49]
	v_mfma_f32_16x16x32_bf16 v[42:45], v[138:141], v[154:157], v[42:45]
	v_mfma_f32_16x16x32_bf16 v[30:33], v[130:133], v[162:165], v[30:33]
	v_mfma_f32_16x16x32_bf16 v[26:29], v[138:141], v[162:165], v[26:29]
	v_mfma_f32_16x16x32_bf16 v[14:17], v[130:133], v[182:185], v[14:17]
	v_mfma_f32_16x16x32_bf16 v[10:13], v[138:141], v[182:185], v[10:13]
	v_mfma_f32_16x16x32_bf16 v[62:65], v[134:137], v[150:153], v[62:65]
	v_mfma_f32_16x16x32_bf16 v[58:61], v[142:145], v[150:153], v[58:61]
	v_mfma_f32_16x16x32_bf16 v[46:49], v[134:137], v[158:161], v[46:49]
	v_mfma_f32_16x16x32_bf16 v[42:45], v[142:145], v[158:161], v[42:45]
	v_mfma_f32_16x16x32_bf16 v[30:33], v[134:137], v[178:181], v[30:33]
	v_mfma_f32_16x16x32_bf16 v[26:29], v[142:145], v[178:181], v[26:29]
	v_mfma_f32_16x16x32_bf16 v[14:17], v[134:137], v[202:205], v[14:17]
	v_mfma_f32_16x16x32_bf16 v[10:13], v[142:145], v[202:205], v[10:13]
	s_setprio 0
	s_barrier
; #define PG8_STAGE(bufoff, gbase, voff) do { _Pragma("unroll") for (int _i = 0; _i < 2; ++_i) \
;     __builtin_amdgcn_global_load_lds((const unsigned*)((const char*)(gbase) + (voff)[_i]), (LAS unsigned*)(lds + (bufoff) + ldsw + _i * 8192), 16, 0, 0); } while (0)
; #define PG8_LDA(dst, b, h) do { _Pragma("unroll") for (int m = 0; m < 4; ++m) _Pragma("unroll") for (int k = 0; k < 2; ++k) dst[m][k] = *(const LAS bf16x8*)(lds + PG8_SA(b, h) + aoff + m * 2048 + k * 1024); } while (0)
; #define PG8_LDB(dst, b, h) do { _Pragma("unroll") for (int n = 0; n < 2; ++n) _Pragma("unroll") for (int k = 0; k < 2; ++k) dst[n][k] = *(const LAS bf16x8*)(lds + PG8_SB(b, h) + boff + n * 2048 + k * 1024); } while (0)
; #define PG8_MMA(ai, bj, At, Bt) do { __builtin_amdgcn_s_setprio(1); _Pragma("unroll") for (int m = 0; m < 4; ++m) _Pragma("unroll") for (int n = 0; n < 2; ++n) _Pragma("unroll") for (int k = 0; k < 2; ++k) \
;     acc[ai][bj][m][n] = __builtin_amdgcn_mfma_f32_16x16x32_bf16(Bt[n][k], At[m][k], acc[ai][bj][m][n], 0, 0, 0); __builtin_amdgcn_s_setprio(0); } while (0)
; #define PG8_WAIT_V(n) asm volatile("s_waitcnt vmcnt(" #n ")" ::: "memory")
; #define PG8_WAIT_L(n) asm volatile("s_waitcnt lgkmcnt(" #n ")" ::: "memory")
; #define PG8_BAR __builtin_amdgcn_s_barrier()
; #define PG8_SCHED __builtin_amdgcn_sched_barrier(0)
; template <class Epi, class Sched>
; DI void gemm_phase(LAS unsigned char* lds, const int tid, const Gemm g, const Sched& S, const Epi& E) {
;     ...
;       PG8_BAR; PG8_WAIT_L(0); PG8_MMA(1, 0, At, B0); PG8_BAR; PG8_SCHED;
;       PG8_STAGE(PG8_SB(0, 1), b2 + hstepB, voffB);
;       PG8_WAIT_V(6); PG8_BAR; PG8_MMA(1, 1, At, B1); PG8_BAR;
;       PG8_LDB(B0, 1, 0); PG8_SCHED; PG8_LDA(At, 1, 0); PG8_STAGE(PG8_SA(0, 1), a2 + hstepA, voffA);
;       PG8_WAIT_L(8); PG8_BAR; PG8_WAIT_L(0); PG8_MMA(0, 0, At, B0); PG8_BAR; PG8_SCHED;
;       PG8_LDB(B1, 1, 1); PG8_STAGE(PG8_SB(1, 0), b3, voffB);
;       PG8_BAR; PG8_WAIT_L(0); PG8_MMA(0, 1, At, B1); PG8_BAR;
;       PG8_LDA(At, 1, 1); PG8_STAGE(PG8_SA(1, 0), a3, voffA);
;       PG8_BAR; PG8_WAIT_L(0); PG8_MMA(1, 0, At, B0); PG8_BAR; PG8_SCHED;
	s_add_u32 s10, s14, s52
	s_addc_u32 s11, s15, 0
	s_add_i32 s14, s34, s53
	v_lshl_add_u64 v[216:217], s[10:11], 0, v[168:169]
	s_mov_b32 m0, s14
	v_lshl_add_u64 v[218:219], s[10:11], 0, v[172:173]
	global_load_lds_dwordx4 v[216:217], off
	s_add_i32 m0, s14, 0x2000
	s_nop 0
	global_load_lds_dwordx4 v[218:219], off
	s_waitcnt vmcnt(6)
	s_barrier
	s_setprio 1
	v_mfma_f32_16x16x32_bf16 v[54:57], v[208:211], v[146:149], v[54:57]
	v_mfma_f32_16x16x32_bf16 v[50:53], v[238:241], v[146:149], v[50:53]
	v_mfma_f32_16x16x32_bf16 v[38:41], v[208:211], v[154:157], v[38:41]
	v_mfma_f32_16x16x32_bf16 v[34:37], v[238:241], v[154:157], v[34:37]
	v_mfma_f32_16x16x32_bf16 v[22:25], v[208:211], v[162:165], v[22:25]
	v_mfma_f32_16x16x32_bf16 v[18:21], v[238:241], v[162:165], v[18:21]
	v_mfma_f32_16x16x32_bf16 v[6:9], v[208:211], v[182:185], v[6:9]
	v_mfma_f32_16x16x32_bf16 v[2:5], v[238:241], v[182:185], v[2:5]
	v_mfma_f32_16x16x32_bf16 v[54:57], v[226:229], v[150:153], v[54:57]
	v_mfma_f32_16x16x32_bf16 v[50:53], v[242:245], v[150:153], v[50:53]
	v_mfma_f32_16x16x32_bf16 v[38:41], v[226:229], v[158:161], v[38:41]
	v_mfma_f32_16x16x32_bf16 v[34:37], v[242:245], v[158:161], v[34:37]
	v_mfma_f32_16x16x32_bf16 v[22:25], v[226:229], v[178:181], v[22:25]
	v_mfma_f32_16x16x32_bf16 v[18:21], v[242:245], v[178:181], v[18:21]
	v_mfma_f32_16x16x32_bf16 v[6:9], v[226:229], v[202:205], v[6:9]
	v_mfma_f32_16x16x32_bf16 v[2:5], v[242:245], v[202:205], v[2:5]
	s_setprio 0
	s_add_i32 s14, 0, 0x18000
	v_add_u32_e32 v0, s14, v206
	s_barrier
	ds_read_b128 v[130:133], v0
	ds_read_b128 v[134:137], v0 offset:1024
	ds_read_b128 v[138:141], v0 offset:2048
	ds_read_b128 v[142:145], v0 offset:3072
	s_add_u32 s10, s12, 0x18000
	s_addc_u32 s11, s13, 0
	s_mov_b32 m0, s61
	ds_read_b128 v[146:149], v207 offset:32768
	ds_read_b128 v[150:153], v207 offset:33792
	ds_read_b128 v[154:157], v207 offset:34816
	ds_read_b128 v[158:161], v207 offset:35840
	ds_read_b128 v[162:165], v207 offset:36864
	ds_read_b128 v[178:181], v207 offset:37888
	ds_read_b128 v[182:185], v207 offset:38912
	ds_read_b128 v[202:205], v207 offset:39936
	global_load_lds_dwordx4 v166, s[10:11]
	s_mov_b32 m0, s62
	s_nop 0
	global_load_lds_dwordx4 v170, s[10:11]
	s_waitcnt lgkmcnt(8)
	s_barrier
	s_waitcnt lgkmcnt(0)
	s_setprio 1
	s_waitcnt lgkmcnt(0)
	v_mfma_f32_16x16x32_bf16 v[126:129], v[130:133], v[146:149], v[126:129]
	v_mfma_f32_16x16x32_bf16 v[122:125], v[138:141], v[146:149], v[122:125]
	v_mfma_f32_16x16x32_bf16 v[110:113], v[130:133], v[154:157], v[110:113]
	v_mfma_f32_16x16x32_bf16 v[106:109], v[138:141], v[154:157], v[106:109]
	v_mfma_f32_16x16x32_bf16 v[94:97], v[130:133], v[162:165], v[94:97]
	v_mfma_f32_16x16x32_bf16 v[90:93], v[138:141], v[162:165], v[90:93]
	v_mfma_f32_16x16x32_bf16 v[78:81], v[130:133], v[182:185], v[78:81]
	v_mfma_f32_16x16x32_bf16 v[74:77], v[138:141], v[182:185], v[74:77]
	v_mfma_f32_16x16x32_bf16 v[126:129], v[134:137], v[150:153], v[126:129]
	v_mfma_f32_16x16x32_bf16 v[122:125], v[142:145], v[150:153], v[122:125]
	v_mfma_f32_16x16x32_bf16 v[110:113], v[134:137], v[158:161], v[110:113]
	v_mfma_f32_16x16x32_bf16 v[106:109], v[142:145], v[158:161], v[106:109]
	v_mfma_f32_16x16x32_bf16 v[94:97], v[134:137], v[178:181], v[94:97]
	v_mfma_f32_16x16x32_bf16 v[90:93], v[142:145], v[178:181], v[90:93]
	v_mfma_f32_16x16x32_bf16 v[78:81], v[134:137], v[202:205], v[78:81]
	v_mfma_f32_16x16x32_bf16 v[74:77], v[142:145], v[202:205], v[74:77]
	s_setprio 0
	s_barrier
	s_add_i32 s10, 0, 0x1c000
	s_add_i32 s11, s14, s53
	v_add_u32_e32 v0, s10, v206
	s_mov_b32 m0, s11
	ds_read_b128 v[208:211], v0
	ds_read_b128 v[226:229], v0 offset:1024
	ds_read_b128 v[238:241], v0 offset:2048
	ds_read_b128 v[242:245], v0 offset:3072
	global_load_lds_dwordx4 v168, s[98:99]
	s_add_i32 m0, s11, 0x2000
	s_nop 0
	global_load_lds_dwordx4 v172, s[98:99]
	s_barrier
	s_waitcnt lgkmcnt(0)
	s_setprio 1
	s_waitcnt lgkmcnt(0)
	v_mfma_f32_16x16x32_bf16 v[118:121], v[208:211], v[146:149], v[118:121]
	v_mfma_f32_16x16x32_bf16 v[114:117], v[238:241], v[146:149], v[114:117]
	v_mfma_f32_16x16x32_bf16 v[102:105], v[208:211], v[154:157], v[102:105]
	v_mfma_f32_16x16x32_bf16 v[98:101], v[238:241], v[154:157], v[98:101]
	v_mfma_f32_16x16x32_bf16 v[86:89], v[208:211], v[162:165], v[86:89]
	v_mfma_f32_16x16x32_bf16 v[82:85], v[238:241], v[162:165], v[82:85]
	v_mfma_f32_16x16x32_bf16 v[70:73], v[208:211], v[182:185], v[70:73]
	v_mfma_f32_16x16x32_bf16 v[66:69], v[238:241], v[182:185], v[66:69]
	v_mfma_f32_16x16x32_bf16 v[118:121], v[226:229], v[150:153], v[118:121]
	v_mfma_f32_16x16x32_bf16 v[114:117], v[242:245], v[150:153], v[114:117]
	v_mfma_f32_16x16x32_bf16 v[102:105], v[226:229], v[158:161], v[102:105]
	v_mfma_f32_16x16x32_bf16 v[98:101], v[242:245], v[158:161], v[98:101]
	v_mfma_f32_16x16x32_bf16 v[86:89], v[226:229], v[178:181], v[86:89]
	v_mfma_f32_16x16x32_bf16 v[82:85], v[242:245], v[178:181], v[82:85]
	v_mfma_f32_16x16x32_bf16 v[70:73], v[226:229], v[202:205], v[70:73]
	v_mfma_f32_16x16x32_bf16 v[66:69], v[242:245], v[202:205], v[66:69]
	s_setprio 0
	s_mov_b32 m0, s57
	s_barrier
	ds_read_b128 v[146:149], v207 offset:49152
	ds_read_b128 v[150:153], v207 offset:50176
	ds_read_b128 v[154:157], v207 offset:51200
	ds_read_b128 v[158:161], v207 offset:52224
	ds_read_b128 v[162:165], v207 offset:53248
	ds_read_b128 v[178:181], v207 offset:54272
	ds_read_b128 v[182:185], v207 offset:55296
	ds_read_b128 v[202:205], v207 offset:56320
	global_load_lds_dwordx4 v166, s[100:101]
	s_mov_b32 m0, s74
	s_nop 0
	global_load_lds_dwordx4 v170, s[100:101]
	s_barrier
; template <class Epi, class Sched>
; DI void gemm_phase(LAS unsigned char* lds, const int tid, const Gemm g, const Sched& S, const Epi& E) {
;     ...
;       PG8_BAR; PG8_WAIT_L(0); PG8_MMA(1, 0, At, B0); PG8_BAR; PG8_SCHED;
;       PG8_STAGE(PG8_SB(1, 1), b3 + hstepB, voffB);
;       PG8_WAIT_V(6); PG8_BAR; PG8_MMA(1, 1, At, B1); PG8_BAR;
;     }
;     { int z_e = 0; asm volatile("" : "+v"(z_e)); const int lane_e = __builtin_amdgcn_mbcnt_hi(~0u, __builtin_amdgcn_mbcnt_lo(~0u, (unsigned)z_e));
;   DI void operator()(const AccT& acc, const Unit& u, int wr, int wc, int fr, int fq) const {
;     ...
;       const char* sc_b = (const char*)(ssq_ckv + (size_t)rowb * 2);
;       if (kind == 0) {
;         const char* skr_b = (const char*)(ssq_kr + rowb); const char* kr_b = (const char*)(KR + (size_t)rowb * 32);
;         const char* base = (const char*)(K + (size_t)rowb * 768 + head * 96);
;         const unsigned o0 = (rl0 * 768u + fq * 8) * 2u, o1 = (rl0 * 768u + 64 + fq * 8) * 2u, ko0 = (rl0 * 32u + fq * 8) * 4u;
;         f32x4 gv[2][2];
;         COLS_LOOP gv[bj][n] = ld4p((const char*)g_mk + (bj * 32 + n * 4) * 4, fq * 32u);
; #pragma unroll
;         for (int aim = 0; aim < 4; ++aim) { const int ai = aim >> 1, m0 = (aim & 1) * 2;
;           f32x2 s2[4]; float skr[4]; f32x4 k0[4], k1[4];
; #pragma unroll
;           for (int m = m0; m < m0 + 2; ++m) { s2[m] = ld2p(sc_b + (ai * 128 + m * 16) * 8, rl0 * 8u); skr[m] = ld1p(skr_b + (ai * 128 + m * 16) * 4, rl0 * 4u);
;             const char* krp = kr_b + (size_t)(ai * 128 + m * 16) * 32 * 4; k0[m] = ld4p(krp, ko0); k1[m] = ld4p(krp + 16, ko0); }
; #pragma unroll
;           for (int m = m0; m < m0 + 2; ++m) {
;             const float rs = rsqrtf((s2[m][0] + s2[m][1]) * (1.f / 128.f) + EPS);
;             const float ss = lane_ssq(acc, ai, m, rs);
;             const float rk = rsqrtf((ss + skr[m]) * (1.f / 96.f) + EPS);
;             char* rb = (char*)base + (size_t)(ai * 128 + m * 16) * 768 * 2;
; #pragma unroll
;             for (int bj = 0; bj < 2; ++bj) st8p(rb + bj * 64, o0, acc[ai][bj][m][0] * (rs * rk) * gv[bj][0], acc[ai][bj][m][1] * (rs * rk) * gv[bj][1]);
;             st8p(rb, o1, k0[m] * rk, k1[m] * rk);
;           }
;         }
;       } else {
;         const char* base = (const char*)(V + (size_t)rowb * 512 + head * 64);
;         const unsigned o0 = (rl0 * 512u + fq * 8) * 2u;
;         f32x2 s2[2][4];
	s_waitcnt lgkmcnt(0)
	s_setprio 1
	s_waitcnt lgkmcnt(0)
	v_mfma_f32_16x16x32_bf16 v[62:65], v[130:133], v[146:149], v[62:65]
	v_mfma_f32_16x16x32_bf16 v[58:61], v[138:141], v[146:149], v[58:61]
	v_mfma_f32_16x16x32_bf16 v[46:49], v[130:133], v[154:157], v[46:49]
	v_mfma_f32_16x16x32_bf16 v[42:45], v[138:141], v[154:157], v[42:45]
	v_mfma_f32_16x16x32_bf16 v[30:33], v[130:133], v[162:165], v[30:33]
	v_mfma_f32_16x16x32_bf16 v[26:29], v[138:141], v[162:165], v[26:29]
	v_mfma_f32_16x16x32_bf16 v[14:17], v[130:133], v[182:185], v[14:17]
	v_mfma_f32_16x16x32_bf16 v[10:13], v[138:141], v[182:185], v[10:13]
	v_mfma_f32_16x16x32_bf16 v[62:65], v[134:137], v[150:153], v[62:65]
	v_mfma_f32_16x16x32_bf16 v[58:61], v[142:145], v[150:153], v[58:61]
	v_mfma_f32_16x16x32_bf16 v[46:49], v[134:137], v[158:161], v[46:49]
	v_mfma_f32_16x16x32_bf16 v[42:45], v[142:145], v[158:161], v[42:45]
	v_mfma_f32_16x16x32_bf16 v[30:33], v[134:137], v[178:181], v[30:33]
	v_mfma_f32_16x16x32_bf16 v[26:29], v[142:145], v[178:181], v[26:29]
	v_mfma_f32_16x16x32_bf16 v[14:17], v[134:137], v[202:205], v[14:17]
	v_mfma_f32_16x16x32_bf16 v[10:13], v[142:145], v[202:205], v[10:13]
	s_setprio 0
	s_barrier
	s_add_i32 s10, s10, s53
	v_lshl_add_u64 v[130:131], v[216:217], 0, s[50:51]
	s_mov_b32 m0, s10
	s_nop 0
	global_load_lds_dwordx4 v[130:131], off
	v_lshl_add_u64 v[130:131], v[218:219], 0, s[50:51]
	s_add_i32 m0, s10, 0x2000
	s_nop 0
	global_load_lds_dwordx4 v[130:131], off
	s_waitcnt vmcnt(6)
	s_barrier
	s_setprio 1
	v_mfma_f32_16x16x32_bf16 v[54:57], v[208:211], v[146:149], v[54:57]
	v_mfma_f32_16x16x32_bf16 v[50:53], v[238:241], v[146:149], v[50:53]
	v_mfma_f32_16x16x32_bf16 v[38:41], v[208:211], v[154:157], v[38:41]
	v_mfma_f32_16x16x32_bf16 v[34:37], v[238:241], v[154:157], v[34:37]
	v_mfma_f32_16x16x32_bf16 v[22:25], v[208:211], v[162:165], v[22:25]
	v_mfma_f32_16x16x32_bf16 v[18:21], v[238:241], v[162:165], v[18:21]
	v_mfma_f32_16x16x32_bf16 v[6:9], v[208:211], v[182:185], v[6:9]
	v_mfma_f32_16x16x32_bf16 v[2:5], v[238:241], v[182:185], v[2:5]
	v_mfma_f32_16x16x32_bf16 v[54:57], v[226:229], v[150:153], v[54:57]
	v_mfma_f32_16x16x32_bf16 v[50:53], v[242:245], v[150:153], v[50:53]
	v_mfma_f32_16x16x32_bf16 v[38:41], v[226:229], v[158:161], v[38:41]
	v_mfma_f32_16x16x32_bf16 v[34:37], v[242:245], v[158:161], v[34:37]
	v_mfma_f32_16x16x32_bf16 v[22:25], v[226:229], v[178:181], v[22:25]
	v_mfma_f32_16x16x32_bf16 v[18:21], v[242:245], v[178:181], v[18:21]
	v_mfma_f32_16x16x32_bf16 v[6:9], v[226:229], v[202:205], v[6:9]
	v_mfma_f32_16x16x32_bf16 v[2:5], v[242:245], v[202:205], v[2:5]
	s_setprio 0
	s_add_u32 s28, s28, 0x100
	s_addc_u32 s29, s29, 0
	s_cmp_ge_u32 s30, s88
	s_mov_b64 s[10:11], s[0:1]
	s_mov_b32 s12, s30
	s_barrier
	s_cbranch_scc0 .LBB0_589
	v_mov_b32_e32 v0, v1
	s_add_i32 s0, s8, s3
	v_mbcnt_lo_u32_b32 v0, -1, v0
	v_mbcnt_hi_u32_b32 v204, -1, v0
	s_lshl_b32 s96, s80, 8
	s_lshl_b32 s23, s0, 1
	v_ashrrev_i32_e32 v202, 4, v204
	s_cmp_gt_i32 s0, 3
	v_and_or_b32 v205, v204, 15, s56
	s_cbranch_scc0 .LBB0_596
	s_add_i32 s12, s23, s90
	s_lshl_b64 s[0:1], s[96:97], 3
	s_add_u32 s8, s84, s0
	s_addc_u32 s9, s36, s1
	s_mov_b64 s[0:1], -1
	s_and_b64 vcc, exec, s[18:19]
	v_lshlrev_b32_e32 v203, 3, v205
	s_cbranch_vccz .LBB0_593
	global_load_dwordx2 v[136:137], v203, s[8:9]
	global_load_dwordx2 v[146:147], v203, s[8:9] offset:128
	global_load_dwordx2 v[142:143], v203, s[8:9] offset:256
	global_load_dwordx2 v[144:145], v203, s[8:9] offset:384
	global_load_dwordx2 v[138:139], v203, s[8:9] offset:1024
	global_load_dwordx2 v[140:141], v203, s[8:9] offset:1152
	global_load_dwordx2 v[132:133], v203, s[8:9] offset:1280
	global_load_dwordx2 v[134:135], v203, s[8:9] offset:1408
	s_lshl_b64 s[0:1], s[96:97], 10
	s_add_u32 s10, s95, s0
	s_addc_u32 s11, s38, s1
	s_lshl_b32 s0, s12, 6
	s_mov_b32 s1, s97
	s_lshl_b64 s[0:1], s[0:1], 1
	s_add_u32 s10, s10, s0
	s_mov_b32 s0, 0x358637bd
	s_brev_b32 s14, 60
	s_mov_b32 s15, 0x3c2aaaab
	s_addc_u32 s11, s11, s1
	v_and_b32_e32 v0, -16, v204
	v_lshl_add_u32 v0, v205, 10, v0
	v_lshl_add_u64 v[130:131], s[10:11], 0, v[0:1]
	s_waitcnt vmcnt(0)
	v_mov_b32_e32 v149, v136
	v_mov_b32_e32 v148, v146
	v_mov_b32_e32 v136, v147
	v_pk_add_f32 v[146:147], v[148:149], v[136:137]
	v_mov_b64_e32 v[136:137], s[0:1]
	v_pk_fma_f32 v[150:151], v[146:147], s[14:15], v[136:137] op_sel_hi:[1,0,0]
	s_nop 0
	v_mul_f32_e32 v146, 0x4b800000, v151
	v_cmp_gt_f32_e64 s[0:1], s45, v151
	v_cmp_gt_f32_e32 vcc, s45, v150
	s_nop 0
	v_cndmask_b32_e64 v146, v151, v146, s[0:1]
	v_rsq_f32_e32 v146, v146
	s_nop 0
	v_mul_f32_e32 v147, 0x45800000, v146
	v_cndmask_b32_e64 v152, v146, v147, s[0:1]
	v_pk_mul_f32 v[148:149], v[128:129], v[152:153] op_sel_hi:[1,0]
	v_pk_mul_f32 v[146:147], v[126:127], v[152:153] op_sel_hi:[1,0]
	v_pk_mul_f32 v[154:155], v[124:125], v[152:153] op_sel_hi:[1,0]
	v_pk_mul_f32 v[156:157], v[122:123], v[152:153] op_sel_hi:[1,0]
	v_cvt_pk_bf16_f32 v146, v146, v147
	v_cvt_pk_bf16_f32 v147, v148, v149
	v_cvt_pk_bf16_f32 v148, v156, v157
	v_cvt_pk_bf16_f32 v149, v154, v155
	global_store_dwordx4 v0, v[146:149], s[10:11]
	v_pk_mul_f32 v[154:155], v[116:117], v[152:153] op_sel_hi:[1,0]
	s_movk_i32 s0, 0x4000
	v_pk_mul_f32 v[148:149], v[120:121], v[152:153] op_sel_hi:[1,0]
	v_pk_mul_f32 v[146:147], v[118:119], v[152:153] op_sel_hi:[1,0]
	v_pk_mul_f32 v[152:153], v[114:115], v[152:153] op_sel_hi:[1,0]
	v_cvt_pk_bf16_f32 v146, v146, v147
	v_cvt_pk_bf16_f32 v147, v148, v149
	v_cvt_pk_bf16_f32 v148, v152, v153
	v_cvt_pk_bf16_f32 v149, v154, v155
	global_store_dwordx4 v0, v[146:149], s[10:11] offset:64
	v_mul_f32_e32 v0, 0x4b800000, v150
	v_cndmask_b32_e32 v0, v150, v0, vcc
; DI void st8p(void* ub, unsigned voff, f32x4 a, f32x4 b) { u32x4 o = {pk(a[0], a[1]), pk(a[2], a[3]), pk(b[0], b[1]), pk(b[2], b[3])}; *(GAS u32x4*)((char*)ub + voff) = o; }
; #define ROWS_LOOP _Pragma("unroll") for (int ai = 0; ai < 2; ++ai) _Pragma("unroll") for (int m = 0; m < 4; ++m)
;   DI void operator()(const AccT& acc, const Unit& u, int wr, int wc, int fr, int fq) const {
;     ...
;         const char* base = (const char*)(V + (size_t)rowb * 512 + head * 64);
;         const unsigned o0 = (rl0 * 512u + fq * 8) * 2u;
;         f32x2 s2[2][4];
;         ROWS_LOOP s2[ai][m] = ld2p(sc_b + (ai * 128 + m * 16) * 8, rl0 * 8u);
;         ROWS_LOOP {
;           const float rs = rsqrtf((s2[ai][m][0] + s2[ai][m][1]) * (1.f / 128.f) + EPS);
;           char* rb = (char*)base + (size_t)(ai * 128 + m * 16) * 512 * 2;
; #pragma unroll
;           for (int bj = 0; bj < 2; ++bj) st8p(rb + bj * 64, o0, acc[ai][bj][m][0] * rs, acc[ai][bj][m][1] * rs);
	v_rsq_f32_e32 v0, v0
	s_nop 0
	v_mul_f32_e32 v146, 0x45800000, v0
	v_cndmask_b32_e32 v0, v0, v146, vcc
	v_pk_mul_f32 v[148:149], v[112:113], v[0:1] op_sel_hi:[1,0]
	v_pk_mul_f32 v[146:147], v[110:111], v[0:1] op_sel_hi:[1,0]
	v_pk_mul_f32 v[150:151], v[108:109], v[0:1] op_sel_hi:[1,0]
	v_pk_mul_f32 v[152:153], v[106:107], v[0:1] op_sel_hi:[1,0]
	v_cvt_pk_bf16_f32 v146, v146, v147
	v_cvt_pk_bf16_f32 v147, v148, v149
	v_cvt_pk_bf16_f32 v149, v150, v151
	v_add_co_u32_e32 v150, vcc, s0, v130
	v_cvt_pk_bf16_f32 v148, v152, v153
	s_nop 0
	v_addc_co_u32_e32 v151, vcc, 0, v131, vcc
	global_store_dwordx4 v[150:151], v[146:149], off
	v_pk_mul_f32 v[152:153], v[100:101], v[0:1] op_sel_hi:[1,0]
	v_pk_mul_f32 v[154:155], v[98:99], v[0:1] op_sel_hi:[1,0]
	v_pk_mul_f32 v[148:149], v[104:105], v[0:1] op_sel_hi:[1,0]
	v_pk_mul_f32 v[146:147], v[102:103], v[0:1] op_sel_hi:[1,0]
	s_nop 0
	v_cvt_pk_bf16_f32 v146, v146, v147
	v_cvt_pk_bf16_f32 v147, v148, v149
	v_cvt_pk_bf16_f32 v148, v154, v155
	v_cvt_pk_bf16_f32 v149, v152, v153
	global_store_dwordx4 v[150:151], v[146:149], off offset:64
	s_nop 1
	v_mov_b32_e32 v146, v144
	v_mov_b32_e32 v147, v142
	v_mov_b32_e32 v142, v145
	v_pk_add_f32 v[142:143], v[146:147], v[142:143]
	s_nop 0
	v_pk_fma_f32 v[142:143], v[142:143], s[14:15], v[136:137] op_sel_hi:[1,0,0]
	s_nop 0
	v_mul_f32_e32 v0, 0x4b800000, v143
	v_cmp_gt_f32_e64 s[0:1], s45, v143
	v_cmp_gt_f32_e32 vcc, s45, v142
	s_nop 0
	v_cndmask_b32_e64 v0, v143, v0, s[0:1]
	v_rsq_f32_e32 v0, v0
	s_nop 0
	v_mul_f32_e32 v143, 0x45800000, v0
	v_cndmask_b32_e64 v0, v0, v143, s[0:1]
	v_pk_mul_f32 v[146:147], v[96:97], v[0:1] op_sel_hi:[1,0]
	v_pk_mul_f32 v[144:145], v[94:95], v[0:1] op_sel_hi:[1,0]
	v_pk_mul_f32 v[148:149], v[92:93], v[0:1] op_sel_hi:[1,0]
	s_mov_b32 s0, 0x8000
	v_pk_mul_f32 v[150:151], v[90:91], v[0:1] op_sel_hi:[1,0]
	v_cvt_pk_bf16_f32 v144, v144, v145
	v_cvt_pk_bf16_f32 v145, v146, v147
	v_cvt_pk_bf16_f32 v147, v148, v149
	v_add_co_u32_e64 v148, s[0:1], s0, v130
	v_cvt_pk_bf16_f32 v146, v150, v151
	s_nop 0
	v_addc_co_u32_e64 v149, s[0:1], 0, v131, s[0:1]
	global_store_dwordx4 v[148:149], v[144:147], off
	v_pk_mul_f32 v[150:151], v[84:85], v[0:1] op_sel_hi:[1,0]
	v_pk_mul_f32 v[152:153], v[82:83], v[0:1] op_sel_hi:[1,0]
	v_pk_mul_f32 v[146:147], v[88:89], v[0:1] op_sel_hi:[1,0]
	v_pk_mul_f32 v[144:145], v[86:87], v[0:1] op_sel_hi:[1,0]
	v_mul_f32_e32 v0, 0x4b800000, v142
	v_cndmask_b32_e32 v0, v142, v0, vcc
	v_rsq_f32_e32 v0, v0
	v_cvt_pk_bf16_f32 v144, v144, v145
	v_cvt_pk_bf16_f32 v145, v146, v147
	v_cvt_pk_bf16_f32 v146, v152, v153
	v_mul_f32_e32 v142, 0x45800000, v0
	v_cvt_pk_bf16_f32 v147, v150, v151
	v_cndmask_b32_e32 v0, v0, v142, vcc
	global_store_dwordx4 v[148:149], v[144:147], off offset:64
	v_pk_mul_f32 v[142:143], v[78:79], v[0:1] op_sel_hi:[1,0]
	s_mov_b32 s0, 0xc000
	v_pk_mul_f32 v[144:145], v[80:81], v[0:1] op_sel_hi:[1,0]
	v_pk_mul_f32 v[146:147], v[76:77], v[0:1] op_sel_hi:[1,0]
	v_pk_mul_f32 v[148:149], v[74:75], v[0:1] op_sel_hi:[1,0]
	v_cvt_pk_bf16_f32 v142, v142, v143
	v_cvt_pk_bf16_f32 v143, v144, v145
	v_cvt_pk_bf16_f32 v145, v146, v147
	v_add_co_u32_e32 v146, vcc, s0, v130
	v_cvt_pk_bf16_f32 v144, v148, v149
	s_nop 0
	v_addc_co_u32_e32 v147, vcc, 0, v131, vcc
	global_store_dwordx4 v[146:147], v[142:145], off
	v_pk_mul_f32 v[148:149], v[68:69], v[0:1] op_sel_hi:[1,0]
	v_pk_mul_f32 v[150:151], v[66:67], v[0:1] op_sel_hi:[1,0]
	v_pk_mul_f32 v[144:145], v[72:73], v[0:1] op_sel_hi:[1,0]
	v_pk_mul_f32 v[142:143], v[70:71], v[0:1] op_sel_hi:[1,0]
	s_nop 0
	v_cvt_pk_bf16_f32 v142, v142, v143
	v_cvt_pk_bf16_f32 v143, v144, v145
	v_cvt_pk_bf16_f32 v144, v150, v151
	v_cvt_pk_bf16_f32 v145, v148, v149
	global_store_dwordx4 v[146:147], v[142:145], off offset:64
	s_nop 1
	v_mov_b32_e32 v142, v140
	v_mov_b32_e32 v143, v138
	v_mov_b32_e32 v138, v141
	v_pk_add_f32 v[138:139], v[142:143], v[138:139]
	s_nop 0
	v_pk_fma_f32 v[142:143], v[138:139], s[14:15], v[136:137] op_sel_hi:[1,0,0]
	s_nop 0
	v_mul_f32_e32 v0, 0x4b800000, v143
	v_cmp_gt_f32_e64 s[0:1], s45, v143
	v_cmp_gt_f32_e32 vcc, s45, v142
	s_nop 0
	v_cndmask_b32_e64 v0, v143, v0, s[0:1]
	v_rsq_f32_e32 v0, v0
	s_nop 0
	v_mul_f32_e32 v138, 0x45800000, v0
	v_cndmask_b32_e64 v0, v0, v138, s[0:1]
	v_pk_mul_f32 v[140:141], v[64:65], v[0:1] op_sel_hi:[1,0]
	v_pk_mul_f32 v[138:139], v[62:63], v[0:1] op_sel_hi:[1,0]
	v_pk_mul_f32 v[144:145], v[60:61], v[0:1] op_sel_hi:[1,0]
	v_pk_mul_f32 v[146:147], v[58:59], v[0:1] op_sel_hi:[1,0]
	v_cvt_pk_bf16_f32 v138, v138, v139
	v_cvt_pk_bf16_f32 v139, v140, v141
; DI void st8p(void* ub, unsigned voff, f32x4 a, f32x4 b) { u32x4 o = {pk(a[0], a[1]), pk(a[2], a[3]), pk(b[0], b[1]), pk(b[2], b[3])}; *(GAS u32x4*)((char*)ub + voff) = o; }
; #define ROWS_LOOP _Pragma("unroll") for (int ai = 0; ai < 2; ++ai) _Pragma("unroll") for (int m = 0; m < 4; ++m)
;   DI void operator()(const AccT& acc, const Unit& u, int wr, int wc, int fr, int fq) const {
;     ...
;         const char* base = (const char*)(V + (size_t)rowb * 512 + head * 64);
;         const unsigned o0 = (rl0 * 512u + fq * 8) * 2u;
;         f32x2 s2[2][4];
;         ROWS_LOOP s2[ai][m] = ld2p(sc_b + (ai * 128 + m * 16) * 8, rl0 * 8u);
;         ROWS_LOOP {
;           const float rs = rsqrtf((s2[ai][m][0] + s2[ai][m][1]) * (1.f / 128.f) + EPS);
;           char* rb = (char*)base + (size_t)(ai * 128 + m * 16) * 512 * 2;
; #pragma unroll
;           for (int bj = 0; bj < 2; ++bj) st8p(rb + bj * 64, o0, acc[ai][bj][m][0] * rs, acc[ai][bj][m][1] * rs);
	v_cvt_pk_bf16_f32 v141, v144, v145
	v_add_co_u32_e64 v144, s[0:1], s71, v130
	v_cvt_pk_bf16_f32 v140, v146, v147
	s_nop 0
	v_addc_co_u32_e64 v145, s[0:1], 0, v131, s[0:1]
	global_store_dwordx4 v[144:145], v[138:141], off
	v_pk_mul_f32 v[146:147], v[52:53], v[0:1] op_sel_hi:[1,0]
	v_pk_mul_f32 v[148:149], v[50:51], v[0:1] op_sel_hi:[1,0]
	v_pk_mul_f32 v[140:141], v[56:57], v[0:1] op_sel_hi:[1,0]
	v_pk_mul_f32 v[138:139], v[54:55], v[0:1] op_sel_hi:[1,0]
	v_mul_f32_e32 v0, 0x4b800000, v142
	v_cndmask_b32_e32 v0, v142, v0, vcc
	v_rsq_f32_e32 v0, v0
	v_cvt_pk_bf16_f32 v138, v138, v139
	v_cvt_pk_bf16_f32 v139, v140, v141
	v_cvt_pk_bf16_f32 v140, v148, v149
	v_cvt_pk_bf16_f32 v141, v146, v147
	global_store_dwordx4 v[144:145], v[138:141], off offset:64
	s_mov_b32 s0, 0x24000
	s_nop 0
	v_mul_f32_e32 v138, 0x45800000, v0
	v_cndmask_b32_e32 v0, v0, v138, vcc
	v_pk_mul_f32 v[140:141], v[48:49], v[0:1] op_sel_hi:[1,0]
	v_pk_mul_f32 v[138:139], v[46:47], v[0:1] op_sel_hi:[1,0]
	v_pk_mul_f32 v[142:143], v[44:45], v[0:1] op_sel_hi:[1,0]
	v_pk_mul_f32 v[144:145], v[42:43], v[0:1] op_sel_hi:[1,0]
	v_cvt_pk_bf16_f32 v138, v138, v139
	v_cvt_pk_bf16_f32 v139, v140, v141
	v_cvt_pk_bf16_f32 v141, v142, v143
	v_add_co_u32_e32 v142, vcc, s0, v130
	v_cvt_pk_bf16_f32 v140, v144, v145
	s_nop 0
	v_addc_co_u32_e32 v143, vcc, 0, v131, vcc
	global_store_dwordx4 v[142:143], v[138:141], off
	v_pk_mul_f32 v[144:145], v[36:37], v[0:1] op_sel_hi:[1,0]
	v_pk_mul_f32 v[146:147], v[34:35], v[0:1] op_sel_hi:[1,0]
	v_pk_mul_f32 v[140:141], v[40:41], v[0:1] op_sel_hi:[1,0]
	v_pk_mul_f32 v[138:139], v[38:39], v[0:1] op_sel_hi:[1,0]
	s_nop 0
	v_cvt_pk_bf16_f32 v138, v138, v139
	v_cvt_pk_bf16_f32 v139, v140, v141
	v_cvt_pk_bf16_f32 v140, v146, v147
	v_cvt_pk_bf16_f32 v141, v144, v145
	global_store_dwordx4 v[142:143], v[138:141], off offset:64
	s_nop 1
	v_mov_b32_e32 v138, v134
	v_mov_b32_e32 v139, v132
	v_mov_b32_e32 v132, v135
	v_pk_add_f32 v[132:133], v[138:139], v[132:133]
	s_nop 0
	v_pk_fma_f32 v[136:137], v[132:133], s[14:15], v[136:137] op_sel_hi:[1,0,0]
	s_nop 0
	v_mul_f32_e32 v0, 0x4b800000, v137
	v_cmp_gt_f32_e64 s[0:1], s45, v137
	v_cmp_gt_f32_e32 vcc, s45, v136
	s_nop 0
	v_cndmask_b32_e64 v0, v137, v0, s[0:1]
	v_rsq_f32_e32 v0, v0
	s_nop 0
	v_mul_f32_e32 v132, 0x45800000, v0
	v_cndmask_b32_e64 v0, v0, v132, s[0:1]
	v_pk_mul_f32 v[134:135], v[32:33], v[0:1] op_sel_hi:[1,0]
	v_pk_mul_f32 v[132:133], v[30:31], v[0:1] op_sel_hi:[1,0]
	v_pk_mul_f32 v[138:139], v[28:29], v[0:1] op_sel_hi:[1,0]
	s_mov_b32 s0, 0x28000
	v_pk_mul_f32 v[140:141], v[26:27], v[0:1] op_sel_hi:[1,0]
	v_cvt_pk_bf16_f32 v132, v132, v133
	v_cvt_pk_bf16_f32 v133, v134, v135
	v_cvt_pk_bf16_f32 v135, v138, v139
	v_add_co_u32_e64 v138, s[0:1], s0, v130
	v_cvt_pk_bf16_f32 v134, v140, v141
	s_nop 0
	v_addc_co_u32_e64 v139, s[0:1], 0, v131, s[0:1]
	global_store_dwordx4 v[138:139], v[132:135], off
	v_pk_mul_f32 v[140:141], v[20:21], v[0:1] op_sel_hi:[1,0]
	v_pk_mul_f32 v[142:143], v[18:19], v[0:1] op_sel_hi:[1,0]
	v_pk_mul_f32 v[134:135], v[24:25], v[0:1] op_sel_hi:[1,0]
	v_pk_mul_f32 v[132:133], v[22:23], v[0:1] op_sel_hi:[1,0]
	v_mul_f32_e32 v0, 0x4b800000, v136
	v_cndmask_b32_e32 v0, v136, v0, vcc
	v_rsq_f32_e32 v0, v0
	v_cvt_pk_bf16_f32 v132, v132, v133
	v_cvt_pk_bf16_f32 v133, v134, v135
	v_cvt_pk_bf16_f32 v134, v142, v143
	v_cvt_pk_bf16_f32 v135, v140, v141
	global_store_dwordx4 v[138:139], v[132:135], off offset:64
	s_mov_b32 s0, 0x2c000
	s_nop 0
	v_mul_f32_e32 v132, 0x45800000, v0
	v_cndmask_b32_e32 v0, v0, v132, vcc
	v_pk_mul_f32 v[134:135], v[16:17], v[0:1] op_sel_hi:[1,0]
	v_pk_mul_f32 v[132:133], v[14:15], v[0:1] op_sel_hi:[1,0]
	v_pk_mul_f32 v[136:137], v[12:13], v[0:1] op_sel_hi:[1,0]
	v_pk_mul_f32 v[138:139], v[10:11], v[0:1] op_sel_hi:[1,0]
	v_cvt_pk_bf16_f32 v132, v132, v133
	v_cvt_pk_bf16_f32 v133, v134, v135
	v_cvt_pk_bf16_f32 v135, v136, v137
	v_add_co_u32_e32 v136, vcc, s0, v130
	v_cvt_pk_bf16_f32 v134, v138, v139
	s_nop 0
	v_addc_co_u32_e32 v137, vcc, 0, v131, vcc
	global_store_dwordx4 v[136:137], v[132:135], off
	v_pk_mul_f32 v[136:137], v[4:5], v[0:1] op_sel_hi:[1,0]
	v_pk_mul_f32 v[140:141], v[2:3], v[0:1] op_sel_hi:[1,0]
	v_pk_mul_f32 v[132:133], v[8:9], v[0:1] op_sel_hi:[1,0]
	v_pk_mul_f32 v[134:135], v[6:7], v[0:1] op_sel_hi:[1,0]
	s_mov_b64 s[0:1], 0x2c040
	v_cvt_pk_bf16_f32 v138, v134, v135
	v_cvt_pk_bf16_f32 v139, v132, v133
	v_cvt_pk_bf16_f32 v140, v140, v141
	v_cvt_pk_bf16_f32 v141, v136, v137
	v_lshl_add_u64 v[142:143], v[130:131], 0, s[0:1]
	s_mov_b64 s[0:1], 0

; #define PG8_STAGE(bufoff, gbase, voff) do { _Pragma("unroll") for (int _i = 0; _i < 2; ++_i) \
;     __builtin_amdgcn_global_load_lds((const unsigned*)((const char*)(gbase) + (voff)[_i]), (LAS unsigned*)(lds + (bufoff) + ldsw + _i * 8192), 16, 0, 0); } while (0)
; #define PG8_LDA(dst, b, h) do { _Pragma("unroll") for (int m = 0; m < 4; ++m) _Pragma("unroll") for (int k = 0; k < 2; ++k) dst[m][k] = *(const LAS bf16x8*)(lds + PG8_SA(b, h) + aoff + m * 2048 + k * 1024); } while (0)
; #define PG8_LDB(dst, b, h) do { _Pragma("unroll") for (int n = 0; n < 2; ++n) _Pragma("unroll") for (int k = 0; k < 2; ++k) dst[n][k] = *(const LAS bf16x8*)(lds + PG8_SB(b, h) + boff + n * 2048 + k * 1024); } while (0)
; #define PG8_MMA(ai, bj, At, Bt) do { __builtin_amdgcn_s_setprio(1); _Pragma("unroll") for (int m = 0; m < 4; ++m) _Pragma("unroll") for (int n = 0; n < 2; ++n) _Pragma("unroll") for (int k = 0; k < 2; ++k) \
;     acc[ai][bj][m][n] = __builtin_amdgcn_mfma_f32_16x16x32_bf16(Bt[n][k], At[m][k], acc[ai][bj][m][n], 0, 0, 0); __builtin_amdgcn_s_setprio(0); } while (0)
; #define PG8_WAIT_V(n) asm volatile("s_waitcnt vmcnt(" #n ")" ::: "memory")
; #define PG8_WAIT_L(n) asm volatile("s_waitcnt lgkmcnt(" #n ")" ::: "memory")
; #define PG8_BAR __builtin_amdgcn_s_barrier()
; #define PG8_SCHED __builtin_amdgcn_sched_barrier(0)
; template <class Epi, class Sched>
; DI void gemm_phase(LAS unsigned char* lds, const int tid, const Gemm g, const Sched& S, const Epi& E) {
;     ...
;       const bool last = (t == nt - 2);
;       const char* a1 = cA + (size_t)(t + 1) * kstep;
;       const char* a2 = last ? nA : cA + (size_t)(t + 2) * kstep; const char* b2 = last ? nB : cB + (size_t)(t + 2) * kstep;
;       const char* a3 = a2 + kstep; const char* b3 = b2 + kstep;
;       PG8_LDB(B0, 0, 0); PG8_SCHED; PG8_LDA(At, 0, 0); PG8_STAGE(PG8_SA(1, 1), a1 + hstepA, voffA);
;       PG8_WAIT_L(8); PG8_BAR; PG8_WAIT_L(0); PG8_MMA(0, 0, At, B0); PG8_BAR; PG8_SCHED;
;       PG8_LDB(B1, 0, 1); PG8_STAGE(PG8_SB(0, 0), b2, voffB);
;       PG8_BAR; PG8_WAIT_L(0); PG8_MMA(0, 1, At, B1); PG8_BAR;
;       PG8_LDA(At, 0, 1); PG8_STAGE(PG8_SA(0, 0), a2, voffA);
;       PG8_BAR; PG8_WAIT_L(0); PG8_MMA(1, 0, At, B0); PG8_BAR; PG8_SCHED;
;       PG8_STAGE(PG8_SB(0, 1), b2 + hstepB, voffB);
;       PG8_WAIT_V(6); PG8_BAR; PG8_MMA(1, 1, At, B1); PG8_BAR;
.LBB0_645:
	s_add_u32 s14, s12, 0xfffe0080
	s_addc_u32 s15, s13, -1
	s_add_i32 s40, 0, 0x10000
	v_add_u32_e32 v0, s40, v142
	ds_read_b128 v[144:147], v0
	ds_read_b128 v[148:151], v0 offset:1024
	ds_read_b128 v[152:155], v0 offset:2048
	ds_read_b128 v[156:159], v0 offset:3072
	s_cmp_eq_u32 s39, 4
	s_cselect_b32 s17, s7, s15
	s_cselect_b32 s16, s35, s14
	s_cselect_b32 s15, s5, s38
	s_cselect_b32 s14, s36, s37
	s_add_i32 m0, s22, 0xc000
	ds_read_b128 v[160:163], v143
	ds_read_b128 v[164:167], v143 offset:1024
	ds_read_b128 v[168:171], v143 offset:2048
	ds_read_b128 v[172:175], v143 offset:3072
	ds_read_b128 v[176:179], v143 offset:4096
	ds_read_b128 v[180:183], v143 offset:5120
	ds_read_b128 v[202:205], v143 offset:6144
	ds_read_b128 v[206:209], v143 offset:7168
	global_load_lds_dwordx4 v140, s[12:13]
	s_add_i32 m0, s22, 0xe000
	s_nop 0
	global_load_lds_dwordx4 v138, s[12:13]
	s_waitcnt lgkmcnt(8)
	s_barrier
	s_waitcnt lgkmcnt(0)
	s_setprio 1
	s_waitcnt lgkmcnt(0)
	v_mfma_f32_16x16x32_bf16 v[126:129], v[144:147], v[160:163], v[126:129]
	v_mfma_f32_16x16x32_bf16 v[122:125], v[152:155], v[160:163], v[122:125]
	v_mfma_f32_16x16x32_bf16 v[118:121], v[144:147], v[168:171], v[118:121]
	v_mfma_f32_16x16x32_bf16 v[114:117], v[152:155], v[168:171], v[114:117]
	v_mfma_f32_16x16x32_bf16 v[102:105], v[144:147], v[176:179], v[102:105]
	v_mfma_f32_16x16x32_bf16 v[98:101], v[152:155], v[176:179], v[98:101]
	v_mfma_f32_16x16x32_bf16 v[86:89], v[144:147], v[202:205], v[86:89]
	v_mfma_f32_16x16x32_bf16 v[82:85], v[152:155], v[202:205], v[82:85]
	v_mfma_f32_16x16x32_bf16 v[126:129], v[148:151], v[164:167], v[126:129]
	v_mfma_f32_16x16x32_bf16 v[122:125], v[156:159], v[164:167], v[122:125]
	v_mfma_f32_16x16x32_bf16 v[118:121], v[148:151], v[172:175], v[118:121]
	v_mfma_f32_16x16x32_bf16 v[114:117], v[156:159], v[172:175], v[114:117]
	v_mfma_f32_16x16x32_bf16 v[102:105], v[148:151], v[180:183], v[102:105]
	v_mfma_f32_16x16x32_bf16 v[98:101], v[156:159], v[180:183], v[98:101]
	v_mfma_f32_16x16x32_bf16 v[86:89], v[148:151], v[206:209], v[86:89]
	v_mfma_f32_16x16x32_bf16 v[82:85], v[156:159], v[206:209], v[82:85]
	s_setprio 0
	s_barrier
	s_add_i32 s42, 0, 0x14000
	s_add_i32 s40, s40, s21
	v_add_u32_e32 v0, s42, v142
	s_add_u32 s98, s14, s50
	s_addc_u32 s99, s15, s51
	s_mov_b32 m0, s40
	ds_read_b128 v[210:213], v0
	ds_read_b128 v[226:229], v0 offset:1024
	ds_read_b128 v[238:241], v0 offset:2048
	ds_read_b128 v[242:245], v0 offset:3072
	global_load_lds_dwordx4 v134, s[14:15]
	s_add_i32 m0, s40, 0x2000
	s_nop 0
	global_load_lds_dwordx4 v130, s[14:15]
	s_barrier
	s_waitcnt lgkmcnt(0)
	s_setprio 1
	s_waitcnt lgkmcnt(0)
	v_mfma_f32_16x16x32_bf16 v[110:113], v[210:213], v[160:163], v[110:113]
	v_mfma_f32_16x16x32_bf16 v[106:109], v[238:241], v[160:163], v[106:109]
	v_mfma_f32_16x16x32_bf16 v[94:97], v[210:213], v[168:171], v[94:97]
	v_mfma_f32_16x16x32_bf16 v[90:93], v[238:241], v[168:171], v[90:93]
	v_mfma_f32_16x16x32_bf16 v[78:81], v[210:213], v[176:179], v[78:81]
	v_mfma_f32_16x16x32_bf16 v[74:77], v[238:241], v[176:179], v[74:77]
	v_mfma_f32_16x16x32_bf16 v[70:73], v[210:213], v[202:205], v[70:73]
	v_mfma_f32_16x16x32_bf16 v[66:69], v[238:241], v[202:205], v[66:69]
	v_mfma_f32_16x16x32_bf16 v[110:113], v[226:229], v[164:167], v[110:113]
	v_mfma_f32_16x16x32_bf16 v[106:109], v[242:245], v[164:167], v[106:109]
	v_mfma_f32_16x16x32_bf16 v[94:97], v[226:229], v[172:175], v[94:97]
	v_mfma_f32_16x16x32_bf16 v[90:93], v[242:245], v[172:175], v[90:93]
	v_mfma_f32_16x16x32_bf16 v[78:81], v[226:229], v[180:183], v[78:81]
	v_mfma_f32_16x16x32_bf16 v[74:77], v[242:245], v[180:183], v[74:77]
	v_mfma_f32_16x16x32_bf16 v[70:73], v[226:229], v[206:209], v[70:73]
	v_mfma_f32_16x16x32_bf16 v[66:69], v[242:245], v[206:209], v[66:69]
	s_setprio 0
	s_mov_b32 m0, s22
	s_add_u32 s100, s16, s50
	s_addc_u32 s101, s17, s51
	s_barrier
	ds_read_b128 v[160:163], v143 offset:16384
	ds_read_b128 v[164:167], v143 offset:17408
	ds_read_b128 v[168:171], v143 offset:18432
	ds_read_b128 v[172:175], v143 offset:19456
	ds_read_b128 v[176:179], v143 offset:20480
	ds_read_b128 v[180:183], v143 offset:21504
	ds_read_b128 v[202:205], v143 offset:22528
	ds_read_b128 v[206:209], v143 offset:23552
	global_load_lds_dwordx4 v136, s[16:17]
	s_mov_b32 m0, s23
	s_nop 0
	global_load_lds_dwordx4 v132, s[16:17]
	s_barrier
	s_waitcnt lgkmcnt(0)
	s_setprio 1
	s_waitcnt lgkmcnt(0)
	v_mfma_f32_16x16x32_bf16 v[62:65], v[144:147], v[160:163], v[62:65]
	v_mfma_f32_16x16x32_bf16 v[58:61], v[152:155], v[160:163], v[58:61]
	v_mfma_f32_16x16x32_bf16 v[54:57], v[144:147], v[168:171], v[54:57]
	v_mfma_f32_16x16x32_bf16 v[50:53], v[152:155], v[168:171], v[50:53]
	v_mfma_f32_16x16x32_bf16 v[38:41], v[144:147], v[176:179], v[38:41]
	v_mfma_f32_16x16x32_bf16 v[34:37], v[152:155], v[176:179], v[34:37]
	v_mfma_f32_16x16x32_bf16 v[22:25], v[144:147], v[202:205], v[22:25]
	v_mfma_f32_16x16x32_bf16 v[18:21], v[152:155], v[202:205], v[18:21]
	v_mfma_f32_16x16x32_bf16 v[62:65], v[148:151], v[164:167], v[62:65]
	v_mfma_f32_16x16x32_bf16 v[58:61], v[156:159], v[164:167], v[58:61]
	v_mfma_f32_16x16x32_bf16 v[54:57], v[148:151], v[172:175], v[54:57]
	v_mfma_f32_16x16x32_bf16 v[50:53], v[156:159], v[172:175], v[50:53]
	v_mfma_f32_16x16x32_bf16 v[38:41], v[148:151], v[180:183], v[38:41]
	v_mfma_f32_16x16x32_bf16 v[34:37], v[156:159], v[180:183], v[34:37]
	v_mfma_f32_16x16x32_bf16 v[22:25], v[148:151], v[206:209], v[22:25]
	v_mfma_f32_16x16x32_bf16 v[18:21], v[156:159], v[206:209], v[18:21]
	s_setprio 0
	s_barrier
	s_add_u32 s40, s14, 0x20000
	s_addc_u32 s41, s15, 0
	s_add_i32 s42, s42, s21
	s_mov_b32 m0, s42
	s_nop 0
	global_load_lds_dwordx4 v134, s[40:41]
	s_add_i32 m0, s42, 0x2000
	s_nop 0
	global_load_lds_dwordx4 v130, s[40:41]
	s_waitcnt vmcnt(6)
	s_barrier
; #define PG8_STAGE(bufoff, gbase, voff) do { _Pragma("unroll") for (int _i = 0; _i < 2; ++_i) \
;     __builtin_amdgcn_global_load_lds((const unsigned*)((const char*)(gbase) + (voff)[_i]), (LAS unsigned*)(lds + (bufoff) + ldsw + _i * 8192), 16, 0, 0); } while (0)
; #define PG8_LDA(dst, b, h) do { _Pragma("unroll") for (int m = 0; m < 4; ++m) _Pragma("unroll") for (int k = 0; k < 2; ++k) dst[m][k] = *(const LAS bf16x8*)(lds + PG8_SA(b, h) + aoff + m * 2048 + k * 1024); } while (0)
; #define PG8_LDB(dst, b, h) do { _Pragma("unroll") for (int n = 0; n < 2; ++n) _Pragma("unroll") for (int k = 0; k < 2; ++k) dst[n][k] = *(const LAS bf16x8*)(lds + PG8_SB(b, h) + boff + n * 2048 + k * 1024); } while (0)
; #define PG8_MMA(ai, bj, At, Bt) do { __builtin_amdgcn_s_setprio(1); _Pragma("unroll") for (int m = 0; m < 4; ++m) _Pragma("unroll") for (int n = 0; n < 2; ++n) _Pragma("unroll") for (int k = 0; k < 2; ++k) \
;     acc[ai][bj][m][n] = __builtin_amdgcn_mfma_f32_16x16x32_bf16(Bt[n][k], At[m][k], acc[ai][bj][m][n], 0, 0, 0); __builtin_amdgcn_s_setprio(0); } while (0)
; #define PG8_WAIT_V(n) asm volatile("s_waitcnt vmcnt(" #n ")" ::: "memory")
; #define PG8_WAIT_L(n) asm volatile("s_waitcnt lgkmcnt(" #n ")" ::: "memory")
; #define PG8_BAR __builtin_amdgcn_s_barrier()
; #define PG8_SCHED __builtin_amdgcn_sched_barrier(0)
; template <class Epi, class Sched>
; DI void gemm_phase(LAS unsigned char* lds, const int tid, const Gemm g, const Sched& S, const Epi& E) {
;     ...
;       PG8_WAIT_V(6); PG8_BAR; PG8_MMA(1, 1, At, B1); PG8_BAR;
;       PG8_LDB(B0, 1, 0); PG8_SCHED; PG8_LDA(At, 1, 0); PG8_STAGE(PG8_SA(0, 1), a2 + hstepA, voffA);
;       PG8_WAIT_L(8); PG8_BAR; PG8_WAIT_L(0); PG8_MMA(0, 0, At, B0); PG8_BAR; PG8_SCHED;
;       PG8_LDB(B1, 1, 1); PG8_STAGE(PG8_SB(1, 0), b3, voffB);
;       PG8_BAR; PG8_WAIT_L(0); PG8_MMA(0, 1, At, B1); PG8_BAR;
;       PG8_LDA(At, 1, 1); PG8_STAGE(PG8_SA(1, 0), a3, voffA);
;       PG8_BAR; PG8_WAIT_L(0); PG8_MMA(1, 0, At, B0); PG8_BAR; PG8_SCHED;
	s_setprio 1
	v_mfma_f32_16x16x32_bf16 v[46:49], v[210:213], v[160:163], v[46:49]
	v_mfma_f32_16x16x32_bf16 v[42:45], v[238:241], v[160:163], v[42:45]
	v_mfma_f32_16x16x32_bf16 v[30:33], v[210:213], v[168:171], v[30:33]
	v_mfma_f32_16x16x32_bf16 v[26:29], v[238:241], v[168:171], v[26:29]
	v_mfma_f32_16x16x32_bf16 v[14:17], v[210:213], v[176:179], v[14:17]
	v_mfma_f32_16x16x32_bf16 v[10:13], v[238:241], v[176:179], v[10:13]
	v_mfma_f32_16x16x32_bf16 v[6:9], v[210:213], v[202:205], v[6:9]
	v_mfma_f32_16x16x32_bf16 v[2:5], v[238:241], v[202:205], v[2:5]
	v_mfma_f32_16x16x32_bf16 v[46:49], v[226:229], v[164:167], v[46:49]
	v_mfma_f32_16x16x32_bf16 v[42:45], v[242:245], v[164:167], v[42:45]
	v_mfma_f32_16x16x32_bf16 v[30:33], v[226:229], v[172:175], v[30:33]
	v_mfma_f32_16x16x32_bf16 v[26:29], v[242:245], v[172:175], v[26:29]
	v_mfma_f32_16x16x32_bf16 v[14:17], v[226:229], v[180:183], v[14:17]
	v_mfma_f32_16x16x32_bf16 v[10:13], v[242:245], v[180:183], v[10:13]
	v_mfma_f32_16x16x32_bf16 v[6:9], v[226:229], v[206:209], v[6:9]
	v_mfma_f32_16x16x32_bf16 v[2:5], v[242:245], v[206:209], v[2:5]
	s_setprio 0
	s_add_i32 s40, 0, 0x18000
	v_add_u32_e32 v0, s40, v142
	s_barrier
	ds_read_b128 v[144:147], v0
	ds_read_b128 v[148:151], v0 offset:1024
	ds_read_b128 v[152:155], v0 offset:2048
	ds_read_b128 v[156:159], v0 offset:3072
	s_add_u32 s16, s16, 0x20000
	s_addc_u32 s17, s17, 0
	s_mov_b32 m0, s24
	ds_read_b128 v[160:163], v143 offset:32768
	ds_read_b128 v[164:167], v143 offset:33792
	ds_read_b128 v[168:171], v143 offset:34816
	ds_read_b128 v[172:175], v143 offset:35840
	ds_read_b128 v[176:179], v143 offset:36864
	ds_read_b128 v[180:183], v143 offset:37888
	ds_read_b128 v[202:205], v143 offset:38912
	ds_read_b128 v[206:209], v143 offset:39936
	global_load_lds_dwordx4 v136, s[16:17]
	s_mov_b32 m0, s25
	s_nop 0
	global_load_lds_dwordx4 v132, s[16:17]
	s_waitcnt lgkmcnt(8)
	s_barrier
	s_waitcnt lgkmcnt(0)
	s_setprio 1
	s_waitcnt lgkmcnt(0)
	v_mfma_f32_16x16x32_bf16 v[126:129], v[144:147], v[160:163], v[126:129]
	v_mfma_f32_16x16x32_bf16 v[122:125], v[152:155], v[160:163], v[122:125]
	v_mfma_f32_16x16x32_bf16 v[118:121], v[144:147], v[168:171], v[118:121]
	v_mfma_f32_16x16x32_bf16 v[114:117], v[152:155], v[168:171], v[114:117]
	v_mfma_f32_16x16x32_bf16 v[102:105], v[144:147], v[176:179], v[102:105]
	v_mfma_f32_16x16x32_bf16 v[98:101], v[152:155], v[176:179], v[98:101]
	v_mfma_f32_16x16x32_bf16 v[86:89], v[144:147], v[202:205], v[86:89]
	v_mfma_f32_16x16x32_bf16 v[82:85], v[152:155], v[202:205], v[82:85]
	v_mfma_f32_16x16x32_bf16 v[126:129], v[148:151], v[164:167], v[126:129]
	v_mfma_f32_16x16x32_bf16 v[122:125], v[156:159], v[164:167], v[122:125]
	v_mfma_f32_16x16x32_bf16 v[118:121], v[148:151], v[172:175], v[118:121]
	v_mfma_f32_16x16x32_bf16 v[114:117], v[156:159], v[172:175], v[114:117]
	v_mfma_f32_16x16x32_bf16 v[102:105], v[148:151], v[180:183], v[102:105]
	v_mfma_f32_16x16x32_bf16 v[98:101], v[156:159], v[180:183], v[98:101]
	v_mfma_f32_16x16x32_bf16 v[86:89], v[148:151], v[206:209], v[86:89]
	v_mfma_f32_16x16x32_bf16 v[82:85], v[156:159], v[206:209], v[82:85]
	s_setprio 0
	s_barrier
	s_add_i32 s16, 0, 0x1c000
	s_add_i32 s17, s40, s21
	v_add_u32_e32 v0, s16, v142
	s_mov_b32 m0, s17
	ds_read_b128 v[210:213], v0
	ds_read_b128 v[226:229], v0 offset:1024
	ds_read_b128 v[238:241], v0 offset:2048
	ds_read_b128 v[242:245], v0 offset:3072
	global_load_lds_dwordx4 v134, s[98:99]
	s_add_i32 m0, s17, 0x2000
	s_nop 0
	global_load_lds_dwordx4 v130, s[98:99]
	s_barrier
	s_waitcnt lgkmcnt(0)
	s_setprio 1
	s_waitcnt lgkmcnt(0)
	v_mfma_f32_16x16x32_bf16 v[110:113], v[210:213], v[160:163], v[110:113]
	v_mfma_f32_16x16x32_bf16 v[106:109], v[238:241], v[160:163], v[106:109]
	v_mfma_f32_16x16x32_bf16 v[94:97], v[210:213], v[168:171], v[94:97]
	v_mfma_f32_16x16x32_bf16 v[90:93], v[238:241], v[168:171], v[90:93]
	v_mfma_f32_16x16x32_bf16 v[78:81], v[210:213], v[176:179], v[78:81]
	v_mfma_f32_16x16x32_bf16 v[74:77], v[238:241], v[176:179], v[74:77]
	v_mfma_f32_16x16x32_bf16 v[70:73], v[210:213], v[202:205], v[70:73]
	v_mfma_f32_16x16x32_bf16 v[66:69], v[238:241], v[202:205], v[66:69]
	v_mfma_f32_16x16x32_bf16 v[110:113], v[226:229], v[164:167], v[110:113]
	v_mfma_f32_16x16x32_bf16 v[106:109], v[242:245], v[164:167], v[106:109]
	v_mfma_f32_16x16x32_bf16 v[94:97], v[226:229], v[172:175], v[94:97]
	v_mfma_f32_16x16x32_bf16 v[90:93], v[242:245], v[172:175], v[90:93]
	v_mfma_f32_16x16x32_bf16 v[78:81], v[226:229], v[180:183], v[78:81]
	v_mfma_f32_16x16x32_bf16 v[74:77], v[242:245], v[180:183], v[74:77]
	v_mfma_f32_16x16x32_bf16 v[70:73], v[226:229], v[206:209], v[70:73]
	v_mfma_f32_16x16x32_bf16 v[66:69], v[242:245], v[206:209], v[66:69]
	s_setprio 0
	s_mov_b32 m0, s28
	s_barrier
	ds_read_b128 v[160:163], v143 offset:49152
	ds_read_b128 v[164:167], v143 offset:50176
	ds_read_b128 v[168:171], v143 offset:51200
	ds_read_b128 v[172:175], v143 offset:52224
	ds_read_b128 v[176:179], v143 offset:53248
	ds_read_b128 v[180:183], v143 offset:54272
	ds_read_b128 v[202:205], v143 offset:55296
	ds_read_b128 v[206:209], v143 offset:56320
	global_load_lds_dwordx4 v136, s[100:101]
	s_mov_b32 m0, s29
	s_nop 0
	global_load_lds_dwordx4 v132, s[100:101]
	s_barrier
; #define PG8_STAGE(bufoff, gbase, voff) do { _Pragma("unroll") for (int _i = 0; _i < 2; ++_i) \
;     __builtin_amdgcn_global_load_lds((const unsigned*)((const char*)(gbase) + (voff)[_i]), (LAS unsigned*)(lds + (bufoff) + ldsw + _i * 8192), 16, 0, 0); } while (0)
; #define PG8_MMA(ai, bj, At, Bt) do { __builtin_amdgcn_s_setprio(1); _Pragma("unroll") for (int m = 0; m < 4; ++m) _Pragma("unroll") for (int n = 0; n < 2; ++n) _Pragma("unroll") for (int k = 0; k < 2; ++k) \
;     acc[ai][bj][m][n] = __builtin_amdgcn_mfma_f32_16x16x32_bf16(Bt[n][k], At[m][k], acc[ai][bj][m][n], 0, 0, 0); __builtin_amdgcn_s_setprio(0); } while (0)
; #define PG8_WAIT_V(n) asm volatile("s_waitcnt vmcnt(" #n ")" ::: "memory")
; #define PG8_WAIT_L(n) asm volatile("s_waitcnt lgkmcnt(" #n ")" ::: "memory")
; #define PG8_BAR __builtin_amdgcn_s_barrier()
; #define PG8_SCHED __builtin_amdgcn_sched_barrier(0)
; template <class Epi, class Sched>
; DI void gemm_phase(LAS unsigned char* lds, const int tid, const Gemm g, const Sched& S, const Epi& E) {
;     ...
;       PG8_BAR; PG8_WAIT_L(0); PG8_MMA(1, 0, At, B0); PG8_BAR; PG8_SCHED;
;       PG8_STAGE(PG8_SB(1, 1), b3 + hstepB, voffB);
;       PG8_WAIT_V(6); PG8_BAR; PG8_MMA(1, 1, At, B1); PG8_BAR;
	s_waitcnt lgkmcnt(0)
	s_setprio 1
	s_waitcnt lgkmcnt(0)
	v_mfma_f32_16x16x32_bf16 v[62:65], v[144:147], v[160:163], v[62:65]
	v_mfma_f32_16x16x32_bf16 v[58:61], v[152:155], v[160:163], v[58:61]
	v_mfma_f32_16x16x32_bf16 v[54:57], v[144:147], v[168:171], v[54:57]
	v_mfma_f32_16x16x32_bf16 v[50:53], v[152:155], v[168:171], v[50:53]
	v_mfma_f32_16x16x32_bf16 v[38:41], v[144:147], v[176:179], v[38:41]
	v_mfma_f32_16x16x32_bf16 v[34:37], v[152:155], v[176:179], v[34:37]
	v_mfma_f32_16x16x32_bf16 v[22:25], v[144:147], v[202:205], v[22:25]
	v_mfma_f32_16x16x32_bf16 v[18:21], v[152:155], v[202:205], v[18:21]
	v_mfma_f32_16x16x32_bf16 v[62:65], v[148:151], v[164:167], v[62:65]
	v_mfma_f32_16x16x32_bf16 v[58:61], v[156:159], v[164:167], v[58:61]
	v_mfma_f32_16x16x32_bf16 v[54:57], v[148:151], v[172:175], v[54:57]
	v_mfma_f32_16x16x32_bf16 v[50:53], v[156:159], v[172:175], v[50:53]
	v_mfma_f32_16x16x32_bf16 v[38:41], v[148:151], v[180:183], v[38:41]
	v_mfma_f32_16x16x32_bf16 v[34:37], v[156:159], v[180:183], v[34:37]
	v_mfma_f32_16x16x32_bf16 v[22:25], v[148:151], v[206:209], v[22:25]
	v_mfma_f32_16x16x32_bf16 v[18:21], v[156:159], v[206:209], v[18:21]
	s_setprio 0
	s_barrier
	s_add_u32 s14, s14, 0x20080
	s_addc_u32 s15, s15, 0
	s_add_i32 s16, s16, s21
	s_mov_b32 m0, s16
	s_nop 0
	global_load_lds_dwordx4 v134, s[14:15]
	s_add_i32 m0, s16, 0x2000
	s_nop 0
	global_load_lds_dwordx4 v130, s[14:15]
	s_waitcnt vmcnt(6)
	s_barrier
	s_setprio 1
	v_mfma_f32_16x16x32_bf16 v[46:49], v[210:213], v[160:163], v[46:49]
	v_mfma_f32_16x16x32_bf16 v[42:45], v[238:241], v[160:163], v[42:45]
	v_mfma_f32_16x16x32_bf16 v[30:33], v[210:213], v[168:171], v[30:33]
	v_mfma_f32_16x16x32_bf16 v[26:29], v[238:241], v[168:171], v[26:29]
	v_mfma_f32_16x16x32_bf16 v[14:17], v[210:213], v[176:179], v[14:17]
	v_mfma_f32_16x16x32_bf16 v[10:13], v[238:241], v[176:179], v[10:13]
	v_mfma_f32_16x16x32_bf16 v[6:9], v[210:213], v[202:205], v[6:9]
	v_mfma_f32_16x16x32_bf16 v[2:5], v[238:241], v[202:205], v[2:5]
	v_mfma_f32_16x16x32_bf16 v[46:49], v[226:229], v[164:167], v[46:49]
	v_mfma_f32_16x16x32_bf16 v[42:45], v[242:245], v[164:167], v[42:45]
	v_mfma_f32_16x16x32_bf16 v[30:33], v[226:229], v[172:175], v[30:33]
	v_mfma_f32_16x16x32_bf16 v[26:29], v[242:245], v[172:175], v[26:29]
	v_mfma_f32_16x16x32_bf16 v[14:17], v[226:229], v[180:183], v[14:17]
	v_mfma_f32_16x16x32_bf16 v[10:13], v[242:245], v[180:183], v[10:13]
	v_mfma_f32_16x16x32_bf16 v[6:9], v[226:229], v[206:209], v[6:9]
	v_mfma_f32_16x16x32_bf16 v[2:5], v[242:245], v[206:209], v[2:5]
	s_setprio 0
	s_add_i32 s39, s39, 2
	s_add_u32 s37, s37, 0x100
	s_addc_u32 s38, s38, 0
	s_add_u32 s12, s12, 0x100
	s_addc_u32 s13, s13, 0
	s_cmp_gt_u32 s39, 5
	s_barrier
	s_cbranch_scc0 .LBB0_645
; DI void st8p(void* ub, unsigned voff, f32x4 a, f32x4 b) { u32x4 o = {pk(a[0], a[1]), pk(a[2], a[3]), pk(b[0], b[1]), pk(b[2], b[3])}; *(GAS u32x4*)((char*)ub + voff) = o; }
; #define ROWS_LOOP _Pragma("unroll") for (int ai = 0; ai < 2; ++ai) _Pragma("unroll") for (int m = 0; m < 4; ++m)
;   DI void operator()(const AccT& acc, const Unit& u, int wr, int wc, int fr, int fq) const {
;     const char* base = (const char*)(MIX + (ctx ? (size_t)(TL + u.pn * 256) : (size_t)(u.pn * 2048 + u.pm * 256)) * D);
;     const unsigned o0 = (unsigned)((wr * 64 + fr) * D + wc * 32 + fq * 8) * 2u;
;     ROWS_LOOP {
;       char* rb = (char*)base + (size_t)(ai * 128 + m * 16) * D * 2;
; #pragma unroll
;       for (int bj = 0; bj < 2; ++bj) st8p(rb + bj * 256, o0, acc[ai][bj][m][0], acc[ai][bj][m][1]);
;     }
;   }
	v_mov_b32_e32 v0, v1
	s_lshl_b32 s12, s34, 8
	v_mbcnt_lo_u32_b32 v0, -1, v0
	v_mbcnt_hi_u32_b32 v0, -1, v0
	s_ashr_i32 s13, s12, 31
	s_lshl_b64 s[12:13], s[12:13], 11
	v_lshlrev_b32_e32 v144, 11, v0
	s_add_u32 s12, s26, s12
	v_and_b32_e32 v144, 0x7800, v144
	v_and_b32_e32 v0, -16, v0
	s_addc_u32 s13, s27, s13
	v_add3_u32 v0, s30, v0, v144
	v_lshl_add_u64 v[144:145], s[12:13], 0, v[0:1]
	s_brev_b32 s5, 32
	s_mov_b64 s[12:13], 0x4000000
	v_cvt_pk_bf16_f32 v126, v126, v127
	v_cvt_pk_bf16_f32 v127, v128, v129
	v_cvt_pk_bf16_f32 v128, v122, v123
	v_add_co_u32_e32 v122, vcc, s5, v144
	v_lshl_add_u64 v[146:147], v[144:145], 0, s[12:13]
	s_nop 0
	v_addc_co_u32_e32 v123, vcc, 0, v145, vcc
	v_cvt_pk_bf16_f32 v110, v110, v111
	v_cvt_pk_bf16_f32 v111, v112, v113
	v_cvt_pk_bf16_f32 v112, v106, v107
	v_cvt_pk_bf16_f32 v113, v108, v109
	s_mov_b32 s5, 0x4008000
	global_store_dwordx4 v[146:147], v[110:113], off offset:256
	v_cvt_pk_bf16_f32 v94, v94, v95
	v_cvt_pk_bf16_f32 v95, v96, v97
	v_add_co_u32_e32 v110, vcc, s5, v144
	v_cvt_pk_bf16_f32 v96, v90, v91
	s_nop 0
	v_addc_co_u32_e32 v111, vcc, 0, v145, vcc
	v_cvt_pk_bf16_f32 v97, v92, v93
	s_mov_b32 s5, 0x4010000
	global_store_dwordx4 v[110:111], v[94:97], off offset:256
	v_cvt_pk_bf16_f32 v78, v78, v79
	v_cvt_pk_bf16_f32 v79, v80, v81
	v_add_co_u32_e32 v94, vcc, s5, v144
	v_cvt_pk_bf16_f32 v80, v74, v75
	s_nop 0
	v_addc_co_u32_e32 v95, vcc, 0, v145, vcc
	v_cvt_pk_bf16_f32 v81, v76, v77
	s_mov_b32 s5, 0x4018000
	global_store_dwordx4 v[94:95], v[78:81], off offset:256
	v_cvt_pk_bf16_f32 v62, v62, v63
	v_cvt_pk_bf16_f32 v63, v64, v65
	v_add_co_u32_e32 v78, vcc, s5, v144
	s_mov_b32 s5, 0x4040000
	s_nop 0
	v_addc_co_u32_e32 v79, vcc, 0, v145, vcc
	v_cvt_pk_bf16_f32 v64, v58, v59
	v_add_co_u32_e32 v58, vcc, s5, v144
	v_cvt_pk_bf16_f32 v46, v46, v47
	s_nop 0
	v_addc_co_u32_e32 v59, vcc, 0, v145, vcc
	v_cvt_pk_bf16_f32 v47, v48, v49
	v_cvt_pk_bf16_f32 v48, v42, v43
	v_cvt_pk_bf16_f32 v49, v44, v45
	s_mov_b32 s5, 0x4048000
	global_store_dwordx4 v[58:59], v[46:49], off offset:256
	v_cvt_pk_bf16_f32 v30, v30, v31
	v_cvt_pk_bf16_f32 v31, v32, v33
	v_add_co_u32_e32 v46, vcc, s5, v144
	v_cvt_pk_bf16_f32 v32, v26, v27
	s_nop 0
	v_addc_co_u32_e32 v47, vcc, 0, v145, vcc
	v_cvt_pk_bf16_f32 v33, v28, v29
	s_mov_b32 s5, 0x4050000
	global_store_dwordx4 v[46:47], v[30:33], off offset:256
	v_cvt_pk_bf16_f32 v14, v14, v15
	v_cvt_pk_bf16_f32 v15, v16, v17
	v_add_co_u32_e32 v30, vcc, s5, v144
	v_cvt_pk_bf16_f32 v16, v10, v11
	s_nop 0
	v_addc_co_u32_e32 v31, vcc, 0, v145, vcc
	v_cvt_pk_bf16_f32 v17, v12, v13
	s_mov_b32 s5, 0x4058000
	global_store_dwordx4 v[30:31], v[14:17], off offset:256
	v_cvt_pk_bf16_f32 v129, v124, v125
	v_cvt_pk_bf16_f32 v106, v118, v119
	v_add_co_u32_e32 v14, vcc, s5, v144
	v_cvt_pk_bf16_f32 v107, v120, v121
	s_nop 0
	v_addc_co_u32_e32 v15, vcc, 0, v145, vcc
	v_cvt_pk_bf16_f32 v108, v114, v115
	v_cvt_pk_bf16_f32 v109, v116, v117
	v_cvt_pk_bf16_f32 v90, v102, v103
	v_cvt_pk_bf16_f32 v91, v104, v105
	v_cvt_pk_bf16_f32 v92, v98, v99
	v_cvt_pk_bf16_f32 v93, v100, v101
	v_cvt_pk_bf16_f32 v74, v86, v87
	v_cvt_pk_bf16_f32 v75, v88, v89
	v_cvt_pk_bf16_f32 v76, v82, v83
	v_cvt_pk_bf16_f32 v77, v84, v85
	v_cvt_pk_bf16_f32 v70, v70, v71
	v_cvt_pk_bf16_f32 v71, v72, v73
	v_cvt_pk_bf16_f32 v72, v66, v67
	v_cvt_pk_bf16_f32 v73, v68, v69
	v_cvt_pk_bf16_f32 v65, v60, v61
	v_cvt_pk_bf16_f32 v42, v54, v55
	v_cvt_pk_bf16_f32 v43, v56, v57
	v_cvt_pk_bf16_f32 v44, v50, v51
	v_cvt_pk_bf16_f32 v45, v52, v53
	v_cvt_pk_bf16_f32 v26, v38, v39
	v_cvt_pk_bf16_f32 v27, v40, v41
	v_cvt_pk_bf16_f32 v28, v34, v35
	v_cvt_pk_bf16_f32 v29, v36, v37
	v_cvt_pk_bf16_f32 v10, v22, v23
	v_cvt_pk_bf16_f32 v11, v24, v25
	v_cvt_pk_bf16_f32 v12, v18, v19
	v_cvt_pk_bf16_f32 v13, v20, v21
	v_cvt_pk_bf16_f32 v6, v6, v7
	v_cvt_pk_bf16_f32 v7, v8, v9
	v_cvt_pk_bf16_f32 v8, v2, v3
	v_cvt_pk_bf16_f32 v9, v4, v5
	s_and_b64 vcc, exec, s[0:1]
	s_mov_b32 s34, s4
	s_mov_b64 s[12:13], s[10:11]
	s_mov_b64 s[16:17], s[8:9]
	global_store_dwordx4 v[122:123], v[126:129], off
	global_store_dwordx4 v[110:111], v[106:109], off
	global_store_dwordx4 v[94:95], v[90:93], off
	global_store_dwordx4 v[78:79], v[74:77], off
	global_store_dwordx4 v[78:79], v[70:73], off offset:256
	global_store_dwordx4 v[58:59], v[62:65], off
	global_store_dwordx4 v[46:47], v[42:45], off
	global_store_dwordx4 v[30:31], v[26:29], off
	global_store_dwordx4 v[14:15], v[10:13], off
	global_store_dwordx4 v[14:15], v[6:9], off offset:256
	s_cbranch_vccz .LBB0_642
	s_waitcnt vmcnt(0)
	s_cmpk_gt_u32 s2, 0xff
	s_cbranch_scc1 .LBB0_649
	s_barrier

; #define PG8_STAGE(bufoff, gbase, voff) do { _Pragma("unroll") for (int _i = 0; _i < 2; ++_i) \
;     __builtin_amdgcn_global_load_lds((const unsigned*)((const char*)(gbase) + (voff)[_i]), (LAS unsigned*)(lds + (bufoff) + ldsw + _i * 8192), 16, 0, 0); } while (0)
; #define PG8_LDA(dst, b, h) do { _Pragma("unroll") for (int m = 0; m < 4; ++m) _Pragma("unroll") for (int k = 0; k < 2; ++k) dst[m][k] = *(const LAS bf16x8*)(lds + PG8_SA(b, h) + aoff + m * 2048 + k * 1024); } while (0)
; #define PG8_LDB(dst, b, h) do { _Pragma("unroll") for (int n = 0; n < 2; ++n) _Pragma("unroll") for (int k = 0; k < 2; ++k) dst[n][k] = *(const LAS bf16x8*)(lds + PG8_SB(b, h) + boff + n * 2048 + k * 1024); } while (0)
; #define PG8_MMA(ai, bj, At, Bt) do { __builtin_amdgcn_s_setprio(1); _Pragma("unroll") for (int m = 0; m < 4; ++m) _Pragma("unroll") for (int n = 0; n < 2; ++n) _Pragma("unroll") for (int k = 0; k < 2; ++k) \
;     acc[ai][bj][m][n] = __builtin_amdgcn_mfma_f32_16x16x32_bf16(Bt[n][k], At[m][k], acc[ai][bj][m][n], 0, 0, 0); __builtin_amdgcn_s_setprio(0); } while (0)
; #define PG8_WAIT_V(n) asm volatile("s_waitcnt vmcnt(" #n ")" ::: "memory")
; #define PG8_WAIT_L(n) asm volatile("s_waitcnt lgkmcnt(" #n ")" ::: "memory")
; #define PG8_BAR __builtin_amdgcn_s_barrier()
; #define PG8_SCHED __builtin_amdgcn_sched_barrier(0)
; template <class Epi, class Sched>
; DI void gemm_phase(LAS unsigned char* lds, const int tid, const Gemm g, const Sched& S, const Epi& E) {
;     ...
;       const bool last = (t == nt - 2);
;       const char* a1 = cA + (size_t)(t + 1) * kstep;
;       const char* a2 = last ? nA : cA + (size_t)(t + 2) * kstep; const char* b2 = last ? nB : cB + (size_t)(t + 2) * kstep;
;       const char* a3 = a2 + kstep; const char* b3 = b2 + kstep;
;       PG8_LDB(B0, 0, 0); PG8_SCHED; PG8_LDA(At, 0, 0); PG8_STAGE(PG8_SA(1, 1), a1 + hstepA, voffA);
;       PG8_WAIT_L(8); PG8_BAR; PG8_WAIT_L(0); PG8_MMA(0, 0, At, B0); PG8_BAR; PG8_SCHED;
;       PG8_LDB(B1, 0, 1); PG8_STAGE(PG8_SB(0, 0), b2, voffB);
;       PG8_BAR; PG8_WAIT_L(0); PG8_MMA(0, 1, At, B1); PG8_BAR;
;       PG8_LDA(At, 0, 1); PG8_STAGE(PG8_SA(0, 0), a2, voffA);
;       PG8_BAR; PG8_WAIT_L(0); PG8_MMA(1, 0, At, B0); PG8_BAR; PG8_SCHED;
;       PG8_STAGE(PG8_SB(0, 1), b2 + hstepB, voffB);
;       PG8_WAIT_V(6); PG8_BAR; PG8_MMA(1, 1, At, B1); PG8_BAR;
.LBB0_659:
	s_add_u32 s14, s12, 0xfff00080
	s_addc_u32 s15, s13, -1
	s_add_i32 s41, 0, 0x10000
	v_add_u32_e32 v0, s41, v142
	ds_read_b128 v[144:147], v0
	ds_read_b128 v[148:151], v0 offset:1024
	ds_read_b128 v[152:155], v0 offset:2048
	ds_read_b128 v[156:159], v0 offset:3072
	s_cmp_eq_u32 s40, 60
	s_cselect_b32 s17, s7, s15
	s_cselect_b32 s16, s36, s14
	s_cselect_b32 s15, s1, s39
	s_cselect_b32 s14, s37, s38
	s_add_i32 m0, s22, 0xc000
	ds_read_b128 v[160:163], v143
	ds_read_b128 v[164:167], v143 offset:1024
	ds_read_b128 v[168:171], v143 offset:2048
	ds_read_b128 v[172:175], v143 offset:3072
	ds_read_b128 v[176:179], v143 offset:4096
	ds_read_b128 v[180:183], v143 offset:5120
	ds_read_b128 v[202:205], v143 offset:6144
	ds_read_b128 v[206:209], v143 offset:7168
	global_load_lds_dwordx4 v140, s[12:13]
	s_add_i32 m0, s22, 0xe000
	s_nop 0
	global_load_lds_dwordx4 v138, s[12:13]
	s_waitcnt lgkmcnt(8)
	s_barrier
	s_waitcnt lgkmcnt(0)
	s_setprio 1
	s_waitcnt lgkmcnt(0)
	v_mfma_f32_16x16x32_bf16 v[126:129], v[144:147], v[160:163], v[126:129]
	v_mfma_f32_16x16x32_bf16 v[122:125], v[152:155], v[160:163], v[122:125]
	v_mfma_f32_16x16x32_bf16 v[118:121], v[144:147], v[168:171], v[118:121]
	v_mfma_f32_16x16x32_bf16 v[114:117], v[152:155], v[168:171], v[114:117]
	v_mfma_f32_16x16x32_bf16 v[102:105], v[144:147], v[176:179], v[102:105]
	v_mfma_f32_16x16x32_bf16 v[98:101], v[152:155], v[176:179], v[98:101]
	v_mfma_f32_16x16x32_bf16 v[86:89], v[144:147], v[202:205], v[86:89]
	v_mfma_f32_16x16x32_bf16 v[82:85], v[152:155], v[202:205], v[82:85]
	v_mfma_f32_16x16x32_bf16 v[126:129], v[148:151], v[164:167], v[126:129]
	v_mfma_f32_16x16x32_bf16 v[122:125], v[156:159], v[164:167], v[122:125]
	v_mfma_f32_16x16x32_bf16 v[118:121], v[148:151], v[172:175], v[118:121]
	v_mfma_f32_16x16x32_bf16 v[114:117], v[156:159], v[172:175], v[114:117]
	v_mfma_f32_16x16x32_bf16 v[102:105], v[148:151], v[180:183], v[102:105]
	v_mfma_f32_16x16x32_bf16 v[98:101], v[156:159], v[180:183], v[98:101]
	v_mfma_f32_16x16x32_bf16 v[86:89], v[148:151], v[206:209], v[86:89]
	v_mfma_f32_16x16x32_bf16 v[82:85], v[156:159], v[206:209], v[82:85]
	s_setprio 0
	s_barrier
	s_add_i32 s44, 0, 0x14000
	s_add_i32 s41, s41, s21
	v_add_u32_e32 v0, s44, v142
	s_add_u32 s98, s14, s50
	s_addc_u32 s99, s15, s51
	s_mov_b32 m0, s41
	ds_read_b128 v[210:213], v0
	ds_read_b128 v[226:229], v0 offset:1024
	ds_read_b128 v[238:241], v0 offset:2048
	ds_read_b128 v[242:245], v0 offset:3072
	global_load_lds_dwordx4 v134, s[14:15]
	s_add_i32 m0, s41, 0x2000
	s_nop 0
	global_load_lds_dwordx4 v130, s[14:15]
	s_barrier
	s_waitcnt lgkmcnt(0)
	s_setprio 1
	s_waitcnt lgkmcnt(0)
	v_mfma_f32_16x16x32_bf16 v[110:113], v[210:213], v[160:163], v[110:113]
	v_mfma_f32_16x16x32_bf16 v[106:109], v[238:241], v[160:163], v[106:109]
	v_mfma_f32_16x16x32_bf16 v[94:97], v[210:213], v[168:171], v[94:97]
	v_mfma_f32_16x16x32_bf16 v[90:93], v[238:241], v[168:171], v[90:93]
	v_mfma_f32_16x16x32_bf16 v[78:81], v[210:213], v[176:179], v[78:81]
	v_mfma_f32_16x16x32_bf16 v[74:77], v[238:241], v[176:179], v[74:77]
	v_mfma_f32_16x16x32_bf16 v[70:73], v[210:213], v[202:205], v[70:73]
	v_mfma_f32_16x16x32_bf16 v[66:69], v[238:241], v[202:205], v[66:69]
	v_mfma_f32_16x16x32_bf16 v[110:113], v[226:229], v[164:167], v[110:113]
	v_mfma_f32_16x16x32_bf16 v[106:109], v[242:245], v[164:167], v[106:109]
	v_mfma_f32_16x16x32_bf16 v[94:97], v[226:229], v[172:175], v[94:97]
	v_mfma_f32_16x16x32_bf16 v[90:93], v[242:245], v[172:175], v[90:93]
	v_mfma_f32_16x16x32_bf16 v[78:81], v[226:229], v[180:183], v[78:81]
	v_mfma_f32_16x16x32_bf16 v[74:77], v[242:245], v[180:183], v[74:77]
	v_mfma_f32_16x16x32_bf16 v[70:73], v[226:229], v[206:209], v[70:73]
	v_mfma_f32_16x16x32_bf16 v[66:69], v[242:245], v[206:209], v[66:69]
	s_setprio 0
	s_mov_b32 m0, s22
	s_add_u32 s100, s16, s50
	s_addc_u32 s101, s17, s51
	s_barrier
	ds_read_b128 v[160:163], v143 offset:16384
	ds_read_b128 v[164:167], v143 offset:17408
	ds_read_b128 v[168:171], v143 offset:18432
	ds_read_b128 v[172:175], v143 offset:19456
	ds_read_b128 v[176:179], v143 offset:20480
	ds_read_b128 v[180:183], v143 offset:21504
	ds_read_b128 v[202:205], v143 offset:22528
	ds_read_b128 v[206:209], v143 offset:23552
	global_load_lds_dwordx4 v136, s[16:17]
	s_mov_b32 m0, s23
	s_nop 0
	global_load_lds_dwordx4 v132, s[16:17]
	s_barrier
	s_waitcnt lgkmcnt(0)
	s_setprio 1
	s_waitcnt lgkmcnt(0)
	v_mfma_f32_16x16x32_bf16 v[62:65], v[144:147], v[160:163], v[62:65]
	v_mfma_f32_16x16x32_bf16 v[58:61], v[152:155], v[160:163], v[58:61]
	v_mfma_f32_16x16x32_bf16 v[54:57], v[144:147], v[168:171], v[54:57]
	v_mfma_f32_16x16x32_bf16 v[50:53], v[152:155], v[168:171], v[50:53]
	v_mfma_f32_16x16x32_bf16 v[38:41], v[144:147], v[176:179], v[38:41]
	v_mfma_f32_16x16x32_bf16 v[34:37], v[152:155], v[176:179], v[34:37]
	v_mfma_f32_16x16x32_bf16 v[22:25], v[144:147], v[202:205], v[22:25]
	v_mfma_f32_16x16x32_bf16 v[18:21], v[152:155], v[202:205], v[18:21]
	v_mfma_f32_16x16x32_bf16 v[62:65], v[148:151], v[164:167], v[62:65]
	v_mfma_f32_16x16x32_bf16 v[58:61], v[156:159], v[164:167], v[58:61]
	v_mfma_f32_16x16x32_bf16 v[54:57], v[148:151], v[172:175], v[54:57]
	v_mfma_f32_16x16x32_bf16 v[50:53], v[156:159], v[172:175], v[50:53]
	v_mfma_f32_16x16x32_bf16 v[38:41], v[148:151], v[180:183], v[38:41]
	v_mfma_f32_16x16x32_bf16 v[34:37], v[156:159], v[180:183], v[34:37]
	v_mfma_f32_16x16x32_bf16 v[22:25], v[148:151], v[206:209], v[22:25]
	v_mfma_f32_16x16x32_bf16 v[18:21], v[156:159], v[206:209], v[18:21]
	s_setprio 0
	s_barrier
	s_add_u32 s42, s14, 0x100000
	s_addc_u32 s43, s15, 0
	s_add_i32 s41, s44, s21
	s_mov_b32 m0, s41
	s_nop 0
	global_load_lds_dwordx4 v134, s[42:43]
	s_add_i32 m0, s41, 0x2000
	s_nop 0
	global_load_lds_dwordx4 v130, s[42:43]
	s_waitcnt vmcnt(6)
	s_barrier
; #define PG8_STAGE(bufoff, gbase, voff) do { _Pragma("unroll") for (int _i = 0; _i < 2; ++_i) \
;     __builtin_amdgcn_global_load_lds((const unsigned*)((const char*)(gbase) + (voff)[_i]), (LAS unsigned*)(lds + (bufoff) + ldsw + _i * 8192), 16, 0, 0); } while (0)
; #define PG8_LDA(dst, b, h) do { _Pragma("unroll") for (int m = 0; m < 4; ++m) _Pragma("unroll") for (int k = 0; k < 2; ++k) dst[m][k] = *(const LAS bf16x8*)(lds + PG8_SA(b, h) + aoff + m * 2048 + k * 1024); } while (0)
; #define PG8_LDB(dst, b, h) do { _Pragma("unroll") for (int n = 0; n < 2; ++n) _Pragma("unroll") for (int k = 0; k < 2; ++k) dst[n][k] = *(const LAS bf16x8*)(lds + PG8_SB(b, h) + boff + n * 2048 + k * 1024); } while (0)
; #define PG8_MMA(ai, bj, At, Bt) do { __builtin_amdgcn_s_setprio(1); _Pragma("unroll") for (int m = 0; m < 4; ++m) _Pragma("unroll") for (int n = 0; n < 2; ++n) _Pragma("unroll") for (int k = 0; k < 2; ++k) \
;     acc[ai][bj][m][n] = __builtin_amdgcn_mfma_f32_16x16x32_bf16(Bt[n][k], At[m][k], acc[ai][bj][m][n], 0, 0, 0); __builtin_amdgcn_s_setprio(0); } while (0)
; #define PG8_WAIT_V(n) asm volatile("s_waitcnt vmcnt(" #n ")" ::: "memory")
; #define PG8_WAIT_L(n) asm volatile("s_waitcnt lgkmcnt(" #n ")" ::: "memory")
; #define PG8_BAR __builtin_amdgcn_s_barrier()
; #define PG8_SCHED __builtin_amdgcn_sched_barrier(0)
; template <class Epi, class Sched>
; DI void gemm_phase(LAS unsigned char* lds, const int tid, const Gemm g, const Sched& S, const Epi& E) {
;     ...
;       PG8_WAIT_V(6); PG8_BAR; PG8_MMA(1, 1, At, B1); PG8_BAR;
;       PG8_LDB(B0, 1, 0); PG8_SCHED; PG8_LDA(At, 1, 0); PG8_STAGE(PG8_SA(0, 1), a2 + hstepA, voffA);
;       PG8_WAIT_L(8); PG8_BAR; PG8_WAIT_L(0); PG8_MMA(0, 0, At, B0); PG8_BAR; PG8_SCHED;
;       PG8_LDB(B1, 1, 1); PG8_STAGE(PG8_SB(1, 0), b3, voffB);
;       PG8_BAR; PG8_WAIT_L(0); PG8_MMA(0, 1, At, B1); PG8_BAR;
;       PG8_LDA(At, 1, 1); PG8_STAGE(PG8_SA(1, 0), a3, voffA);
;       PG8_BAR; PG8_WAIT_L(0); PG8_MMA(1, 0, At, B0); PG8_BAR; PG8_SCHED;
;       PG8_STAGE(PG8_SB(1, 1), b3 + hstepB, voffB);
;       PG8_WAIT_V(6); PG8_BAR; PG8_MMA(1, 1, At, B1); PG8_BAR;
	s_setprio 1
	v_mfma_f32_16x16x32_bf16 v[46:49], v[210:213], v[160:163], v[46:49]
	v_mfma_f32_16x16x32_bf16 v[42:45], v[238:241], v[160:163], v[42:45]
	v_mfma_f32_16x16x32_bf16 v[30:33], v[210:213], v[168:171], v[30:33]
	v_mfma_f32_16x16x32_bf16 v[26:29], v[238:241], v[168:171], v[26:29]
	v_mfma_f32_16x16x32_bf16 v[14:17], v[210:213], v[176:179], v[14:17]
	v_mfma_f32_16x16x32_bf16 v[10:13], v[238:241], v[176:179], v[10:13]
	v_mfma_f32_16x16x32_bf16 v[6:9], v[210:213], v[202:205], v[6:9]
	v_mfma_f32_16x16x32_bf16 v[2:5], v[238:241], v[202:205], v[2:5]
	v_mfma_f32_16x16x32_bf16 v[46:49], v[226:229], v[164:167], v[46:49]
	v_mfma_f32_16x16x32_bf16 v[42:45], v[242:245], v[164:167], v[42:45]
	v_mfma_f32_16x16x32_bf16 v[30:33], v[226:229], v[172:175], v[30:33]
	v_mfma_f32_16x16x32_bf16 v[26:29], v[242:245], v[172:175], v[26:29]
	v_mfma_f32_16x16x32_bf16 v[14:17], v[226:229], v[180:183], v[14:17]
	v_mfma_f32_16x16x32_bf16 v[10:13], v[242:245], v[180:183], v[10:13]
	v_mfma_f32_16x16x32_bf16 v[6:9], v[226:229], v[206:209], v[6:9]
	v_mfma_f32_16x16x32_bf16 v[2:5], v[242:245], v[206:209], v[2:5]
	s_setprio 0
	s_add_i32 s41, 0, 0x18000
	v_add_u32_e32 v0, s41, v142
	s_barrier
	ds_read_b128 v[144:147], v0
	ds_read_b128 v[148:151], v0 offset:1024
	ds_read_b128 v[152:155], v0 offset:2048
	ds_read_b128 v[156:159], v0 offset:3072
	s_add_u32 s16, s16, 0x100000
	s_addc_u32 s17, s17, 0
	s_mov_b32 m0, s24
	ds_read_b128 v[160:163], v143 offset:32768
	ds_read_b128 v[164:167], v143 offset:33792
	ds_read_b128 v[168:171], v143 offset:34816
	ds_read_b128 v[172:175], v143 offset:35840
	ds_read_b128 v[176:179], v143 offset:36864
	ds_read_b128 v[180:183], v143 offset:37888
	ds_read_b128 v[202:205], v143 offset:38912
	ds_read_b128 v[206:209], v143 offset:39936
	global_load_lds_dwordx4 v136, s[16:17]
	s_mov_b32 m0, s25
	s_nop 0
	global_load_lds_dwordx4 v132, s[16:17]
	s_waitcnt lgkmcnt(8)
	s_barrier
	s_waitcnt lgkmcnt(0)
	s_setprio 1
	s_waitcnt lgkmcnt(0)
	v_mfma_f32_16x16x32_bf16 v[126:129], v[144:147], v[160:163], v[126:129]
	v_mfma_f32_16x16x32_bf16 v[122:125], v[152:155], v[160:163], v[122:125]
	v_mfma_f32_16x16x32_bf16 v[118:121], v[144:147], v[168:171], v[118:121]
	v_mfma_f32_16x16x32_bf16 v[114:117], v[152:155], v[168:171], v[114:117]
	v_mfma_f32_16x16x32_bf16 v[102:105], v[144:147], v[176:179], v[102:105]
	v_mfma_f32_16x16x32_bf16 v[98:101], v[152:155], v[176:179], v[98:101]
	v_mfma_f32_16x16x32_bf16 v[86:89], v[144:147], v[202:205], v[86:89]
	v_mfma_f32_16x16x32_bf16 v[82:85], v[152:155], v[202:205], v[82:85]
	v_mfma_f32_16x16x32_bf16 v[126:129], v[148:151], v[164:167], v[126:129]
	v_mfma_f32_16x16x32_bf16 v[122:125], v[156:159], v[164:167], v[122:125]
	v_mfma_f32_16x16x32_bf16 v[118:121], v[148:151], v[172:175], v[118:121]
	v_mfma_f32_16x16x32_bf16 v[114:117], v[156:159], v[172:175], v[114:117]
	v_mfma_f32_16x16x32_bf16 v[102:105], v[148:151], v[180:183], v[102:105]
	v_mfma_f32_16x16x32_bf16 v[98:101], v[156:159], v[180:183], v[98:101]
	v_mfma_f32_16x16x32_bf16 v[86:89], v[148:151], v[206:209], v[86:89]
	v_mfma_f32_16x16x32_bf16 v[82:85], v[156:159], v[206:209], v[82:85]
	s_setprio 0
	s_barrier
	s_add_i32 s16, 0, 0x1c000
	s_add_i32 s17, s41, s21
	v_add_u32_e32 v0, s16, v142
	s_mov_b32 m0, s17
	ds_read_b128 v[210:213], v0
	ds_read_b128 v[226:229], v0 offset:1024
	ds_read_b128 v[238:241], v0 offset:2048
	ds_read_b128 v[242:245], v0 offset:3072
	global_load_lds_dwordx4 v134, s[98:99]
	s_add_i32 m0, s17, 0x2000
	s_nop 0
	global_load_lds_dwordx4 v130, s[98:99]
	s_barrier
	s_waitcnt lgkmcnt(0)
	s_setprio 1
	s_waitcnt lgkmcnt(0)
	v_mfma_f32_16x16x32_bf16 v[110:113], v[210:213], v[160:163], v[110:113]
	v_mfma_f32_16x16x32_bf16 v[106:109], v[238:241], v[160:163], v[106:109]
	v_mfma_f32_16x16x32_bf16 v[94:97], v[210:213], v[168:171], v[94:97]
	v_mfma_f32_16x16x32_bf16 v[90:93], v[238:241], v[168:171], v[90:93]
	v_mfma_f32_16x16x32_bf16 v[78:81], v[210:213], v[176:179], v[78:81]
	v_mfma_f32_16x16x32_bf16 v[74:77], v[238:241], v[176:179], v[74:77]
	v_mfma_f32_16x16x32_bf16 v[70:73], v[210:213], v[202:205], v[70:73]
	v_mfma_f32_16x16x32_bf16 v[66:69], v[238:241], v[202:205], v[66:69]
	v_mfma_f32_16x16x32_bf16 v[110:113], v[226:229], v[164:167], v[110:113]
	v_mfma_f32_16x16x32_bf16 v[106:109], v[242:245], v[164:167], v[106:109]
	v_mfma_f32_16x16x32_bf16 v[94:97], v[226:229], v[172:175], v[94:97]
	v_mfma_f32_16x16x32_bf16 v[90:93], v[242:245], v[172:175], v[90:93]
	v_mfma_f32_16x16x32_bf16 v[78:81], v[226:229], v[180:183], v[78:81]
	v_mfma_f32_16x16x32_bf16 v[74:77], v[242:245], v[180:183], v[74:77]
	v_mfma_f32_16x16x32_bf16 v[70:73], v[226:229], v[206:209], v[70:73]
	v_mfma_f32_16x16x32_bf16 v[66:69], v[242:245], v[206:209], v[66:69]
	s_setprio 0
	s_mov_b32 m0, s28
	s_barrier
	ds_read_b128 v[160:163], v143 offset:49152
	ds_read_b128 v[164:167], v143 offset:50176
	ds_read_b128 v[168:171], v143 offset:51200
	ds_read_b128 v[172:175], v143 offset:52224
	ds_read_b128 v[176:179], v143 offset:53248
	ds_read_b128 v[180:183], v143 offset:54272
	ds_read_b128 v[202:205], v143 offset:55296
	ds_read_b128 v[206:209], v143 offset:56320
	global_load_lds_dwordx4 v136, s[100:101]
	s_mov_b32 m0, s29
	s_nop 0
	global_load_lds_dwordx4 v132, s[100:101]
	s_barrier
; #define PG8_STAGE(bufoff, gbase, voff) do { _Pragma("unroll") for (int _i = 0; _i < 2; ++_i) \
;     __builtin_amdgcn_global_load_lds((const unsigned*)((const char*)(gbase) + (voff)[_i]), (LAS unsigned*)(lds + (bufoff) + ldsw + _i * 8192), 16, 0, 0); } while (0)
; #define PG8_LDA(dst, b, h) do { _Pragma("unroll") for (int m = 0; m < 4; ++m) _Pragma("unroll") for (int k = 0; k < 2; ++k) dst[m][k] = *(const LAS bf16x8*)(lds + PG8_SA(b, h) + aoff + m * 2048 + k * 1024); } while (0)
; #define PG8_MMA(ai, bj, At, Bt) do { __builtin_amdgcn_s_setprio(1); _Pragma("unroll") for (int m = 0; m < 4; ++m) _Pragma("unroll") for (int n = 0; n < 2; ++n) _Pragma("unroll") for (int k = 0; k < 2; ++k) \
;     acc[ai][bj][m][n] = __builtin_amdgcn_mfma_f32_16x16x32_bf16(Bt[n][k], At[m][k], acc[ai][bj][m][n], 0, 0, 0); __builtin_amdgcn_s_setprio(0); } while (0)
; #define PG8_WAIT_V(n) asm volatile("s_waitcnt vmcnt(" #n ")" ::: "memory")
; #define PG8_WAIT_L(n) asm volatile("s_waitcnt lgkmcnt(" #n ")" ::: "memory")
; #define PG8_BAR __builtin_amdgcn_s_barrier()
; #define PG8_SCHED __builtin_amdgcn_sched_barrier(0)
; template <class Epi, class Sched>
; DI void gemm_phase(LAS unsigned char* lds, const int tid, const Gemm g, const Sched& S, const Epi& E) {
;     ...
;       PG8_BAR; PG8_WAIT_L(0); PG8_MMA(0, 1, At, B1); PG8_BAR;
;       PG8_LDA(At, 1, 1); PG8_STAGE(PG8_SA(1, 0), a3, voffA);
;       PG8_BAR; PG8_WAIT_L(0); PG8_MMA(1, 0, At, B0); PG8_BAR; PG8_SCHED;
;       PG8_STAGE(PG8_SB(1, 1), b3 + hstepB, voffB);
;       PG8_WAIT_V(6); PG8_BAR; PG8_MMA(1, 1, At, B1); PG8_BAR;
;     }
	s_waitcnt lgkmcnt(0)
	s_setprio 1
	s_waitcnt lgkmcnt(0)
	v_mfma_f32_16x16x32_bf16 v[62:65], v[144:147], v[160:163], v[62:65]
	v_mfma_f32_16x16x32_bf16 v[58:61], v[152:155], v[160:163], v[58:61]
	v_mfma_f32_16x16x32_bf16 v[54:57], v[144:147], v[168:171], v[54:57]
	v_mfma_f32_16x16x32_bf16 v[50:53], v[152:155], v[168:171], v[50:53]
	v_mfma_f32_16x16x32_bf16 v[38:41], v[144:147], v[176:179], v[38:41]
	v_mfma_f32_16x16x32_bf16 v[34:37], v[152:155], v[176:179], v[34:37]
	v_mfma_f32_16x16x32_bf16 v[22:25], v[144:147], v[202:205], v[22:25]
	v_mfma_f32_16x16x32_bf16 v[18:21], v[152:155], v[202:205], v[18:21]
	v_mfma_f32_16x16x32_bf16 v[62:65], v[148:151], v[164:167], v[62:65]
	v_mfma_f32_16x16x32_bf16 v[58:61], v[156:159], v[164:167], v[58:61]
	v_mfma_f32_16x16x32_bf16 v[54:57], v[148:151], v[172:175], v[54:57]
	v_mfma_f32_16x16x32_bf16 v[50:53], v[156:159], v[172:175], v[50:53]
	v_mfma_f32_16x16x32_bf16 v[38:41], v[148:151], v[180:183], v[38:41]
	v_mfma_f32_16x16x32_bf16 v[34:37], v[156:159], v[180:183], v[34:37]
	v_mfma_f32_16x16x32_bf16 v[22:25], v[148:151], v[206:209], v[22:25]
	v_mfma_f32_16x16x32_bf16 v[18:21], v[156:159], v[206:209], v[18:21]
	s_setprio 0
	s_barrier
	s_add_u32 s14, s14, 0x100080
	s_addc_u32 s15, s15, 0
	s_add_i32 s16, s16, s21
	s_mov_b32 m0, s16
	s_nop 0
	global_load_lds_dwordx4 v134, s[14:15]
	s_add_i32 m0, s16, 0x2000
	s_nop 0
	global_load_lds_dwordx4 v130, s[14:15]
	s_waitcnt vmcnt(6)
	s_barrier
	s_setprio 1
	v_mfma_f32_16x16x32_bf16 v[46:49], v[210:213], v[160:163], v[46:49]
	v_mfma_f32_16x16x32_bf16 v[42:45], v[238:241], v[160:163], v[42:45]
	v_mfma_f32_16x16x32_bf16 v[30:33], v[210:213], v[168:171], v[30:33]
	v_mfma_f32_16x16x32_bf16 v[26:29], v[238:241], v[168:171], v[26:29]
	v_mfma_f32_16x16x32_bf16 v[14:17], v[210:213], v[176:179], v[14:17]
	v_mfma_f32_16x16x32_bf16 v[10:13], v[238:241], v[176:179], v[10:13]
	v_mfma_f32_16x16x32_bf16 v[6:9], v[210:213], v[202:205], v[6:9]
	v_mfma_f32_16x16x32_bf16 v[2:5], v[238:241], v[202:205], v[2:5]
	v_mfma_f32_16x16x32_bf16 v[46:49], v[226:229], v[164:167], v[46:49]
	v_mfma_f32_16x16x32_bf16 v[42:45], v[242:245], v[164:167], v[42:45]
	v_mfma_f32_16x16x32_bf16 v[30:33], v[226:229], v[172:175], v[30:33]
	v_mfma_f32_16x16x32_bf16 v[26:29], v[242:245], v[172:175], v[26:29]
	v_mfma_f32_16x16x32_bf16 v[14:17], v[226:229], v[180:183], v[14:17]
	v_mfma_f32_16x16x32_bf16 v[10:13], v[242:245], v[180:183], v[10:13]
	v_mfma_f32_16x16x32_bf16 v[6:9], v[226:229], v[206:209], v[6:9]
	v_mfma_f32_16x16x32_bf16 v[2:5], v[242:245], v[206:209], v[2:5]
	s_setprio 0
	s_add_i32 s40, s40, 2
	s_add_u32 s38, s38, 0x100
	s_addc_u32 s39, s39, 0
	s_add_u32 s12, s12, 0x100
	s_addc_u32 s13, s13, 0
	s_cmp_gt_u32 s40, 61
	s_barrier
	s_cbranch_scc0 .LBB0_659
; DI void st8p(void* ub, unsigned voff, f32x4 a, f32x4 b) { u32x4 o = {pk(a[0], a[1]), pk(a[2], a[3]), pk(b[0], b[1]), pk(b[2], b[3])}; *(GAS u32x4*)((char*)ub + voff) = o; }
; #define ROWS_LOOP _Pragma("unroll") for (int ai = 0; ai < 2; ++ai) _Pragma("unroll") for (int m = 0; m < 4; ++m)
; template <class Epi, class Sched>
; DI void gemm_phase(LAS unsigned char* lds, const int tid, const Gemm g, const Sched& S, const Epi& E) {
;     ...
;     { int z_e = 0; asm volatile("" : "+v"(z_e)); const int lane_e = __builtin_amdgcn_mbcnt_hi(~0u, __builtin_amdgcn_mbcnt_lo(~0u, (unsigned)z_e));
;       E(acc, cur, wr, wc, lane_e & 15, lane_e >> 4); }
;     if (!has_next) break;
;   DI void operator()(const AccT& acc, const Unit& u, int wr, int wc, int fr, int fq) const {
;     const char* base = (const char*)(MIX + (ctx ? (size_t)(TL + u.pn * 256) : (size_t)(u.pn * 2048 + u.pm * 256)) * D);
;     const unsigned o0 = (unsigned)((wr * 64 + fr) * D + wc * 32 + fq * 8) * 2u;
;     ROWS_LOOP {
;       char* rb = (char*)base + (size_t)(ai * 128 + m * 16) * D * 2;
; #pragma unroll
;       for (int bj = 0; bj < 2; ++bj) st8p(rb + bj * 256, o0, acc[ai][bj][m][0], acc[ai][bj][m][1]);
;     }
;   }
	v_mov_b32_e32 v0, v1
	s_lshl_b32 s1, s34, 11
	s_lshl_b32 s7, s35, 8
	v_mbcnt_lo_u32_b32 v0, -1, v0
	s_add_i32 s12, s7, s1
	v_mbcnt_hi_u32_b32 v0, -1, v0
	s_ashr_i32 s13, s12, 31
	s_lshl_b64 s[12:13], s[12:13], 11
	v_lshlrev_b32_e32 v144, 11, v0
	s_add_u32 s12, s26, s12
	v_and_b32_e32 v144, 0x7800, v144
	v_and_b32_e32 v0, -16, v0
	s_addc_u32 s13, s27, s13
	v_add3_u32 v0, s30, v0, v144
	v_lshl_add_u64 v[144:145], s[12:13], 0, v[0:1]
	v_cvt_pk_bf16_f32 v110, v110, v111
	v_cvt_pk_bf16_f32 v111, v112, v113
	v_cvt_pk_bf16_f32 v112, v106, v107
	v_cvt_pk_bf16_f32 v113, v108, v109
	s_mov_b32 s1, 0x8000
	global_store_dwordx4 v0, v[110:113], s[12:13] offset:256
	v_cvt_pk_bf16_f32 v94, v94, v95
	v_cvt_pk_bf16_f32 v95, v96, v97
	v_add_co_u32_e32 v110, vcc, s1, v144
	v_cvt_pk_bf16_f32 v96, v90, v91
	s_nop 0
	v_addc_co_u32_e32 v111, vcc, 0, v145, vcc
	v_cvt_pk_bf16_f32 v97, v92, v93
	global_store_dwordx4 v[110:111], v[94:97], off offset:256
	v_cvt_pk_bf16_f32 v78, v78, v79
	v_cvt_pk_bf16_f32 v79, v80, v81
	v_add_co_u32_e32 v94, vcc, s68, v144
	v_cvt_pk_bf16_f32 v80, v74, v75
	s_nop 0
	v_addc_co_u32_e32 v95, vcc, 0, v145, vcc
	v_cvt_pk_bf16_f32 v81, v76, v77
	s_mov_b32 s1, 0x18000
	global_store_dwordx4 v[94:95], v[78:81], off offset:256
	v_cvt_pk_bf16_f32 v62, v62, v63
	v_cvt_pk_bf16_f32 v63, v64, v65
	v_add_co_u32_e32 v78, vcc, s1, v144
	s_mov_b32 s1, 0x40000
	s_nop 0
	v_addc_co_u32_e32 v79, vcc, 0, v145, vcc
	v_cvt_pk_bf16_f32 v64, v58, v59
	v_add_co_u32_e32 v58, vcc, s1, v144
	v_cvt_pk_bf16_f32 v46, v46, v47
	s_nop 0
	v_addc_co_u32_e32 v59, vcc, 0, v145, vcc
	v_cvt_pk_bf16_f32 v47, v48, v49
	v_cvt_pk_bf16_f32 v48, v42, v43
	v_cvt_pk_bf16_f32 v49, v44, v45
	s_mov_b32 s1, 0x48000
	global_store_dwordx4 v[58:59], v[46:49], off offset:256
	v_cvt_pk_bf16_f32 v30, v30, v31
	v_cvt_pk_bf16_f32 v31, v32, v33
	v_add_co_u32_e32 v46, vcc, s1, v144
	v_cvt_pk_bf16_f32 v32, v26, v27
	s_nop 0
	v_addc_co_u32_e32 v47, vcc, 0, v145, vcc
	v_cvt_pk_bf16_f32 v33, v28, v29
	s_mov_b32 s1, 0x50000
	global_store_dwordx4 v[46:47], v[30:33], off offset:256
	v_cvt_pk_bf16_f32 v14, v14, v15
	v_cvt_pk_bf16_f32 v15, v16, v17
	v_add_co_u32_e32 v30, vcc, s1, v144
	v_cvt_pk_bf16_f32 v16, v10, v11
	s_nop 0
	v_addc_co_u32_e32 v31, vcc, 0, v145, vcc
	v_cvt_pk_bf16_f32 v17, v12, v13
	s_mov_b32 s1, 0x58000
	global_store_dwordx4 v[30:31], v[14:17], off offset:256
	v_cvt_pk_bf16_f32 v126, v126, v127
	v_cvt_pk_bf16_f32 v127, v128, v129
	v_add_co_u32_e32 v14, vcc, s1, v144
	v_cvt_pk_bf16_f32 v128, v122, v123
	v_cvt_pk_bf16_f32 v129, v124, v125
	v_addc_co_u32_e32 v15, vcc, 0, v145, vcc
	global_store_dwordx4 v0, v[126:129], s[12:13]
	v_cvt_pk_bf16_f32 v106, v118, v119
	v_cvt_pk_bf16_f32 v107, v120, v121
	v_cvt_pk_bf16_f32 v108, v114, v115
	v_cvt_pk_bf16_f32 v109, v116, v117
	v_cvt_pk_bf16_f32 v90, v102, v103
	v_cvt_pk_bf16_f32 v91, v104, v105
	v_cvt_pk_bf16_f32 v92, v98, v99
	v_cvt_pk_bf16_f32 v93, v100, v101
	v_cvt_pk_bf16_f32 v74, v86, v87
	v_cvt_pk_bf16_f32 v75, v88, v89
	v_cvt_pk_bf16_f32 v76, v82, v83
	v_cvt_pk_bf16_f32 v77, v84, v85
	v_cvt_pk_bf16_f32 v70, v70, v71
	v_cvt_pk_bf16_f32 v71, v72, v73
	v_cvt_pk_bf16_f32 v72, v66, v67
	v_cvt_pk_bf16_f32 v73, v68, v69
	v_cvt_pk_bf16_f32 v65, v60, v61
	v_cvt_pk_bf16_f32 v42, v54, v55
	v_cvt_pk_bf16_f32 v43, v56, v57
	v_cvt_pk_bf16_f32 v44, v50, v51
	v_cvt_pk_bf16_f32 v45, v52, v53
	v_cvt_pk_bf16_f32 v26, v38, v39
	v_cvt_pk_bf16_f32 v27, v40, v41
	v_cvt_pk_bf16_f32 v28, v34, v35
	v_cvt_pk_bf16_f32 v29, v36, v37
	v_cvt_pk_bf16_f32 v10, v22, v23
	v_cvt_pk_bf16_f32 v11, v24, v25
	v_cvt_pk_bf16_f32 v12, v18, v19
	v_cvt_pk_bf16_f32 v13, v20, v21
	v_cvt_pk_bf16_f32 v6, v6, v7
	v_cvt_pk_bf16_f32 v7, v8, v9
	v_cvt_pk_bf16_f32 v8, v2, v3
	v_cvt_pk_bf16_f32 v9, v4, v5
	s_and_b64 vcc, exec, s[4:5]
	s_mov_b32 s34, s0
	s_mov_b32 s35, s6
	s_mov_b64 s[12:13], s[10:11]
	s_mov_b64 s[16:17], s[8:9]
	global_store_dwordx4 v[110:111], v[106:109], off
	global_store_dwordx4 v[94:95], v[90:93], off
	global_store_dwordx4 v[78:79], v[74:77], off
	global_store_dwordx4 v[78:79], v[70:73], off offset:256
	global_store_dwordx4 v[58:59], v[62:65], off
	global_store_dwordx4 v[46:47], v[42:45], off
	global_store_dwordx4 v[30:31], v[26:29], off
	global_store_dwordx4 v[14:15], v[10:13], off
	global_store_dwordx4 v[14:15], v[6:9], off offset:256
	s_cbranch_vccz .LBB0_656
	s_waitcnt vmcnt(0)
	s_cmpk_gt_u32 s2, 0xff
	s_cbranch_scc1 .LBB0_663
	s_barrier

; DI float fexp2(float x) { return __builtin_amdgcn_exp2f(x); }
; #define AT_LDK(dst, k4_) _Pragma("unroll") for (int kc = 0; kc < NKC; ++kc) dst[kc] = *(const LAS bf16x8*)(kb + (((k4_) * 32 + r) * KS + kc * 16 + hh * 8) * 2)
; #define AT_MMK(src, k4_) do { _Pragma("unroll") for (int i = 0; i < 16; ++i) s[k4_][i] = 0.f; _Pragma("unroll") for (int kc = 0; kc < NKC; ++kc) s[k4_] = MFMA32(src[kc], qf[kc], s[k4_]); } while (0)
; template <int DK> ...
;     ...
;       { bf16x8 ka[NKC], kb2[NKC];
;         AT_LDK(ka, 0); __builtin_amdgcn_sched_barrier(0);
;         AT_LDK(kb2, 1); __builtin_amdgcn_sched_barrier(0); AT_MMK(ka, 0); __builtin_amdgcn_sched_barrier(0);
;         AT_LDK(ka, 2); __builtin_amdgcn_sched_barrier(0); AT_MMK(kb2, 1); __builtin_amdgcn_sched_barrier(0);
;         AT_LDK(kb2, 3); __builtin_amdgcn_sched_barrier(0); AT_MMK(ka, 2); __builtin_amdgcn_sched_barrier(0);
;         AT_MMK(kb2, 3); __builtin_amdgcn_sched_barrier(0); }
;     ...
;       if (masked) {
; #pragma unroll
;         for (int k4 = 0; k4 < 4; ++k4)
; #pragma unroll
;           for (int i = 0; i < 16; ++i) { const int dd = (tq0 + r) - (kpos_t + k4 * 32 + (i & 3) + 8 * (i >> 2) + 4 * hh); if (dd > 128 || dd < -128) s[k4][i] = -1e30f; }
;       }
;       float mx = -3e38f;
; #pragma unroll
;       for (int k4 = 0; k4 < 4; ++k4)
; #pragma unroll
;         for (int i = 0; i < 16; i += 2) mx = fmaxf(fmaxf(mx, s[k4][i]), s[k4][i + 1]);
;       mx = fmaxf(mx, __shfl_xor(mx, 32));
;       const float mnew = fmaxf(mrun, mx * cq), alpha = fexp2(mrun - mnew); mrun = mnew;
;       f32x2 ls2 = {0.f, 0.f}; const f32x2 cq2 = {cq, cq}, mn2 = {-mnew, -mnew};
; #pragma unroll
;       for (int k4 = 0; k4 < 4; ++k4)
; #pragma unroll
;         for (int i = 0; i < 16; i += 2) {
;           f32x2 xv = {s[k4][i], s[k4][i + 1]}; xv = xv * cq2 + mn2;
;           f32x2 pv = {fexp2(xv[0]), fexp2(xv[1])}; s[k4][i] = pv[0]; s[k4][i + 1] = pv[1]; ls2 += pv;
;         }
;       lrun = lrun * alpha + (ls2[0] + ls2[1]);
;       if (__builtin_amdgcn_ballot_w64(alpha != 1.f) != 0ull) { o0 *= alpha; o1 *= alpha; }
.LBB0_754:
	s_and_b32 s1, s6, 1
	s_mul_i32 s6, s1, 0xaa00
	s_add_i32 s6, s6, 0
	v_add3_u32 v162, s6, v146, v165
	ds_read_b128 v[34:37], v162
	ds_read_b128 v[38:41], v162 offset:32
	ds_read_b128 v[42:45], v162 offset:64
	ds_read_b128 v[46:49], v162 offset:96
	ds_read_b128 v[50:53], v162 offset:128
	ds_read_b128 v[54:57], v162 offset:160
	ds_read_b128 v[58:61], v162 offset:6656
	ds_read_b128 v[62:65], v162 offset:6688
	ds_read_b128 v[170:173], v162 offset:6720
	ds_read_b128 v[174:177], v162 offset:6752
	ds_read_b128 v[178:181], v162 offset:6784
	ds_read_b128 v[182:185], v162 offset:6816
	s_waitcnt lgkmcnt(11)
	v_mfma_f32_32x32x16_bf16 v[82:97], v[34:37], v[118:121], 0
	s_waitcnt lgkmcnt(10)
	v_mfma_f32_32x32x16_bf16 v[82:97], v[38:41], v[98:101], v[82:97]
	s_waitcnt lgkmcnt(9)
	v_mfma_f32_32x32x16_bf16 v[82:97], v[42:45], v[102:105], v[82:97]
	s_waitcnt lgkmcnt(8)
	v_mfma_f32_32x32x16_bf16 v[82:97], v[46:49], v[106:109], v[82:97]
	s_waitcnt lgkmcnt(7)
	v_mfma_f32_32x32x16_bf16 v[82:97], v[50:53], v[110:113], v[82:97]
	s_waitcnt lgkmcnt(6)
	v_mfma_f32_32x32x16_bf16 v[82:97], v[54:57], v[114:117], v[82:97]
	ds_read_b128 v[34:37], v162 offset:13312
	ds_read_b128 v[38:41], v162 offset:13344
	ds_read_b128 v[42:45], v162 offset:13376
	ds_read_b128 v[46:49], v162 offset:13408
	ds_read_b128 v[202:205], v162 offset:13440
	ds_read_b128 v[206:209], v162 offset:13472
	s_waitcnt lgkmcnt(11)
	v_mfma_f32_32x32x16_bf16 v[66:81], v[58:61], v[118:121], 0
	s_waitcnt lgkmcnt(10)
	v_mfma_f32_32x32x16_bf16 v[66:81], v[62:65], v[98:101], v[66:81]
	s_waitcnt lgkmcnt(9)
	v_mfma_f32_32x32x16_bf16 v[66:81], v[170:173], v[102:105], v[66:81]
	s_waitcnt lgkmcnt(8)
	v_mfma_f32_32x32x16_bf16 v[66:81], v[174:177], v[106:109], v[66:81]
	s_waitcnt lgkmcnt(7)
	v_mfma_f32_32x32x16_bf16 v[66:81], v[178:181], v[110:113], v[66:81]
	s_waitcnt lgkmcnt(6)
	v_mfma_f32_32x32x16_bf16 v[66:81], v[182:185], v[114:117], v[66:81]
	ds_read_b128 v[170:173], v162 offset:19968
	ds_read_b128 v[174:177], v162 offset:20000
	ds_read_b128 v[178:181], v162 offset:20032
	ds_read_b128 v[182:185], v162 offset:20064
	ds_read_b128 v[210:213], v162 offset:20096
	ds_read_b128 v[226:229], v162 offset:20128
	s_waitcnt lgkmcnt(11)
	v_mfma_f32_32x32x16_bf16 v[50:65], v[34:37], v[118:121], 0
	v_max3_f32 v162, v82, s56, v83
	v_max3_f32 v162, v162, v84, v85
	s_waitcnt lgkmcnt(10)
	v_mfma_f32_32x32x16_bf16 v[50:65], v[38:41], v[98:101], v[50:65]
	v_max3_f32 v162, v162, v86, v87
	v_max3_f32 v162, v162, v88, v89
	s_waitcnt lgkmcnt(9)
	v_mfma_f32_32x32x16_bf16 v[50:65], v[42:45], v[102:105], v[50:65]
	v_max3_f32 v162, v162, v90, v91
	v_max3_f32 v162, v162, v92, v93
	s_waitcnt lgkmcnt(8)
	v_mfma_f32_32x32x16_bf16 v[50:65], v[46:49], v[106:109], v[50:65]
	v_max3_f32 v162, v162, v94, v95
	v_max3_f32 v162, v162, v96, v97
	s_waitcnt lgkmcnt(7)
	v_mfma_f32_32x32x16_bf16 v[50:65], v[202:205], v[110:113], v[50:65]
	v_max3_f32 v162, v162, v66, v67
	v_max3_f32 v162, v162, v68, v69
	s_waitcnt lgkmcnt(6)
	v_mfma_f32_32x32x16_bf16 v[50:65], v[206:209], v[114:117], v[50:65]
	v_max3_f32 v162, v162, v70, v71
	v_max3_f32 v162, v162, v72, v73
	s_waitcnt lgkmcnt(5)
	v_mfma_f32_32x32x16_bf16 v[34:49], v[170:173], v[118:121], 0
	v_max3_f32 v162, v162, v74, v75
	v_max3_f32 v162, v162, v76, v77
	s_waitcnt lgkmcnt(4)
	v_mfma_f32_32x32x16_bf16 v[34:49], v[174:177], v[98:101], v[34:49]
	v_max3_f32 v162, v162, v78, v79
	v_max3_f32 v162, v162, v80, v81
	s_waitcnt lgkmcnt(3)
	v_mfma_f32_32x32x16_bf16 v[34:49], v[178:181], v[102:105], v[34:49]
	v_add3_u32 v169, s6, v164, v168
	v_add_u32_e32 v190, 0x6800, v169
	v_add_u32_e32 v169, 0x8800, v169
	s_waitcnt lgkmcnt(2)
	v_mfma_f32_32x32x16_bf16 v[34:49], v[182:185], v[106:109], v[34:49]
	v_max3_f32 v162, v162, v50, v51
	v_max3_f32 v162, v162, v52, v53
	s_waitcnt lgkmcnt(1)
	v_mfma_f32_32x32x16_bf16 v[34:49], v[210:213], v[110:113], v[34:49]
	v_max3_f32 v162, v162, v54, v55
	v_max3_f32 v162, v162, v56, v57
	s_waitcnt lgkmcnt(0)
	v_mfma_f32_32x32x16_bf16 v[34:49], v[226:229], v[114:117], v[34:49]
	v_max3_f32 v162, v162, v58, v59
	v_max3_f32 v162, v162, v60, v61
	v_max3_f32 v162, v162, v62, v63
	v_max3_f32 v162, v162, v64, v65
	ds_read2_b64 v[170:173], v190 offset1:2
	ds_read2_b64 v[174:177], v190 offset0:4 offset1:6
	ds_read2_b64 v[178:181], v169 offset0:32 offset1:34
	ds_read2_b64 v[182:185], v169 offset0:36 offset1:38
	s_nop 3
	v_max3_f32 v162, v162, v34, v35
	v_max3_f32 v162, v162, v36, v37
	v_max3_f32 v162, v162, v38, v39
	v_max3_f32 v162, v162, v40, v41
	v_max3_f32 v162, v162, v42, v43
	v_max3_f32 v162, v162, v44, v45
	v_max3_f32 v162, v162, v46, v47
	v_max3_f32 v162, v162, v48, v49
	ds_bpermute_b32 v210, v166, v162
	s_waitcnt lgkmcnt(0)
	v_max_f32_e32 v210, v210, v210
	v_max_f32_e32 v162, v162, v210
	v_mul_f32_e32 v162, v150, v162
	v_max_f32_e32 v210, v160, v160
	v_max_f32_e32 v162, v210, v162
	v_sub_f32_e32 v160, v160, v162
	v_exp_f32_e32 v160, v160
	s_nop 0
	v_cmp_neq_f32_e32 vcc, 1.0, v160
	s_cbranch_vccz .Lmla_norescale
	v_pk_mul_f32 v[32:33], v[32:33], v[160:161] op_sel_hi:[1,0]
	v_pk_mul_f32 v[30:31], v[30:31], v[160:161] op_sel_hi:[1,0]
	v_pk_mul_f32 v[28:29], v[28:29], v[160:161] op_sel_hi:[1,0]
	v_pk_mul_f32 v[26:27], v[26:27], v[160:161] op_sel_hi:[1,0]
	v_pk_mul_f32 v[24:25], v[24:25], v[160:161] op_sel_hi:[1,0]
	v_pk_mul_f32 v[22:23], v[22:23], v[160:161] op_sel_hi:[1,0]
	v_pk_mul_f32 v[20:21], v[20:21], v[160:161] op_sel_hi:[1,0]
	v_pk_mul_f32 v[18:19], v[18:19], v[160:161] op_sel_hi:[1,0]
	v_pk_mul_f32 v[16:17], v[16:17], v[160:161] op_sel_hi:[1,0]
	v_pk_mul_f32 v[14:15], v[14:15], v[160:161] op_sel_hi:[1,0]
	v_pk_mul_f32 v[12:13], v[12:13], v[160:161] op_sel_hi:[1,0]
	v_pk_mul_f32 v[10:11], v[10:11], v[160:161] op_sel_hi:[1,0]
	v_pk_mul_f32 v[8:9], v[8:9], v[160:161] op_sel_hi:[1,0]
	v_pk_mul_f32 v[6:7], v[6:7], v[160:161] op_sel_hi:[1,0]
	v_pk_mul_f32 v[4:5], v[4:5], v[160:161] op_sel_hi:[1,0]
	v_pk_mul_f32 v[2:3], v[2:3], v[160:161] op_sel_hi:[1,0]
; DI float fexp2(float x) { return __builtin_amdgcn_exp2f(x); }
; template <int DK> ...
;     ...
;       f32x2 ls2 = {0.f, 0.f}; const f32x2 cq2 = {cq, cq}, mn2 = {-mnew, -mnew};
; #pragma unroll
;       for (int k4 = 0; k4 < 4; ++k4)
; #pragma unroll
;         for (int i = 0; i < 16; i += 2) {
;           f32x2 xv = {s[k4][i], s[k4][i + 1]}; xv = xv * cq2 + mn2;
;           f32x2 pv = {fexp2(xv[0]), fexp2(xv[1])}; s[k4][i] = pv[0]; s[k4][i + 1] = pv[1]; ls2 += pv;
;         }
;       lrun = lrun * alpha + (ls2[0] + ls2[1]);
;       if (__builtin_amdgcn_ballot_w64(alpha != 1.f) != 0ull) { o0 *= alpha; o1 *= alpha; }
;     ...
;       { bf16x8 va[2][2], vb2[2][2];
;         AT_LDV(va, 0); __builtin_amdgcn_sched_barrier(0);
;         AT_LDV(vb2, 1); __builtin_amdgcn_sched_barrier(0); AT_MMV(va, 0); __builtin_amdgcn_sched_barrier(0);
;         AT_LDV(va, 2); __builtin_amdgcn_sched_barrier(0); AT_MMV(vb2, 1); __builtin_amdgcn_sched_barrier(0);
;         AT_LDV(vb2, 3); __builtin_amdgcn_sched_barrier(0); AT_MMV(va, 2); __builtin_amdgcn_sched_barrier(0);
;         AT_MMV(vb2, 3); }
.Lmla_norescale:
	v_pk_fma_f32 v[82:83], v[150:151], v[82:83], v[162:163] op_sel_hi:[1,1,0] neg_lo:[0,0,1] neg_hi:[0,0,1]
	v_pk_fma_f32 v[84:85], v[150:151], v[84:85], v[162:163] op_sel_hi:[1,1,0] neg_lo:[0,0,1] neg_hi:[0,0,1]
	v_pk_fma_f32 v[86:87], v[150:151], v[86:87], v[162:163] op_sel_hi:[1,1,0] neg_lo:[0,0,1] neg_hi:[0,0,1]
	v_pk_fma_f32 v[88:89], v[150:151], v[88:89], v[162:163] op_sel_hi:[1,1,0] neg_lo:[0,0,1] neg_hi:[0,0,1]
	v_pk_fma_f32 v[90:91], v[150:151], v[90:91], v[162:163] op_sel_hi:[1,1,0] neg_lo:[0,0,1] neg_hi:[0,0,1]
	v_pk_fma_f32 v[92:93], v[150:151], v[92:93], v[162:163] op_sel_hi:[1,1,0] neg_lo:[0,0,1] neg_hi:[0,0,1]
	v_pk_fma_f32 v[94:95], v[150:151], v[94:95], v[162:163] op_sel_hi:[1,1,0] neg_lo:[0,0,1] neg_hi:[0,0,1]
	v_pk_fma_f32 v[96:97], v[150:151], v[96:97], v[162:163] op_sel_hi:[1,1,0] neg_lo:[0,0,1] neg_hi:[0,0,1]
	v_exp_f32_e32 v82, v82
	v_exp_f32_e32 v83, v83
	v_exp_f32_e32 v84, v84
	v_exp_f32_e32 v85, v85
	v_exp_f32_e32 v86, v86
	v_exp_f32_e32 v87, v87
	v_exp_f32_e32 v88, v88
	v_exp_f32_e32 v89, v89
	v_exp_f32_e32 v90, v90
	v_exp_f32_e32 v91, v91
	v_exp_f32_e32 v92, v92
	v_exp_f32_e32 v93, v93
	v_exp_f32_e32 v94, v94
	v_exp_f32_e32 v95, v95
	v_exp_f32_e32 v96, v96
	v_exp_f32_e32 v97, v97
	v_cvt_pk_bf16_f32 v238, v82, v83
	v_cvt_pk_bf16_f32 v239, v84, v85
	v_cvt_pk_bf16_f32 v240, v86, v87
	v_cvt_pk_bf16_f32 v241, v88, v89
	v_cvt_pk_bf16_f32 v242, v90, v91
	v_cvt_pk_bf16_f32 v243, v92, v93
	v_cvt_pk_bf16_f32 v244, v94, v95
	v_cvt_pk_bf16_f32 v245, v96, v97
	v_mfma_f32_32x32x16_bf16 v[18:33], v[170:173], v[238:241], v[18:33]
	v_pk_fma_f32 v[66:67], v[150:151], v[66:67], v[162:163] op_sel_hi:[1,1,0] neg_lo:[0,0,1] neg_hi:[0,0,1]
	v_pk_fma_f32 v[68:69], v[150:151], v[68:69], v[162:163] op_sel_hi:[1,1,0] neg_lo:[0,0,1] neg_hi:[0,0,1]
	v_pk_fma_f32 v[70:71], v[150:151], v[70:71], v[162:163] op_sel_hi:[1,1,0] neg_lo:[0,0,1] neg_hi:[0,0,1]
	v_pk_fma_f32 v[72:73], v[150:151], v[72:73], v[162:163] op_sel_hi:[1,1,0] neg_lo:[0,0,1] neg_hi:[0,0,1]
	v_pk_fma_f32 v[74:75], v[150:151], v[74:75], v[162:163] op_sel_hi:[1,1,0] neg_lo:[0,0,1] neg_hi:[0,0,1]
	v_pk_fma_f32 v[76:77], v[150:151], v[76:77], v[162:163] op_sel_hi:[1,1,0] neg_lo:[0,0,1] neg_hi:[0,0,1]
	v_pk_fma_f32 v[78:79], v[150:151], v[78:79], v[162:163] op_sel_hi:[1,1,0] neg_lo:[0,0,1] neg_hi:[0,0,1]
	v_pk_fma_f32 v[80:81], v[150:151], v[80:81], v[162:163] op_sel_hi:[1,1,0] neg_lo:[0,0,1] neg_hi:[0,0,1]
	v_pk_add_f32 v[82:83], v[86:87], v[82:83]
	v_pk_add_f32 v[84:85], v[88:89], v[84:85]
	v_mfma_f32_32x32x16_bf16 v[2:17], v[178:181], v[238:241], v[2:17]
	v_exp_f32_e32 v66, v66
	v_exp_f32_e32 v67, v67
	v_exp_f32_e32 v68, v68
	v_exp_f32_e32 v69, v69
	v_exp_f32_e32 v70, v70
	v_exp_f32_e32 v71, v71
	v_exp_f32_e32 v72, v72
	v_exp_f32_e32 v73, v73
	v_pk_add_f32 v[82:83], v[90:91], v[82:83]
	v_pk_add_f32 v[84:85], v[92:93], v[84:85]
	v_mfma_f32_32x32x16_bf16 v[18:33], v[174:177], v[242:245], v[18:33]
	ds_read2_b64 v[170:173], v190 offset0:8 offset1:10
	ds_read2_b64 v[174:177], v190 offset0:12 offset1:14
	v_exp_f32_e32 v74, v74
	v_exp_f32_e32 v75, v75
	v_exp_f32_e32 v76, v76
	v_exp_f32_e32 v77, v77
	v_exp_f32_e32 v78, v78
	v_exp_f32_e32 v79, v79
	v_exp_f32_e32 v80, v80
	v_exp_f32_e32 v81, v81
	v_pk_add_f32 v[82:83], v[94:95], v[82:83]
	v_pk_add_f32 v[84:85], v[96:97], v[84:85]
	v_mfma_f32_32x32x16_bf16 v[2:17], v[182:185], v[242:245], v[2:17]
	ds_read2_b64 v[178:181], v169 offset0:40 offset1:42
	ds_read2_b64 v[182:185], v169 offset0:44 offset1:46
	v_cvt_pk_bf16_f32 v202, v66, v67
	v_cvt_pk_bf16_f32 v203, v68, v69
	v_cvt_pk_bf16_f32 v204, v70, v71
	v_cvt_pk_bf16_f32 v205, v72, v73
	v_cvt_pk_bf16_f32 v206, v74, v75
	v_cvt_pk_bf16_f32 v207, v76, v77
	v_cvt_pk_bf16_f32 v208, v78, v79
	v_cvt_pk_bf16_f32 v209, v80, v81
	v_pk_add_f32 v[82:83], v[84:85], v[82:83]
	s_waitcnt lgkmcnt(2)
	v_mfma_f32_32x32x16_bf16 v[18:33], v[170:173], v[202:205], v[18:33]
	v_pk_fma_f32 v[50:51], v[150:151], v[50:51], v[162:163] op_sel_hi:[1,1,0] neg_lo:[0,0,1] neg_hi:[0,0,1]
	v_pk_fma_f32 v[52:53], v[150:151], v[52:53], v[162:163] op_sel_hi:[1,1,0] neg_lo:[0,0,1] neg_hi:[0,0,1]
	v_pk_fma_f32 v[54:55], v[150:151], v[54:55], v[162:163] op_sel_hi:[1,1,0] neg_lo:[0,0,1] neg_hi:[0,0,1]
	v_pk_fma_f32 v[56:57], v[150:151], v[56:57], v[162:163] op_sel_hi:[1,1,0] neg_lo:[0,0,1] neg_hi:[0,0,1]
	v_pk_fma_f32 v[58:59], v[150:151], v[58:59], v[162:163] op_sel_hi:[1,1,0] neg_lo:[0,0,1] neg_hi:[0,0,1]
	v_pk_fma_f32 v[60:61], v[150:151], v[60:61], v[162:163] op_sel_hi:[1,1,0] neg_lo:[0,0,1] neg_hi:[0,0,1]
	v_pk_fma_f32 v[62:63], v[150:151], v[62:63], v[162:163] op_sel_hi:[1,1,0] neg_lo:[0,0,1] neg_hi:[0,0,1]
	v_pk_fma_f32 v[64:65], v[150:151], v[64:65], v[162:163] op_sel_hi:[1,1,0] neg_lo:[0,0,1] neg_hi:[0,0,1]
	v_pk_add_f32 v[66:67], v[70:71], v[66:67]
	v_pk_add_f32 v[68:69], v[72:73], v[68:69]
	s_waitcnt lgkmcnt(0)
; DI float fexp2(float x) { return __builtin_amdgcn_exp2f(x); }
; template <int DK> ...
;     ...
;         for (int i = 0; i < 16; i += 2) {
;           f32x2 xv = {s[k4][i], s[k4][i + 1]}; xv = xv * cq2 + mn2;
;           f32x2 pv = {fexp2(xv[0]), fexp2(xv[1])}; s[k4][i] = pv[0]; s[k4][i + 1] = pv[1]; ls2 += pv;
;         }
;       lrun = lrun * alpha + (ls2[0] + ls2[1]);
;       if (__builtin_amdgcn_ballot_w64(alpha != 1.f) != 0ull) { o0 *= alpha; o1 *= alpha; }
;     ...
;       { bf16x8 va[2][2], vb2[2][2];
;         AT_LDV(va, 0); __builtin_amdgcn_sched_barrier(0);
;         AT_LDV(vb2, 1); __builtin_amdgcn_sched_barrier(0); AT_MMV(va, 0); __builtin_amdgcn_sched_barrier(0);
;         AT_LDV(va, 2); __builtin_amdgcn_sched_barrier(0); AT_MMV(vb2, 1); __builtin_amdgcn_sched_barrier(0);
;         AT_LDV(vb2, 3); __builtin_amdgcn_sched_barrier(0); AT_MMV(va, 2); __builtin_amdgcn_sched_barrier(0);
;         AT_MMV(vb2, 3); }
;     ...
;     }
;     if (t + 1 < nt) AT_LSTORE(buf ^ 1);
;     __syncthreads();
	v_mfma_f32_32x32x16_bf16 v[2:17], v[178:181], v[202:205], v[2:17]
	v_exp_f32_e32 v50, v50
	v_exp_f32_e32 v51, v51
	v_exp_f32_e32 v52, v52
	v_exp_f32_e32 v53, v53
	v_exp_f32_e32 v54, v54
	v_exp_f32_e32 v55, v55
	v_exp_f32_e32 v56, v56
	v_exp_f32_e32 v57, v57
	v_pk_add_f32 v[66:67], v[74:75], v[66:67]
	v_pk_add_f32 v[68:69], v[76:77], v[68:69]
	v_mfma_f32_32x32x16_bf16 v[18:33], v[174:177], v[206:209], v[18:33]
	ds_read2_b64 v[170:173], v190 offset0:16 offset1:18
	ds_read2_b64 v[174:177], v190 offset0:20 offset1:22
	v_exp_f32_e32 v58, v58
	v_exp_f32_e32 v59, v59
	v_exp_f32_e32 v60, v60
	v_exp_f32_e32 v61, v61
	v_exp_f32_e32 v62, v62
	v_exp_f32_e32 v63, v63
	v_exp_f32_e32 v64, v64
	v_exp_f32_e32 v65, v65
	v_pk_add_f32 v[66:67], v[78:79], v[66:67]
	v_pk_add_f32 v[68:69], v[80:81], v[68:69]
	v_mfma_f32_32x32x16_bf16 v[2:17], v[182:185], v[206:209], v[2:17]
	ds_read2_b64 v[178:181], v169 offset0:48 offset1:50
	ds_read2_b64 v[182:185], v169 offset0:52 offset1:54
	v_cvt_pk_bf16_f32 v238, v50, v51
	v_cvt_pk_bf16_f32 v239, v52, v53
	v_cvt_pk_bf16_f32 v240, v54, v55
	v_cvt_pk_bf16_f32 v241, v56, v57
	v_cvt_pk_bf16_f32 v242, v58, v59
	v_cvt_pk_bf16_f32 v243, v60, v61
	v_cvt_pk_bf16_f32 v244, v62, v63
	v_cvt_pk_bf16_f32 v245, v64, v65
	v_pk_add_f32 v[66:67], v[68:69], v[66:67]
	s_waitcnt lgkmcnt(2)
	v_mfma_f32_32x32x16_bf16 v[18:33], v[170:173], v[238:241], v[18:33]
	v_pk_fma_f32 v[34:35], v[150:151], v[34:35], v[162:163] op_sel_hi:[1,1,0] neg_lo:[0,0,1] neg_hi:[0,0,1]
	v_pk_fma_f32 v[36:37], v[150:151], v[36:37], v[162:163] op_sel_hi:[1,1,0] neg_lo:[0,0,1] neg_hi:[0,0,1]
	v_pk_fma_f32 v[38:39], v[150:151], v[38:39], v[162:163] op_sel_hi:[1,1,0] neg_lo:[0,0,1] neg_hi:[0,0,1]
	v_pk_fma_f32 v[40:41], v[150:151], v[40:41], v[162:163] op_sel_hi:[1,1,0] neg_lo:[0,0,1] neg_hi:[0,0,1]
	v_pk_fma_f32 v[42:43], v[150:151], v[42:43], v[162:163] op_sel_hi:[1,1,0] neg_lo:[0,0,1] neg_hi:[0,0,1]
	v_pk_fma_f32 v[44:45], v[150:151], v[44:45], v[162:163] op_sel_hi:[1,1,0] neg_lo:[0,0,1] neg_hi:[0,0,1]
	v_pk_fma_f32 v[46:47], v[150:151], v[46:47], v[162:163] op_sel_hi:[1,1,0] neg_lo:[0,0,1] neg_hi:[0,0,1]
	v_pk_fma_f32 v[48:49], v[150:151], v[48:49], v[162:163] op_sel_hi:[1,1,0] neg_lo:[0,0,1] neg_hi:[0,0,1]
	v_pk_add_f32 v[50:51], v[54:55], v[50:51]
	v_pk_add_f32 v[52:53], v[56:57], v[52:53]
	s_waitcnt lgkmcnt(0)
	v_mfma_f32_32x32x16_bf16 v[2:17], v[178:181], v[238:241], v[2:17]
	v_exp_f32_e32 v34, v34
	v_exp_f32_e32 v35, v35
	v_exp_f32_e32 v36, v36
	v_exp_f32_e32 v37, v37
	v_exp_f32_e32 v38, v38
	v_exp_f32_e32 v39, v39
	v_exp_f32_e32 v40, v40
	v_exp_f32_e32 v41, v41
	v_pk_add_f32 v[50:51], v[58:59], v[50:51]
	v_pk_add_f32 v[52:53], v[60:61], v[52:53]
	v_mfma_f32_32x32x16_bf16 v[18:33], v[174:177], v[242:245], v[18:33]
	ds_read2_b64 v[170:173], v190 offset0:24 offset1:26
	ds_read2_b64 v[174:177], v190 offset0:28 offset1:30
	v_exp_f32_e32 v42, v42
	v_exp_f32_e32 v43, v43
	v_exp_f32_e32 v44, v44
	v_exp_f32_e32 v45, v45
	v_exp_f32_e32 v46, v46
	v_exp_f32_e32 v47, v47
	v_exp_f32_e32 v48, v48
	v_exp_f32_e32 v49, v49
	v_pk_add_f32 v[50:51], v[62:63], v[50:51]
	v_pk_add_f32 v[52:53], v[64:65], v[52:53]
	v_mfma_f32_32x32x16_bf16 v[2:17], v[182:185], v[242:245], v[2:17]
	ds_read2_b64 v[178:181], v169 offset0:56 offset1:58
	ds_read2_b64 v[182:185], v169 offset0:60 offset1:62
	v_cvt_pk_bf16_f32 v202, v34, v35
	v_cvt_pk_bf16_f32 v203, v36, v37
	v_cvt_pk_bf16_f32 v204, v38, v39
	v_cvt_pk_bf16_f32 v205, v40, v41
	v_cvt_pk_bf16_f32 v206, v42, v43
	v_cvt_pk_bf16_f32 v207, v44, v45
	v_cvt_pk_bf16_f32 v208, v46, v47
	v_cvt_pk_bf16_f32 v209, v48, v49
	v_pk_add_f32 v[50:51], v[52:53], v[50:51]
	s_waitcnt lgkmcnt(2)
	v_mfma_f32_32x32x16_bf16 v[18:33], v[170:173], v[202:205], v[18:33]
	v_pk_add_f32 v[34:35], v[38:39], v[34:35]
	v_pk_add_f32 v[36:37], v[40:41], v[36:37]
	s_waitcnt lgkmcnt(0)
	v_mfma_f32_32x32x16_bf16 v[2:17], v[178:181], v[202:205], v[2:17]
	v_pk_add_f32 v[34:35], v[42:43], v[34:35]
	v_pk_add_f32 v[36:37], v[44:45], v[36:37]
	v_mfma_f32_32x32x16_bf16 v[18:33], v[174:177], v[206:209], v[18:33]
	v_pk_add_f32 v[34:35], v[46:47], v[34:35]
	v_pk_add_f32 v[36:37], v[48:49], v[36:37]
	s_andn2_b64 vcc, exec, s[4:5]
	v_mfma_f32_32x32x16_bf16 v[2:17], v[182:185], v[206:209], v[2:17]
	v_pk_add_f32 v[34:35], v[36:37], v[34:35]
	v_pk_add_f32 v[66:67], v[66:67], v[82:83]
	s_nop 0
	v_pk_add_f32 v[34:35], v[34:35], v[50:51]
	s_nop 1
	v_pk_add_f32 v[34:35], v[34:35], v[66:67]
	s_cbranch_vccnz .LBB0_758
	s_xor_b32 s1, s1, 1
	s_mul_i32 s1, s1, 0xaa00
	s_add_i32 s1, s1, 0
	v_add3_u32 v169, s1, v134, v137
	s_waitcnt vmcnt(6)
	ds_write_b128 v169, v[126:129]
	v_add3_u32 v169, s1, v136, v161
	s_waitcnt vmcnt(5)
	ds_write_b128 v169, v[122:125]
	v_add3_u32 v169, s1, v140, v163
	s_waitcnt vmcnt(4)
	ds_write_b128 v169, v[130:133]
	s_waitcnt vmcnt(3)
	v_and_b32_e32 v169, 0xffff, v152
	s_waitcnt vmcnt(2)
	v_lshl_or_b32 v170, v154, 16, v169
	s_waitcnt vmcnt(1)
	v_and_b32_e32 v169, 0xffff, v156
	s_waitcnt vmcnt(0)
	v_lshl_or_b32 v171, v158, 16, v169
	v_lshrrev_b32_e32 v169, 16, v152
	v_and_or_b32 v172, v154, s55, v169
	v_lshrrev_b32_e32 v169, 16, v156
	v_and_or_b32 v173, v158, s55, v169
	v_and_b32_e32 v169, 0xffff, v153
	v_lshl_or_b32 v174, v155, 16, v169
	v_and_b32_e32 v169, 0xffff, v157
	v_lshl_or_b32 v175, v159, 16, v169
	v_lshrrev_b32_e32 v169, 16, v153
	v_and_or_b32 v176, v155, s55, v169
	v_lshrrev_b32_e32 v169, 16, v157
	v_and_or_b32 v177, v159, s55, v169
	v_add_u32_e32 v169, s1, v147
	v_add_u32_e32 v169, 0x6800, v169
	ds_write2_b64 v169, v[170:171], v[172:173] offset1:33
	ds_write2_b64 v169, v[174:175], v[176:177] offset0:66 offset1:99
.LBB0_758:
	s_addk_i32 s0, 0x80
	s_cmp_lg_u32 s31, s7
	s_waitcnt lgkmcnt(0)
	s_barrier
	v_add_f32_e32 v34, v34, v35
	s_nop 0
	v_fmac_f32_e32 v34, v167, v160
	s_cbranch_scc0 .LBB0_710
	v_mov_b32_e32 v167, v34
	v_mov_b32_e32 v160, v162
	s_mov_b32 s6, s7
	s_branch .LBB0_752

; #define PG8_STAGE(bufoff, gbase, voff) do { _Pragma("unroll") for (int _i = 0; _i < 2; ++_i) \
;     __builtin_amdgcn_global_load_lds((const unsigned*)((const char*)(gbase) + (voff)[_i]), (LAS unsigned*)(lds + (bufoff) + ldsw + _i * 8192), 16, 0, 0); } while (0)
; #define PG8_LDA(dst, b, h) do { _Pragma("unroll") for (int m = 0; m < 4; ++m) _Pragma("unroll") for (int k = 0; k < 2; ++k) dst[m][k] = *(const LAS bf16x8*)(lds + PG8_SA(b, h) + aoff + m * 2048 + k * 1024); } while (0)
; #define PG8_LDB(dst, b, h) do { _Pragma("unroll") for (int n = 0; n < 2; ++n) _Pragma("unroll") for (int k = 0; k < 2; ++k) dst[n][k] = *(const LAS bf16x8*)(lds + PG8_SB(b, h) + boff + n * 2048 + k * 1024); } while (0)
; #define PG8_MMA(ai, bj, At, Bt) do { __builtin_amdgcn_s_setprio(1); _Pragma("unroll") for (int m = 0; m < 4; ++m) _Pragma("unroll") for (int n = 0; n < 2; ++n) _Pragma("unroll") for (int k = 0; k < 2; ++k) \
;     acc[ai][bj][m][n] = __builtin_amdgcn_mfma_f32_16x16x32_bf16(Bt[n][k], At[m][k], acc[ai][bj][m][n], 0, 0, 0); __builtin_amdgcn_s_setprio(0); } while (0)
; #define PG8_WAIT_V(n) asm volatile("s_waitcnt vmcnt(" #n ")" ::: "memory")
; #define PG8_WAIT_L(n) asm volatile("s_waitcnt lgkmcnt(" #n ")" ::: "memory")
; #define PG8_BAR __builtin_amdgcn_s_barrier()
; #define PG8_SCHED __builtin_amdgcn_sched_barrier(0)
; template <class Epi, class Sched>
; DI void gemm_phase(LAS unsigned char* lds, const int tid, const Gemm g, const Sched& S, const Epi& E) {
;     ...
;       PG8_LDB(B0, 0, 0); PG8_SCHED; PG8_LDA(At, 0, 0); PG8_STAGE(PG8_SA(1, 1), a1 + hstepA, voffA);
;       PG8_WAIT_L(8); PG8_BAR; PG8_WAIT_L(0); PG8_MMA(0, 0, At, B0); PG8_BAR; PG8_SCHED;
;       PG8_LDB(B1, 0, 1); PG8_STAGE(PG8_SB(0, 0), b2, voffB);
;       PG8_BAR; PG8_WAIT_L(0); PG8_MMA(0, 1, At, B1); PG8_BAR;
;       PG8_LDA(At, 0, 1); PG8_STAGE(PG8_SA(0, 0), a2, voffA);
;       PG8_BAR; PG8_WAIT_L(0); PG8_MMA(1, 0, At, B0); PG8_BAR; PG8_SCHED;
;       PG8_STAGE(PG8_SB(0, 1), b2 + hstepB, voffB);
;       PG8_WAIT_V(6); PG8_BAR; PG8_MMA(1, 1, At, B1); PG8_BAR;
.LBB0_824:
	s_add_i32 s88, s14, 2
	s_add_u32 s34, s30, 0x80
	s_addc_u32 s15, s31, 0
	s_add_i32 s89, 0, 0x10000
	v_add_u32_e32 v0, s89, v202
	ds_read_b128 v[130:133], v0
	ds_read_b128 v[134:137], v0 offset:1024
	ds_read_b128 v[138:141], v0 offset:2048
	ds_read_b128 v[142:145], v0 offset:3072
	s_cmp_eq_u32 s78, s14
	s_cselect_b32 s14, s0, s34
	s_cselect_b32 s15, s1, s15
	s_cselect_b32 s35, s7, s39
	s_cselect_b32 s34, s6, s38
	s_add_i32 m0, s58, 0xc000
	ds_read_b128 v[146:149], v203
	ds_read_b128 v[150:153], v203 offset:1024
	ds_read_b128 v[154:157], v203 offset:2048
	ds_read_b128 v[166:169], v203 offset:3072
	ds_read_b128 v[170:173], v203 offset:4096
	ds_read_b128 v[174:177], v203 offset:5120
	ds_read_b128 v[178:181], v203 offset:6144
	ds_read_b128 v[182:185], v203 offset:7168
	global_load_lds_dwordx4 v164, s[30:31]
	s_add_i32 m0, s58, 0xe000
	s_nop 0
	global_load_lds_dwordx4 v162, s[30:31]
	s_waitcnt lgkmcnt(8)
	s_barrier
	s_waitcnt lgkmcnt(0)
	s_setprio 1
	s_waitcnt lgkmcnt(0)
	v_mfma_f32_16x16x32_bf16 v[126:129], v[130:133], v[146:149], v[126:129]
	v_mfma_f32_16x16x32_bf16 v[122:125], v[138:141], v[146:149], v[122:125]
	v_mfma_f32_16x16x32_bf16 v[118:121], v[130:133], v[154:157], v[118:121]
	v_mfma_f32_16x16x32_bf16 v[106:109], v[138:141], v[154:157], v[106:109]
	v_mfma_f32_16x16x32_bf16 v[102:105], v[130:133], v[170:173], v[102:105]
	v_mfma_f32_16x16x32_bf16 v[90:93], v[138:141], v[170:173], v[90:93]
	v_mfma_f32_16x16x32_bf16 v[82:85], v[130:133], v[178:181], v[82:85]
	v_mfma_f32_16x16x32_bf16 v[74:77], v[138:141], v[178:181], v[74:77]
	v_mfma_f32_16x16x32_bf16 v[126:129], v[134:137], v[150:153], v[126:129]
	v_mfma_f32_16x16x32_bf16 v[122:125], v[142:145], v[150:153], v[122:125]
	v_mfma_f32_16x16x32_bf16 v[118:121], v[134:137], v[166:169], v[118:121]
	v_mfma_f32_16x16x32_bf16 v[106:109], v[142:145], v[166:169], v[106:109]
	v_mfma_f32_16x16x32_bf16 v[102:105], v[134:137], v[174:177], v[102:105]
	v_mfma_f32_16x16x32_bf16 v[90:93], v[142:145], v[174:177], v[90:93]
	v_mfma_f32_16x16x32_bf16 v[82:85], v[134:137], v[182:185], v[82:85]
	v_mfma_f32_16x16x32_bf16 v[74:77], v[142:145], v[182:185], v[74:77]
	s_setprio 0
	s_barrier
	s_add_i32 s90, 0, 0x14000
	s_add_i32 s89, s89, s53
	v_add_u32_e32 v0, s90, v202
	s_add_u32 s98, s34, s50
	s_addc_u32 s99, s35, s51
	s_mov_b32 m0, s89
	ds_read_b128 v[198:201], v0
	ds_read_b128 v[204:207], v0 offset:1024
	ds_read_b128 v[208:211], v0 offset:2048
	ds_read_b128 v[216:219], v0 offset:3072
	global_load_lds_dwordx4 v160, s[34:35]
	s_add_i32 m0, s89, 0x2000
	s_nop 0
	global_load_lds_dwordx4 v158, s[34:35]
	s_barrier
	s_waitcnt lgkmcnt(0)
	s_setprio 1
	s_waitcnt lgkmcnt(0)
	v_mfma_f32_16x16x32_bf16 v[114:117], v[198:201], v[146:149], v[114:117]
	v_mfma_f32_16x16x32_bf16 v[110:113], v[208:211], v[146:149], v[110:113]
	v_mfma_f32_16x16x32_bf16 v[98:101], v[198:201], v[154:157], v[98:101]
	v_mfma_f32_16x16x32_bf16 v[94:97], v[208:211], v[154:157], v[94:97]
	v_mfma_f32_16x16x32_bf16 v[86:89], v[198:201], v[170:173], v[86:89]
	v_mfma_f32_16x16x32_bf16 v[78:81], v[208:211], v[170:173], v[78:81]
	v_mfma_f32_16x16x32_bf16 v[70:73], v[198:201], v[178:181], v[70:73]
	v_mfma_f32_16x16x32_bf16 v[66:69], v[208:211], v[178:181], v[66:69]
	v_mfma_f32_16x16x32_bf16 v[114:117], v[204:207], v[150:153], v[114:117]
	v_mfma_f32_16x16x32_bf16 v[110:113], v[216:219], v[150:153], v[110:113]
	v_mfma_f32_16x16x32_bf16 v[98:101], v[204:207], v[166:169], v[98:101]
	v_mfma_f32_16x16x32_bf16 v[94:97], v[216:219], v[166:169], v[94:97]
	v_mfma_f32_16x16x32_bf16 v[86:89], v[204:207], v[174:177], v[86:89]
	v_mfma_f32_16x16x32_bf16 v[78:81], v[216:219], v[174:177], v[78:81]
	v_mfma_f32_16x16x32_bf16 v[70:73], v[204:207], v[182:185], v[70:73]
	v_mfma_f32_16x16x32_bf16 v[66:69], v[216:219], v[182:185], v[66:69]
	s_setprio 0
	s_mov_b32 m0, s58
	s_add_u32 s100, s14, s50
	s_addc_u32 s101, s15, s51
	s_barrier
	ds_read_b128 v[146:149], v203 offset:16384
	ds_read_b128 v[150:153], v203 offset:17408
	ds_read_b128 v[154:157], v203 offset:18432
	ds_read_b128 v[166:169], v203 offset:19456
	ds_read_b128 v[170:173], v203 offset:20480
	ds_read_b128 v[174:177], v203 offset:21504
	ds_read_b128 v[178:181], v203 offset:22528
	ds_read_b128 v[182:185], v203 offset:23552
	global_load_lds_dwordx4 v160, s[14:15]
	s_mov_b32 m0, s59
	s_nop 0
	global_load_lds_dwordx4 v158, s[14:15]
	s_barrier
	s_waitcnt lgkmcnt(0)
	s_setprio 1
	s_waitcnt lgkmcnt(0)
	v_mfma_f32_16x16x32_bf16 v[62:65], v[130:133], v[146:149], v[62:65]
	v_mfma_f32_16x16x32_bf16 v[58:61], v[138:141], v[146:149], v[58:61]
	v_mfma_f32_16x16x32_bf16 v[54:57], v[130:133], v[154:157], v[54:57]
	v_mfma_f32_16x16x32_bf16 v[42:45], v[138:141], v[154:157], v[42:45]
	v_mfma_f32_16x16x32_bf16 v[38:41], v[130:133], v[170:173], v[38:41]
	v_mfma_f32_16x16x32_bf16 v[26:29], v[138:141], v[170:173], v[26:29]
	v_mfma_f32_16x16x32_bf16 v[22:25], v[130:133], v[178:181], v[22:25]
	v_mfma_f32_16x16x32_bf16 v[14:17], v[138:141], v[178:181], v[14:17]
	v_mfma_f32_16x16x32_bf16 v[62:65], v[134:137], v[150:153], v[62:65]
	v_mfma_f32_16x16x32_bf16 v[58:61], v[142:145], v[150:153], v[58:61]
	v_mfma_f32_16x16x32_bf16 v[54:57], v[134:137], v[166:169], v[54:57]
	v_mfma_f32_16x16x32_bf16 v[42:45], v[142:145], v[166:169], v[42:45]
	v_mfma_f32_16x16x32_bf16 v[38:41], v[134:137], v[174:177], v[38:41]
	v_mfma_f32_16x16x32_bf16 v[26:29], v[142:145], v[174:177], v[26:29]
	v_mfma_f32_16x16x32_bf16 v[22:25], v[134:137], v[182:185], v[22:25]
	v_mfma_f32_16x16x32_bf16 v[14:17], v[142:145], v[182:185], v[14:17]
	s_setprio 0
	s_barrier
; #define PG8_STAGE(bufoff, gbase, voff) do { _Pragma("unroll") for (int _i = 0; _i < 2; ++_i) \
;     __builtin_amdgcn_global_load_lds((const unsigned*)((const char*)(gbase) + (voff)[_i]), (LAS unsigned*)(lds + (bufoff) + ldsw + _i * 8192), 16, 0, 0); } while (0)
; #define PG8_LDA(dst, b, h) do { _Pragma("unroll") for (int m = 0; m < 4; ++m) _Pragma("unroll") for (int k = 0; k < 2; ++k) dst[m][k] = *(const LAS bf16x8*)(lds + PG8_SA(b, h) + aoff + m * 2048 + k * 1024); } while (0)
; #define PG8_LDB(dst, b, h) do { _Pragma("unroll") for (int n = 0; n < 2; ++n) _Pragma("unroll") for (int k = 0; k < 2; ++k) dst[n][k] = *(const LAS bf16x8*)(lds + PG8_SB(b, h) + boff + n * 2048 + k * 1024); } while (0)
; #define PG8_MMA(ai, bj, At, Bt) do { __builtin_amdgcn_s_setprio(1); _Pragma("unroll") for (int m = 0; m < 4; ++m) _Pragma("unroll") for (int n = 0; n < 2; ++n) _Pragma("unroll") for (int k = 0; k < 2; ++k) \
;     acc[ai][bj][m][n] = __builtin_amdgcn_mfma_f32_16x16x32_bf16(Bt[n][k], At[m][k], acc[ai][bj][m][n], 0, 0, 0); __builtin_amdgcn_s_setprio(0); } while (0)
; #define PG8_WAIT_V(n) asm volatile("s_waitcnt vmcnt(" #n ")" ::: "memory")
; #define PG8_WAIT_L(n) asm volatile("s_waitcnt lgkmcnt(" #n ")" ::: "memory")
; #define PG8_BAR __builtin_amdgcn_s_barrier()
; #define PG8_SCHED __builtin_amdgcn_sched_barrier(0)
; template <class Epi, class Sched>
; DI void gemm_phase(LAS unsigned char* lds, const int tid, const Gemm g, const Sched& S, const Epi& E) {
;     ...
;       PG8_STAGE(PG8_SB(0, 1), b2 + hstepB, voffB);
;       PG8_WAIT_V(6); PG8_BAR; PG8_MMA(1, 1, At, B1); PG8_BAR;
;       PG8_LDB(B0, 1, 0); PG8_SCHED; PG8_LDA(At, 1, 0); PG8_STAGE(PG8_SA(0, 1), a2 + hstepA, voffA);
;       PG8_WAIT_L(8); PG8_BAR; PG8_WAIT_L(0); PG8_MMA(0, 0, At, B0); PG8_BAR; PG8_SCHED;
;       PG8_LDB(B1, 1, 1); PG8_STAGE(PG8_SB(1, 0), b3, voffB);
;       PG8_BAR; PG8_WAIT_L(0); PG8_MMA(0, 1, At, B1); PG8_BAR;
;       PG8_LDA(At, 1, 1); PG8_STAGE(PG8_SA(1, 0), a3, voffA);
;       PG8_BAR; PG8_WAIT_L(0); PG8_MMA(1, 0, At, B0); PG8_BAR; PG8_SCHED;
	s_add_u32 s34, s34, s20
	s_addc_u32 s35, s35, 0
	s_add_i32 s89, s90, s53
	v_lshl_add_u64 v[226:227], s[34:35], 0, v[160:161]
	s_mov_b32 m0, s89
	v_lshl_add_u64 v[228:229], s[34:35], 0, v[158:159]
	global_load_lds_dwordx4 v[226:227], off
	s_add_i32 m0, s89, 0x2000
	s_nop 0
	global_load_lds_dwordx4 v[228:229], off
	s_waitcnt vmcnt(6)
	s_barrier
	s_setprio 1
	v_mfma_f32_16x16x32_bf16 v[50:53], v[198:201], v[146:149], v[50:53]
	v_mfma_f32_16x16x32_bf16 v[46:49], v[208:211], v[146:149], v[46:49]
	v_mfma_f32_16x16x32_bf16 v[34:37], v[198:201], v[154:157], v[34:37]
	v_mfma_f32_16x16x32_bf16 v[30:33], v[208:211], v[154:157], v[30:33]
	v_mfma_f32_16x16x32_bf16 v[18:21], v[198:201], v[170:173], v[18:21]
	v_mfma_f32_16x16x32_bf16 v[10:13], v[208:211], v[170:173], v[10:13]
	v_mfma_f32_16x16x32_bf16 v[6:9], v[198:201], v[178:181], v[6:9]
	v_mfma_f32_16x16x32_bf16 v[2:5], v[208:211], v[178:181], v[2:5]
	v_mfma_f32_16x16x32_bf16 v[50:53], v[204:207], v[150:153], v[50:53]
	v_mfma_f32_16x16x32_bf16 v[46:49], v[216:219], v[150:153], v[46:49]
	v_mfma_f32_16x16x32_bf16 v[34:37], v[204:207], v[166:169], v[34:37]
	v_mfma_f32_16x16x32_bf16 v[30:33], v[216:219], v[166:169], v[30:33]
	v_mfma_f32_16x16x32_bf16 v[18:21], v[204:207], v[174:177], v[18:21]
	v_mfma_f32_16x16x32_bf16 v[10:13], v[216:219], v[174:177], v[10:13]
	v_mfma_f32_16x16x32_bf16 v[6:9], v[204:207], v[182:185], v[6:9]
	v_mfma_f32_16x16x32_bf16 v[2:5], v[216:219], v[182:185], v[2:5]
	s_setprio 0
	s_add_i32 s34, 0, 0x18000
	v_add_u32_e32 v0, s34, v202
	s_barrier
	ds_read_b128 v[130:133], v0
	ds_read_b128 v[134:137], v0 offset:1024
	ds_read_b128 v[138:141], v0 offset:2048
	ds_read_b128 v[142:145], v0 offset:3072
	s_add_u32 s14, s14, s20
	s_addc_u32 s15, s15, 0
	s_mov_b32 m0, s60
	ds_read_b128 v[146:149], v203 offset:32768
	ds_read_b128 v[150:153], v203 offset:33792
	ds_read_b128 v[154:157], v203 offset:34816
	ds_read_b128 v[166:169], v203 offset:35840
	ds_read_b128 v[170:173], v203 offset:36864
	ds_read_b128 v[174:177], v203 offset:37888
	ds_read_b128 v[178:181], v203 offset:38912
	ds_read_b128 v[182:185], v203 offset:39936
	global_load_lds_dwordx4 v160, s[14:15]
	s_mov_b32 m0, s61
	s_nop 0
	global_load_lds_dwordx4 v158, s[14:15]
	s_waitcnt lgkmcnt(8)
	s_barrier
	s_waitcnt lgkmcnt(0)
	s_setprio 1
	s_waitcnt lgkmcnt(0)
	v_mfma_f32_16x16x32_bf16 v[126:129], v[130:133], v[146:149], v[126:129]
	v_mfma_f32_16x16x32_bf16 v[122:125], v[138:141], v[146:149], v[122:125]
	v_mfma_f32_16x16x32_bf16 v[118:121], v[130:133], v[154:157], v[118:121]
	v_mfma_f32_16x16x32_bf16 v[106:109], v[138:141], v[154:157], v[106:109]
	v_mfma_f32_16x16x32_bf16 v[102:105], v[130:133], v[170:173], v[102:105]
	v_mfma_f32_16x16x32_bf16 v[90:93], v[138:141], v[170:173], v[90:93]
	v_mfma_f32_16x16x32_bf16 v[82:85], v[130:133], v[178:181], v[82:85]
	v_mfma_f32_16x16x32_bf16 v[74:77], v[138:141], v[178:181], v[74:77]
	v_mfma_f32_16x16x32_bf16 v[126:129], v[134:137], v[150:153], v[126:129]
	v_mfma_f32_16x16x32_bf16 v[122:125], v[142:145], v[150:153], v[122:125]
	v_mfma_f32_16x16x32_bf16 v[118:121], v[134:137], v[166:169], v[118:121]
	v_mfma_f32_16x16x32_bf16 v[106:109], v[142:145], v[166:169], v[106:109]
	v_mfma_f32_16x16x32_bf16 v[102:105], v[134:137], v[174:177], v[102:105]
	v_mfma_f32_16x16x32_bf16 v[90:93], v[142:145], v[174:177], v[90:93]
	v_mfma_f32_16x16x32_bf16 v[82:85], v[134:137], v[182:185], v[82:85]
	v_mfma_f32_16x16x32_bf16 v[74:77], v[142:145], v[182:185], v[74:77]
	s_setprio 0
	s_barrier
	s_add_i32 s14, 0, 0x1c000
	s_add_i32 s15, s34, s53
	v_add_u32_e32 v0, s14, v202
	s_mov_b32 m0, s15
	ds_read_b128 v[198:201], v0
	ds_read_b128 v[204:207], v0 offset:1024
	ds_read_b128 v[208:211], v0 offset:2048
	ds_read_b128 v[216:219], v0 offset:3072
	global_load_lds_dwordx4 v160, s[98:99]
	s_add_i32 m0, s15, 0x2000
	s_nop 0
	global_load_lds_dwordx4 v158, s[98:99]
	s_barrier
	s_waitcnt lgkmcnt(0)
	s_setprio 1
	s_waitcnt lgkmcnt(0)
	v_mfma_f32_16x16x32_bf16 v[114:117], v[198:201], v[146:149], v[114:117]
	v_mfma_f32_16x16x32_bf16 v[110:113], v[208:211], v[146:149], v[110:113]
	v_mfma_f32_16x16x32_bf16 v[98:101], v[198:201], v[154:157], v[98:101]
	v_mfma_f32_16x16x32_bf16 v[94:97], v[208:211], v[154:157], v[94:97]
	v_mfma_f32_16x16x32_bf16 v[86:89], v[198:201], v[170:173], v[86:89]
	v_mfma_f32_16x16x32_bf16 v[78:81], v[208:211], v[170:173], v[78:81]
	v_mfma_f32_16x16x32_bf16 v[70:73], v[198:201], v[178:181], v[70:73]
	v_mfma_f32_16x16x32_bf16 v[66:69], v[208:211], v[178:181], v[66:69]
	v_mfma_f32_16x16x32_bf16 v[114:117], v[204:207], v[150:153], v[114:117]
	v_mfma_f32_16x16x32_bf16 v[110:113], v[216:219], v[150:153], v[110:113]
	v_mfma_f32_16x16x32_bf16 v[98:101], v[204:207], v[166:169], v[98:101]
	v_mfma_f32_16x16x32_bf16 v[94:97], v[216:219], v[166:169], v[94:97]
	v_mfma_f32_16x16x32_bf16 v[86:89], v[204:207], v[174:177], v[86:89]
	v_mfma_f32_16x16x32_bf16 v[78:81], v[216:219], v[174:177], v[78:81]
	v_mfma_f32_16x16x32_bf16 v[70:73], v[204:207], v[182:185], v[70:73]
	v_mfma_f32_16x16x32_bf16 v[66:69], v[216:219], v[182:185], v[66:69]
	s_setprio 0
	s_mov_b32 m0, s75
	s_barrier
	ds_read_b128 v[146:149], v203 offset:49152
	ds_read_b128 v[150:153], v203 offset:50176
	ds_read_b128 v[154:157], v203 offset:51200
	ds_read_b128 v[166:169], v203 offset:52224
	ds_read_b128 v[170:173], v203 offset:53248
	ds_read_b128 v[174:177], v203 offset:54272
	ds_read_b128 v[178:181], v203 offset:55296
	ds_read_b128 v[182:185], v203 offset:56320
	global_load_lds_dwordx4 v160, s[100:101]
	s_mov_b32 m0, s76
	s_nop 0
	global_load_lds_dwordx4 v158, s[100:101]
	s_barrier
; #define GAS __attribute__((address_space(1)))
; #define PG8_STAGE(bufoff, gbase, voff) do { _Pragma("unroll") for (int _i = 0; _i < 2; ++_i) \
;     __builtin_amdgcn_global_load_lds((const unsigned*)((const char*)(gbase) + (voff)[_i]), (LAS unsigned*)(lds + (bufoff) + ldsw + _i * 8192), 16, 0, 0); } while (0)
; #define PG8_MMA(ai, bj, At, Bt) do { __builtin_amdgcn_s_setprio(1); _Pragma("unroll") for (int m = 0; m < 4; ++m) _Pragma("unroll") for (int n = 0; n < 2; ++n) _Pragma("unroll") for (int k = 0; k < 2; ++k) \
;     acc[ai][bj][m][n] = __builtin_amdgcn_mfma_f32_16x16x32_bf16(Bt[n][k], At[m][k], acc[ai][bj][m][n], 0, 0, 0); __builtin_amdgcn_s_setprio(0); } while (0)
; #define PG8_WAIT_V(n) asm volatile("s_waitcnt vmcnt(" #n ")" ::: "memory")
; #define PG8_WAIT_L(n) asm volatile("s_waitcnt lgkmcnt(" #n ")" ::: "memory")
; #define PG8_BAR __builtin_amdgcn_s_barrier()
; #define PG8_SCHED __builtin_amdgcn_sched_barrier(0)
; #define ROWS_LOOP _Pragma("unroll") for (int ai = 0; ai < 2; ++ai) _Pragma("unroll") for (int m = 0; m < 4; ++m)
; #define COLS_LOOP _Pragma("unroll") for (int bj = 0; bj < 2; ++bj) _Pragma("unroll") for (int n = 0; n < 2; ++n)
; template <class Epi, class Sched>
; DI void gemm_phase(LAS unsigned char* lds, const int tid, const Gemm g, const Sched& S, const Epi& E) {
;     ...
;       PG8_BAR; PG8_WAIT_L(0); PG8_MMA(1, 0, At, B0); PG8_BAR; PG8_SCHED;
;       PG8_STAGE(PG8_SB(1, 1), b3 + hstepB, voffB);
;       PG8_WAIT_V(6); PG8_BAR; PG8_MMA(1, 1, At, B1); PG8_BAR;
;     }
;   DI void operator()(const AccT& acc, const Unit& u, int wr, int wc, int fr, int fq) const {
;     const int b = u.pm < 128 ? (u.pm >> 3) : 16;
;     const unsigned c0 = (unsigned)(wc * 32 + fq * 4) * 4u, o0 = (unsigned)((wr * 64 + fr) * D) * 4u + c0;
;     if (pctx) {
;       char* pb = (char*)(pctx + (size_t)(u.pm - 128) * 256 * D + u.pn * 256);
;       ROWS_LOOP {
;         char* rb = pb + (size_t)(ai * 128 + m * 16) * D * 4;
;         COLS_LOOP *(GAS f32x4*)(rb + (bj * 128 + n * 16) * 4 + o0) = acc[ai][bj][m][n];
;       }
;       return;
	s_waitcnt lgkmcnt(0)
	s_setprio 1
	s_waitcnt lgkmcnt(0)
	v_mfma_f32_16x16x32_bf16 v[62:65], v[130:133], v[146:149], v[62:65]
	v_mfma_f32_16x16x32_bf16 v[58:61], v[138:141], v[146:149], v[58:61]
	v_mfma_f32_16x16x32_bf16 v[54:57], v[130:133], v[154:157], v[54:57]
	v_mfma_f32_16x16x32_bf16 v[42:45], v[138:141], v[154:157], v[42:45]
	v_mfma_f32_16x16x32_bf16 v[38:41], v[130:133], v[170:173], v[38:41]
	v_mfma_f32_16x16x32_bf16 v[26:29], v[138:141], v[170:173], v[26:29]
	v_mfma_f32_16x16x32_bf16 v[22:25], v[130:133], v[178:181], v[22:25]
	v_mfma_f32_16x16x32_bf16 v[14:17], v[138:141], v[178:181], v[14:17]
	v_mfma_f32_16x16x32_bf16 v[62:65], v[134:137], v[150:153], v[62:65]
	v_mfma_f32_16x16x32_bf16 v[58:61], v[142:145], v[150:153], v[58:61]
	v_mfma_f32_16x16x32_bf16 v[54:57], v[134:137], v[166:169], v[54:57]
	v_mfma_f32_16x16x32_bf16 v[42:45], v[142:145], v[166:169], v[42:45]
	v_mfma_f32_16x16x32_bf16 v[38:41], v[134:137], v[174:177], v[38:41]
	v_mfma_f32_16x16x32_bf16 v[26:29], v[142:145], v[174:177], v[26:29]
	v_mfma_f32_16x16x32_bf16 v[22:25], v[134:137], v[182:185], v[22:25]
	v_mfma_f32_16x16x32_bf16 v[14:17], v[142:145], v[182:185], v[14:17]
	s_setprio 0
	s_barrier
	s_add_i32 s14, s14, s53
	v_lshl_add_u64 v[130:131], v[226:227], 0, s[50:51]
	s_mov_b32 m0, s14
	s_nop 0
	global_load_lds_dwordx4 v[130:131], off
	v_lshl_add_u64 v[130:131], v[228:229], 0, s[50:51]
	s_add_i32 m0, s14, 0x2000
	s_nop 0
	global_load_lds_dwordx4 v[130:131], off
	s_waitcnt vmcnt(6)
	s_barrier
	s_setprio 1
	v_mfma_f32_16x16x32_bf16 v[50:53], v[198:201], v[146:149], v[50:53]
	v_mfma_f32_16x16x32_bf16 v[46:49], v[208:211], v[146:149], v[46:49]
	v_mfma_f32_16x16x32_bf16 v[34:37], v[198:201], v[154:157], v[34:37]
	v_mfma_f32_16x16x32_bf16 v[30:33], v[208:211], v[154:157], v[30:33]
	v_mfma_f32_16x16x32_bf16 v[18:21], v[198:201], v[170:173], v[18:21]
	v_mfma_f32_16x16x32_bf16 v[10:13], v[208:211], v[170:173], v[10:13]
	v_mfma_f32_16x16x32_bf16 v[6:9], v[198:201], v[178:181], v[6:9]
	v_mfma_f32_16x16x32_bf16 v[2:5], v[208:211], v[178:181], v[2:5]
	v_mfma_f32_16x16x32_bf16 v[50:53], v[204:207], v[150:153], v[50:53]
	v_mfma_f32_16x16x32_bf16 v[46:49], v[216:219], v[150:153], v[46:49]
	v_mfma_f32_16x16x32_bf16 v[34:37], v[204:207], v[166:169], v[34:37]
	v_mfma_f32_16x16x32_bf16 v[30:33], v[216:219], v[166:169], v[30:33]
	v_mfma_f32_16x16x32_bf16 v[18:21], v[204:207], v[174:177], v[18:21]
	v_mfma_f32_16x16x32_bf16 v[10:13], v[216:219], v[174:177], v[10:13]
	v_mfma_f32_16x16x32_bf16 v[6:9], v[204:207], v[182:185], v[6:9]
	v_mfma_f32_16x16x32_bf16 v[2:5], v[216:219], v[182:185], v[2:5]
	s_setprio 0
	s_add_u32 s38, s38, 0x100
	s_addc_u32 s39, s39, 0
	s_add_u32 s30, s30, 0x100
	s_addc_u32 s31, s31, 0
	s_cmp_ge_u32 s88, s74
	s_mov_b32 s14, s88
	s_barrier
	s_cbranch_scc0 .LBB0_824
	s_cmpk_lt_i32 s86, 0x80
	v_mov_b32_e32 v0, 0
	s_cselect_b64 s[30:31], -1, 0
	s_cmpk_gt_i32 s86, 0x7f
	s_mov_b64 s[14:15], 0x24000
	s_cbranch_scc1 .LBB0_827
	s_ashr_i32 s14, s86, 3
	s_mul_hi_i32 s15, s14, 0x2400
	s_mulk_i32 s14, 0x2400
.LBB0_827:
	v_mbcnt_lo_u32_b32 v0, -1, v0
	v_mbcnt_hi_u32_b32 v0, -1, v0
	v_and_b32_e32 v130, -16, v0
	v_lshlrev_b32_e32 v0, 12, v0
	v_and_b32_e32 v0, 0xf000, v0
	v_add_u32_e32 v130, s79, v130
	v_or_b32_e32 v0, s80, v0
	v_add_u32_e32 v0, v0, v130
	s_add_i32 s34, s86, 0xffffff80
	s_andn2_b64 vcc, exec, s[28:29]
	s_mov_b64 s[38:39], -1
	s_cbranch_vccnz .LBB0_829
	s_ashr_i32 s35, s34, 31
	s_lshl_b64 s[38:39], s[34:35], 20
	s_add_u32 s35, s73, s38
	s_addc_u32 s88, s67, s39
	s_lshl_b32 s38, s87, 8
	s_ashr_i32 s39, s38, 31
	s_lshl_b64 s[38:39], s[38:39], 2
	s_add_u32 s38, s35, s38
	s_addc_u32 s39, s88, s39
	v_lshl_add_u64 v[166:167], s[38:39], 0, v[0:1]
	v_add_co_u32_e32 v132, vcc, s68, v166
	global_store_dwordx4 v0, v[126:129], s[38:39]
	global_store_dwordx4 v0, v[122:125], s[38:39] offset:64
	global_store_dwordx4 v0, v[114:117], s[38:39] offset:512
	global_store_dwordx4 v0, v[110:113], s[38:39] offset:576
	v_addc_co_u32_e32 v133, vcc, 0, v167, vcc
	global_store_dwordx4 v[132:133], v[118:121], off
	global_store_dwordx4 v[132:133], v[106:109], off offset:64
	global_store_dwordx4 v[132:133], v[98:101], off offset:512
	global_store_dwordx4 v[132:133], v[94:97], off offset:576
	v_add_co_u32_e32 v132, vcc, s71, v166
	s_mov_b64 s[38:39], 0
	s_nop 0
	v_addc_co_u32_e32 v133, vcc, 0, v167, vcc
	global_store_dwordx4 v[132:133], v[102:105], off
	global_store_dwordx4 v[132:133], v[90:93], off offset:64
	global_store_dwordx4 v[132:133], v[86:89], off offset:512
	global_store_dwordx4 v[132:133], v[78:81], off offset:576
	v_add_co_u32_e32 v132, vcc, s69, v166
	s_nop 1
	v_addc_co_u32_e32 v133, vcc, 0, v167, vcc
	global_store_dwordx4 v[132:133], v[82:85], off
	global_store_dwordx4 v[132:133], v[74:77], off offset:64
	global_store_dwordx4 v[132:133], v[70:73], off offset:512
	global_store_dwordx4 v[132:133], v[66:69], off offset:576
	v_add_co_u32_e32 v132, vcc, s33, v166
	s_nop 1
	v_addc_co_u32_e32 v133, vcc, 0, v167, vcc
	global_store_dwordx4 v[132:133], v[62:65], off
	global_store_dwordx4 v[132:133], v[58:61], off offset:64
	global_store_dwordx4 v[132:133], v[50:53], off offset:512
	global_store_dwordx4 v[132:133], v[46:49], off offset:576
	v_add_co_u32_e32 v132, vcc, 0x90000, v166
	s_nop 1
	v_addc_co_u32_e32 v133, vcc, 0, v167, vcc
	global_store_dwordx4 v[132:133], v[54:57], off
	global_store_dwordx4 v[132:133], v[42:45], off offset:64
	global_store_dwordx4 v[132:133], v[34:37], off offset:512
	global_store_dwordx4 v[132:133], v[30:33], off offset:576
	v_add_co_u32_e32 v132, vcc, 0xa0000, v166
	s_nop 1
	v_addc_co_u32_e32 v133, vcc, 0, v167, vcc
	global_store_dwordx4 v[132:133], v[38:41], off
	global_store_dwordx4 v[132:133], v[26:29], off offset:64
	global_store_dwordx4 v[132:133], v[18:21], off offset:512
	global_store_dwordx4 v[132:133], v[10:13], off offset:576
	v_add_co_u32_e32 v132, vcc, 0xb0000, v166
	s_nop 1
	v_addc_co_u32_e32 v133, vcc, 0, v167, vcc
	global_store_dwordx4 v[132:133], v[22:25], off
	global_store_dwordx4 v[132:133], v[14:17], off offset:64
	global_store_dwordx4 v[132:133], v[6:9], off offset:512
; #define GAS __attribute__((address_space(1)))
; #define COLS_LOOP _Pragma("unroll") for (int bj = 0; bj < 2; ++bj) _Pragma("unroll") for (int n = 0; n < 2; ++n)
;   DI void operator()(const AccT& acc, const Unit& u, int wr, int wc, int fr, int fq) const {
;     ...
;     char* hb = (char*)((u.pm < 128 ? out + (size_t)u.pm * 256 * D : hctx + (size_t)(u.pm - 128) * 256 * D) + u.pn * 256);
;     const char* hs = (const char*)((u.pm < 128 ? hsrc + (size_t)u.pm * 256 * D : hctx + (size_t)(u.pm - 128) * 256 * D) + u.pn * 256);
;     const char* gp = (const char*)(gate + (size_t)b * NMODW + u.pn * 256);
;     f32x4 gv[2][2];
;     COLS_LOOP gv[bj][n] = ld4p(gp + (bj * 128 + n * 16) * 4, c0);
;     __builtin_amdgcn_sched_barrier(0);
;     COLS_LOOP gv[bj][n] = gv[bj][n] * coef;
; #pragma unroll
;     for (int ai = 0; ai < 2; ++ai) {
;       f32x4 hv[4][2][2];
; #pragma unroll
;       for (int m = 0; m < 4; ++m) { const char* rs_ = hs + (size_t)(ai * 128 + m * 16) * D * 4;
;         COLS_LOOP hv[m][bj][n] = *(const GAS f32x4*)(rs_ + (bj * 128 + n * 16) * 4 + o0); }
; #pragma unroll
;       for (int m = 0; m < 4; ++m) { char* rb = hb + (size_t)(ai * 128 + m * 16) * D * 4;
;         COLS_LOOP *(GAS f32x4*)(rb + (bj * 128 + n * 16) * 4 + o0) = hv[m][bj][n] + gv[bj][n] * acc[ai][bj][m][n]; }
.LBB0_829:
	s_andn2_b64 vcc, exec, s[38:39]
	s_cbranch_vccnz .LBB0_816
	s_ashr_i32 s35, s86, 31
	s_and_b64 s[38:39], s[30:31], exec
	s_cselect_b32 s35, s35, 0
	s_cselect_b32 s34, s86, s34
	s_cselect_b32 s86, s27, s25
	s_cselect_b32 s88, s26, s24
	s_lshl_b64 s[38:39], s[34:35], 20
	s_add_u32 s88, s88, s38
	s_addc_u32 s89, s86, s39
	s_lshl_b32 s34, s87, 8
	s_ashr_i32 s35, s34, 31
	s_lshl_b64 s[86:87], s[34:35], 2
	s_add_u32 s34, s88, s86
	s_addc_u32 s35, s89, s87
	s_and_b64 s[30:31], s[30:31], exec
	s_cselect_b32 s31, s63, s24
	s_cselect_b32 s30, s62, s25
	s_add_u32 s31, s31, s38
	s_addc_u32 s30, s30, s39
	s_lshl_b64 s[14:15], s[14:15], 2
	s_add_u32 s14, s64, s14
	s_addc_u32 s15, s65, s15
	s_add_u32 s14, s14, s86
	s_addc_u32 s15, s15, s87
	global_load_dwordx4 v[132:135], v130, s[14:15]
	global_load_dwordx4 v[136:139], v130, s[14:15] offset:64
	global_load_dwordx4 v[140:143], v130, s[14:15] offset:512
	global_load_dwordx4 v[144:147], v130, s[14:15] offset:576
	s_add_u32 s14, s31, s86
	s_addc_u32 s15, s30, s87
	v_lshl_add_u64 v[184:185], s[14:15], 0, v[0:1]
	global_load_dwordx4 v[204:207], v0, s[14:15]
	global_load_dwordx4 v[208:211], v0, s[14:15] offset:64
	global_load_dwordx4 v[226:229], v0, s[14:15] offset:512
	global_load_dwordx4 v[238:241], v0, s[14:15] offset:576
	s_mov_b32 s15, 0x10000
	v_add_co_u32_e32 v130, vcc, s15, v184
	s_mov_b32 s30, 0x20000
	s_nop 0
	v_addc_co_u32_e32 v131, vcc, 0, v185, vcc
	global_load_dwordx4 v[242:245], v[130:131], off
	global_load_dwordx4 v[246:249], v[130:131], off offset:64
	global_load_dwordx4 v[216:219], v[130:131], off offset:512
	global_load_dwordx4 v[220:223], v[130:131], off offset:576
	v_add_co_u32_e32 v130, vcc, s30, v184
	s_mov_b32 s14, 0x30000
	s_nop 0
	v_addc_co_u32_e32 v131, vcc, 0, v185, vcc
	s_waitcnt vmcnt(0)
	v_pk_mul_f32 v[168:169], v[146:147], s[12:13]
	global_load_dwordx4 v[198:201], v[130:131], off
	global_load_dwordx4 v[154:157], v[130:131], off offset:64
	global_load_dwordx4 v[150:153], v[130:131], off offset:512
	global_load_dwordx4 v[146:149], v[130:131], off offset:576
	v_add_co_u32_e32 v130, vcc, s14, v184
	v_pk_mul_f32 v[180:181], v[134:135], s[12:13]
	s_nop 0
	v_addc_co_u32_e32 v131, vcc, 0, v185, vcc
	v_pk_mul_f32 v[182:183], v[132:133], s[10:11]
	v_pk_mul_f32 v[176:177], v[138:139], s[12:13]
	v_pk_mul_f32 v[178:179], v[136:137], s[10:11]
	v_pk_mul_f32 v[172:173], v[142:143], s[12:13]
	v_pk_mul_f32 v[174:175], v[140:141], s[10:11]
	v_pk_mul_f32 v[170:171], v[144:145], s[10:11]
	global_load_dwordx4 v[142:145], v[130:131], off
	global_load_dwordx4 v[138:141], v[130:131], off offset:64
	global_load_dwordx4 v[134:137], v[130:131], off offset:512
	s_nop 0
	global_load_dwordx4 v[130:133], v[130:131], off offset:576
	v_lshl_add_u64 v[166:167], s[34:35], 0, v[0:1]
	s_mov_b32 s31, 0xa0000
	s_mov_b32 s68, 0x10000
	s_mov_b32 s71, 0x20000
	s_mov_b32 s69, 0x30000
	s_mov_b32 s33, 0x80000
	v_pk_fma_f32 v[128:129], v[128:129], v[180:181], v[206:207]
	v_pk_fma_f32 v[126:127], v[126:127], v[182:183], v[204:205]
	v_pk_fma_f32 v[116:117], v[116:117], v[172:173], v[228:229]
	v_pk_fma_f32 v[114:115], v[114:115], v[174:175], v[226:227]
	global_store_dwordx4 v0, v[114:117], s[34:35] offset:512
	v_pk_fma_f32 v[112:113], v[112:113], v[168:169], v[240:241]
	v_pk_fma_f32 v[110:111], v[110:111], v[170:171], v[238:239]
	v_add_co_u32_e32 v114, vcc, s15, v166
	v_pk_fma_f32 v[100:101], v[100:101], v[172:173], v[218:219]
	s_nop 0
	v_addc_co_u32_e32 v115, vcc, 0, v167, vcc
	v_pk_fma_f32 v[98:99], v[98:99], v[174:175], v[216:217]
	global_store_dwordx4 v[114:115], v[98:101], off offset:512
	v_pk_fma_f32 v[96:97], v[96:97], v[168:169], v[222:223]
	v_pk_fma_f32 v[94:95], v[94:95], v[170:171], v[220:221]
	v_add_co_u32_e32 v98, vcc, s30, v166
	s_waitcnt vmcnt(0)
; #define GAS __attribute__((address_space(1)))
; #define COLS_LOOP _Pragma("unroll") for (int bj = 0; bj < 2; ++bj) _Pragma("unroll") for (int n = 0; n < 2; ++n)
;   DI void operator()(const AccT& acc, const Unit& u, int wr, int wc, int fr, int fq) const {
;     ...
;     for (int ai = 0; ai < 2; ++ai) {
;       f32x4 hv[4][2][2];
; #pragma unroll
;       for (int m = 0; m < 4; ++m) { const char* rs_ = hs + (size_t)(ai * 128 + m * 16) * D * 4;
;         COLS_LOOP hv[m][bj][n] = *(const GAS f32x4*)(rs_ + (bj * 128 + n * 16) * 4 + o0); }
; #pragma unroll
;       for (int m = 0; m < 4; ++m) { char* rb = hb + (size_t)(ai * 128 + m * 16) * D * 4;
;         COLS_LOOP *(GAS f32x4*)(rb + (bj * 128 + n * 16) * 4 + o0) = hv[m][bj][n] + gv[bj][n] * acc[ai][bj][m][n]; }
	v_pk_fma_f32 v[80:81], v[80:81], v[168:169], v[148:149]
	v_addc_co_u32_e32 v99, vcc, 0, v167, vcc
	v_pk_fma_f32 v[78:79], v[78:79], v[170:171], v[146:147]
	global_store_dwordx4 v[98:99], v[78:81], off offset:576
	s_mov_b32 s15, 0x80000
	v_pk_fma_f32 v[124:125], v[124:125], v[176:177], v[210:211]
	v_pk_fma_f32 v[122:123], v[122:123], v[178:179], v[208:209]
	v_pk_fma_f32 v[78:79], v[82:83], v[182:183], v[142:143]
	v_add_co_u32_e32 v82, vcc, s14, v166
	v_pk_fma_f32 v[68:69], v[68:69], v[168:169], v[132:133]
	s_nop 0
	v_addc_co_u32_e32 v83, vcc, 0, v167, vcc
	v_pk_fma_f32 v[66:67], v[66:67], v[170:171], v[130:131]
	global_store_dwordx4 v0, v[110:113], s[34:35] offset:576
	v_pk_fma_f32 v[108:109], v[108:109], v[176:177], v[248:249]
	v_pk_fma_f32 v[106:107], v[106:107], v[178:179], v[246:247]
	v_pk_fma_f32 v[112:113], v[120:121], v[180:181], v[244:245]
	v_pk_fma_f32 v[110:111], v[118:119], v[182:183], v[242:243]
	global_store_dwordx4 v[114:115], v[94:97], off offset:576
	v_pk_fma_f32 v[92:93], v[92:93], v[176:177], v[156:157]
	v_pk_fma_f32 v[90:91], v[90:91], v[178:179], v[154:155]
	v_pk_fma_f32 v[96:97], v[104:105], v[180:181], v[200:201]
	v_pk_fma_f32 v[94:95], v[102:103], v[182:183], v[198:199]
	v_pk_fma_f32 v[88:89], v[88:89], v[172:173], v[152:153]
	v_pk_fma_f32 v[86:87], v[86:87], v[174:175], v[150:151]
	v_pk_fma_f32 v[80:81], v[84:85], v[180:181], v[144:145]
	v_pk_fma_f32 v[76:77], v[76:77], v[176:177], v[140:141]
	v_pk_fma_f32 v[74:75], v[74:75], v[178:179], v[138:139]
	v_pk_fma_f32 v[72:73], v[72:73], v[172:173], v[136:137]
	v_pk_fma_f32 v[70:71], v[70:71], v[174:175], v[134:135]
	global_store_dwordx4 v[82:83], v[66:69], off offset:576
	global_store_dwordx4 v0, v[126:129], s[34:35]
	global_store_dwordx4 v0, v[122:125], s[34:35] offset:64
	v_add_co_u32_e32 v66, vcc, s15, v184
	global_store_dwordx4 v[114:115], v[110:113], off
	global_store_dwordx4 v[114:115], v[106:109], off offset:64
	global_store_dwordx4 v[98:99], v[94:97], off
	global_store_dwordx4 v[98:99], v[90:93], off offset:64
	global_store_dwordx4 v[98:99], v[86:89], off offset:512
	global_store_dwordx4 v[82:83], v[78:81], off
	global_store_dwordx4 v[82:83], v[74:77], off offset:64
	global_store_dwordx4 v[82:83], v[70:73], off offset:512
	v_addc_co_u32_e32 v67, vcc, 0, v185, vcc
	s_mov_b32 s30, 0x90000
	global_load_dwordx4 v[94:97], v[66:67], off
	global_load_dwordx4 v[98:101], v[66:67], off offset:64
	global_load_dwordx4 v[102:105], v[66:67], off offset:512
	global_load_dwordx4 v[106:109], v[66:67], off offset:576
	v_add_co_u32_e32 v66, vcc, s30, v184
	s_mov_b32 s14, 0xb0000
	s_nop 0
	v_addc_co_u32_e32 v67, vcc, 0, v185, vcc
	global_load_dwordx4 v[110:113], v[66:67], off
	global_load_dwordx4 v[114:117], v[66:67], off offset:64
	global_load_dwordx4 v[118:121], v[66:67], off offset:512
	global_load_dwordx4 v[122:125], v[66:67], off offset:576
	v_add_co_u32_e32 v66, vcc, s31, v184
	s_waitcnt vmcnt(0)
	v_pk_fma_f32 v[62:63], v[62:63], v[182:183], v[94:95]
	v_addc_co_u32_e32 v67, vcc, 0, v185, vcc
	global_load_dwordx4 v[126:129], v[66:67], off
	global_load_dwordx4 v[90:93], v[66:67], off offset:64
	global_load_dwordx4 v[86:89], v[66:67], off offset:512
	global_load_dwordx4 v[82:85], v[66:67], off offset:576
	v_add_co_u32_e32 v66, vcc, s14, v184
	v_pk_fma_f32 v[52:53], v[52:53], v[172:173], v[104:105]
	s_nop 0
	v_addc_co_u32_e32 v67, vcc, 0, v185, vcc
	global_load_dwordx4 v[78:81], v[66:67], off
	global_load_dwordx4 v[74:77], v[66:67], off offset:64
	global_load_dwordx4 v[70:73], v[66:67], off offset:512
	s_nop 0
	global_load_dwordx4 v[66:69], v[66:67], off offset:576
	v_add_co_u32_e32 v94, vcc, s15, v166
	v_pk_fma_f32 v[50:51], v[50:51], v[174:175], v[102:103]
	s_nop 0
	v_addc_co_u32_e32 v95, vcc, 0, v167, vcc
	global_store_dwordx4 v[94:95], v[50:53], off offset:512
	v_pk_fma_f32 v[36:37], v[36:37], v[172:173], v[120:121]
	v_pk_fma_f32 v[34:35], v[34:35], v[174:175], v[118:119]
	v_add_co_u32_e32 v50, vcc, s30, v166
	v_pk_fma_f32 v[48:49], v[48:49], v[168:169], v[108:109]
	s_nop 0
	v_addc_co_u32_e32 v51, vcc, 0, v167, vcc
	global_store_dwordx4 v[50:51], v[34:37], off offset:512
	v_pk_fma_f32 v[46:47], v[46:47], v[170:171], v[106:107]
	v_pk_fma_f32 v[32:33], v[32:33], v[168:169], v[124:125]
	v_add_co_u32_e32 v34, vcc, s31, v166
	v_pk_fma_f32 v[30:31], v[30:31], v[170:171], v[122:123]
	s_nop 0
	v_addc_co_u32_e32 v35, vcc, 0, v167, vcc
	v_pk_fma_f32 v[64:65], v[64:65], v[180:181], v[96:97]
	v_pk_fma_f32 v[60:61], v[60:61], v[176:177], v[100:101]
	v_pk_fma_f32 v[58:59], v[58:59], v[178:179], v[98:99]
	global_store_dwordx4 v[94:95], v[46:49], off offset:576
	v_pk_fma_f32 v[44:45], v[44:45], v[176:177], v[116:117]
	v_pk_fma_f32 v[42:43], v[42:43], v[178:179], v[114:115]
	v_pk_fma_f32 v[48:49], v[56:57], v[180:181], v[112:113]
	v_pk_fma_f32 v[46:47], v[54:55], v[182:183], v[110:111]
	global_store_dwordx4 v[50:51], v[30:33], off offset:576
	global_store_dwordx4 v[94:95], v[62:65], off
	global_store_dwordx4 v[94:95], v[58:61], off offset:64
	global_store_dwordx4 v[50:51], v[46:49], off
	global_store_dwordx4 v[50:51], v[42:45], off offset:64
	s_waitcnt vmcnt(0)
	v_pk_fma_f32 v[32:33], v[40:41], v[180:181], v[128:129]
	v_pk_fma_f32 v[30:31], v[38:39], v[182:183], v[126:127]
	v_pk_fma_f32 v[20:21], v[20:21], v[172:173], v[88:89]
	v_pk_fma_f32 v[18:19], v[18:19], v[174:175], v[86:87]
	global_store_dwordx4 v[34:35], v[18:21], off offset:512
	v_pk_fma_f32 v[12:13], v[12:13], v[168:169], v[84:85]
	v_pk_fma_f32 v[10:11], v[10:11], v[170:171], v[82:83]
	v_add_co_u32_e32 v18, vcc, s14, v166
	global_store_dwordx4 v[34:35], v[10:13], off offset:576
	s_nop 0
	v_addc_co_u32_e32 v19, vcc, 0, v167, vcc
	v_pk_fma_f32 v[12:13], v[24:25], v[180:181], v[80:81]
	v_pk_fma_f32 v[10:11], v[22:23], v[182:183], v[78:79]
	v_pk_fma_f32 v[28:29], v[28:29], v[176:177], v[92:93]
	v_pk_fma_f32 v[26:27], v[26:27], v[178:179], v[90:91]
	global_store_dwordx4 v[18:19], v[10:13], off
	v_pk_fma_f32 v[8:9], v[8:9], v[172:173], v[72:73]
	v_pk_fma_f32 v[6:7], v[6:7], v[174:175], v[70:71]
	v_pk_fma_f32 v[12:13], v[16:17], v[176:177], v[76:77]
	v_pk_fma_f32 v[10:11], v[14:15], v[178:179], v[74:75]
	v_pk_fma_f32 v[4:5], v[4:5], v[168:169], v[68:69]
	v_pk_fma_f32 v[2:3], v[2:3], v[170:171], v[66:67]
	global_store_dwordx4 v[34:35], v[30:33], off
	global_store_dwordx4 v[34:35], v[26:29], off offset:64
	global_store_dwordx4 v[18:19], v[10:13], off offset:64
	global_store_dwordx4 v[18:19], v[6:9], off offset:512
	s_branch .LBB0_816

; __global__ void __launch_bounds__(512, 2) mega(Params p) {
	.amdhsa_kernel _Z4mega6Params
		.amdhsa_group_segment_fixed_size 0
		.amdhsa_private_segment_fixed_size 0
		.amdhsa_kernarg_size 480
		.amdhsa_user_sgpr_count 2
		.amdhsa_user_sgpr_dispatch_ptr 0
		.amdhsa_user_sgpr_queue_ptr 0
		.amdhsa_user_sgpr_kernarg_segment_ptr 1
		.amdhsa_user_sgpr_dispatch_id 0
		.amdhsa_user_sgpr_kernarg_preload_length 0
		.amdhsa_user_sgpr_kernarg_preload_offset 0
		.amdhsa_user_sgpr_private_segment_size 0
		.amdhsa_uses_dynamic_stack 0
		.amdhsa_enable_private_segment 0
		.amdhsa_system_sgpr_workgroup_id_x 1
		.amdhsa_system_sgpr_workgroup_id_y 0
		.amdhsa_system_sgpr_workgroup_id_z 0
		.amdhsa_system_sgpr_workgroup_info 0
		.amdhsa_system_vgpr_workitem_id 2
		.amdhsa_next_free_vgpr 256
		.amdhsa_next_free_sgpr 102
		.amdhsa_accum_offset 256
		.amdhsa_reserve_vcc 1
		.amdhsa_float_round_mode_32 0
		.amdhsa_float_round_mode_16_64 0
		.amdhsa_float_denorm_mode_32 3
		.amdhsa_float_denorm_mode_16_64 3
		.amdhsa_dx10_clamp 1
		.amdhsa_ieee_mode 1
		.amdhsa_fp16_overflow 0
		.amdhsa_tg_split 0
		.amdhsa_exception_fp_ieee_invalid_op 0
		.amdhsa_exception_fp_denorm_src 0
		.amdhsa_exception_fp_ieee_div_zero 0
		.amdhsa_exception_fp_ieee_overflow 0
		.amdhsa_exception_fp_ieee_underflow 0
		.amdhsa_exception_fp_ieee_inexact 0
		.amdhsa_exception_int_div_zero 0
	.end_amdhsa_kernel

; __global__ void __launch_bounds__(512, 2) mega(Params p) {
amdhsa.kernels:
  - .agpr_count:     0
    .args:
      - .offset:         0
        .size:           224
        .value_kind:     by_value
      - .offset:         224
        .size:           4
        .value_kind:     hidden_block_count_x
      - .offset:         228
        .size:           4
        .value_kind:     hidden_block_count_y
      - .offset:         232
        .size:           4
        .value_kind:     hidden_block_count_z
      - .offset:         236
        .size:           2
        .value_kind:     hidden_group_size_x
      - .offset:         238
        .size:           2
        .value_kind:     hidden_group_size_y
      - .offset:         240
        .size:           2
        .value_kind:     hidden_group_size_z
      - .offset:         242
        .size:           2
        .value_kind:     hidden_remainder_x
      - .offset:         244
        .size:           2
        .value_kind:     hidden_remainder_y
      - .offset:         246
        .size:           2
        .value_kind:     hidden_remainder_z
      - .offset:         264
        .size:           8
        .value_kind:     hidden_global_offset_x
      - .offset:         272
        .size:           8
        .value_kind:     hidden_global_offset_y
      - .offset:         280
        .size:           8
        .value_kind:     hidden_global_offset_z
      - .offset:         288
        .size:           2
        .value_kind:     hidden_grid_dims
      - .offset:         312
        .size:           8
        .value_kind:     hidden_multigrid_sync_arg
      - .offset:         344
        .size:           4
        .value_kind:     hidden_dynamic_lds_size
    .group_segment_fixed_size: 0
    .kernarg_segment_align: 8
    .kernarg_segment_size: 480
    .language:       OpenCL C
    .language_version:
      - 2
      - 0
    .max_flat_workgroup_size: 512
    .name:           _Z4mega6Params
    .private_segment_fixed_size: 0
    .sgpr_count:     108
    .sgpr_spill_count: 135
    .symbol:         _Z4mega6Params.kd
    .uniform_work_group_size: 1
    .uses_dynamic_stack: false
    .vgpr_count:     256
    .vgpr_spill_count: 0
    .wavefront_size: 64
